# gemm k-loops: back-edge scalar bookkeeping moved into the last MFMA block (one per gap), LDS reads first at the loop head
# baseline (speedup 1.0000x reference)
; #define PG8_STAGE(bufoff, gbase, voff) do { _Pragma("unroll") for (int _i = 0; _i < 2; ++_i) \
;         __builtin_amdgcn_global_load_lds((const unsigned*)((const char*)(gbase) + (voff)[_i]), (PG8_LAS unsigned*)(lds + (bufoff) + ldsw + _i * 8192), 16, 0, 0); } while (0)
; #define PG8_LDA(dst, b, h) do { _Pragma("unroll") for (int m = 0; m < 4; ++m) _Pragma("unroll") for (int k = 0; k < 2; ++k) dst[m][k] = *(const PG8_LAS bf16x8*)(lds + PG8_SA(b, h) + aoff + m * 2048 + k * 1024); } while (0)
; #define PG8_LDB(dst, b, h) do { _Pragma("unroll") for (int n = 0; n < 2; ++n) _Pragma("unroll") for (int k = 0; k < 2; ++k) dst[n][k] = *(const PG8_LAS bf16x8*)(lds + PG8_SB(b, h) + boff + n * 2048 + k * 1024); } while (0)
; #define PG8_MMA(ai, bj, At, Bt) do { __builtin_amdgcn_s_setprio(1); _Pragma("unroll") for (int m = 0; m < 4; ++m) _Pragma("unroll") for (int n = 0; n < 2; ++n) _Pragma("unroll") for (int k = 0; k < 2; ++k) \
;         acc[ai][bj][m][n] = __builtin_amdgcn_mfma_f32_16x16x32_bf16(Bt[n][k], At[m][k], acc[ai][bj][m][n], 0, 0, 0); __builtin_amdgcn_s_setprio(0); } while (0)
; #define PG8_WAIT_V(n) asm volatile("s_waitcnt vmcnt(" #n ")" ::: "memory")
; #define PG8_WAIT_L(n) asm volatile("s_waitcnt lgkmcnt(" #n ")" ::: "memory")
; #define PG8_BAR __builtin_amdgcn_s_barrier()
; template <class Epi, class Sched, bool ALIGN_EPI = false, bool SP2 = false>
; __device__ __forceinline__ void gemm_phase(PG8_LAS unsigned char* lds, const Gemm g, const Sched& S, const Epi& E, const int tid) {
;     ...
;         for (int t = 0; t < nt; t += 2) {
;             const bool last = (t == nt - 2);
;             const char* a1 = cA + (size_t)(t + 1) * kstep;
;             const char* a2 = last ? nA : cA + (size_t)(t + 2) * kstep; const char* b2 = last ? nB : cB + (size_t)(t + 2) * kstep;
;             const char* a3 = a2 + kstep; const char* b3 = b2 + kstep;
;             if (last && has_next) S.a_ready(nxt);
;             if constexpr (SP2) {
;             PG8_LDB(B0, 0, 0); PG8_LDB(B1, 0, 1); PG8_SCHED; PG8_LDA(At, 0, 0); PG8_STAGE(PG8_SA(1, 1), a1 + hstep, voffA);
;             PG8_WAIT_V(8); PG8_WAIT_L(0); PG8_BAR; PG8_MMA(0, 0, At, B0); PG8_MMA(0, 1, At, B1); PG8_BAR; PG8_SCHED;
;             PG8_LDA(At, 0, 1); PG8_STAGE(PG8_SB(0, 0), b2, voffB); PG8_STAGE(PG8_SB(0, 1), b2 + hstep, voffB); PG8_STAGE(PG8_SA(0, 0), a2, voffA);
.LBB0_154:
	s_add_i32 s48, 0, 0x10000
	v_add_u32_e32 v2, s48, v149
	ds_read_b128 v[142:145], v2
	ds_read_b128 v[170:173], v2 offset:1024
	ds_read_b128 v[174:177], v2 offset:2048
	ds_read_b128 v[178:181], v2 offset:3072
	s_add_u32 s12, s36, 0xfffc0080
	s_addc_u32 s14, s37, -1
	s_cmp_eq_u32 s47, 12
	s_cselect_b32 s45, s15, s14
	s_cselect_b32 s44, s22, s12
	s_cselect_b32 s43, s23, s46
	s_cselect_b32 s42, s25, s29
	s_add_i32 s12, 0, 0x14000
	v_add_u32_e32 v2, s12, v149
	ds_read_b128 v[182:185], v2
	ds_read_b128 v[186:189], v2 offset:1024
	ds_read_b128 v[190:193], v2 offset:2048
	ds_read_b128 v[194:197], v2 offset:3072
	v_lshl_add_u64 v[146:147], s[36:37], 0, v[138:139]
	s_add_i32 m0, s7, 0xc000
	ds_read_b128 v[212:215], v151
	ds_read_b128 v[216:219], v151 offset:1024
	ds_read_b128 v[220:223], v151 offset:2048
	ds_read_b128 v[224:227], v151 offset:3072
	ds_read_b128 v[228:231], v151 offset:4096
	ds_read_b128 v[236:239], v151 offset:5120
	ds_read_b128 v[240:243], v151 offset:6144
	ds_read_b128 v[244:247], v151 offset:7168
	global_load_lds_dwordx4 v[146:147], off
	v_lshl_add_u64 v[146:147], s[36:37], 0, v[140:141]
	s_add_i32 m0, s7, 0xe000
	s_nop 0
	global_load_lds_dwordx4 v[146:147], off
	s_waitcnt vmcnt(8)
	s_waitcnt lgkmcnt(0)
	s_barrier
	s_setprio 1
	s_waitcnt lgkmcnt(0)
	v_mfma_f32_16x16x32_bf16 v[128:131], v[142:145], v[212:215], v[128:131]
	v_mfma_f32_16x16x32_bf16 v[124:127], v[174:177], v[212:215], v[124:127]
	v_mfma_f32_16x16x32_bf16 v[112:115], v[142:145], v[220:223], v[112:115]
	v_mfma_f32_16x16x32_bf16 v[108:111], v[174:177], v[220:223], v[108:111]
	v_mfma_f32_16x16x32_bf16 v[96:99], v[142:145], v[228:231], v[96:99]
	v_mfma_f32_16x16x32_bf16 v[92:95], v[174:177], v[228:231], v[92:95]
	v_mfma_f32_16x16x32_bf16 v[80:83], v[142:145], v[240:243], v[80:83]
	v_mfma_f32_16x16x32_bf16 v[76:79], v[174:177], v[240:243], v[76:79]
	v_mfma_f32_16x16x32_bf16 v[128:131], v[170:173], v[216:219], v[128:131]
	v_mfma_f32_16x16x32_bf16 v[124:127], v[178:181], v[216:219], v[124:127]
	v_mfma_f32_16x16x32_bf16 v[112:115], v[170:173], v[224:227], v[112:115]
	v_mfma_f32_16x16x32_bf16 v[108:111], v[178:181], v[224:227], v[108:111]
	v_mfma_f32_16x16x32_bf16 v[96:99], v[170:173], v[236:239], v[96:99]
	v_mfma_f32_16x16x32_bf16 v[92:95], v[178:181], v[236:239], v[92:95]
	v_mfma_f32_16x16x32_bf16 v[80:83], v[170:173], v[244:247], v[80:83]
	v_mfma_f32_16x16x32_bf16 v[76:79], v[178:181], v[244:247], v[76:79]
	s_setprio 0
	s_setprio 1
	v_mfma_f32_16x16x32_bf16 v[120:123], v[182:185], v[212:215], v[120:123]
	v_mfma_f32_16x16x32_bf16 v[116:119], v[190:193], v[212:215], v[116:119]
	v_mfma_f32_16x16x32_bf16 v[104:107], v[182:185], v[220:223], v[104:107]
	v_mfma_f32_16x16x32_bf16 v[100:103], v[190:193], v[220:223], v[100:103]
	v_mfma_f32_16x16x32_bf16 v[88:91], v[182:185], v[228:231], v[88:91]
	v_mfma_f32_16x16x32_bf16 v[84:87], v[190:193], v[228:231], v[84:87]
	v_mfma_f32_16x16x32_bf16 v[72:75], v[182:185], v[240:243], v[72:75]
	v_mfma_f32_16x16x32_bf16 v[68:71], v[190:193], v[240:243], v[68:71]
	v_mfma_f32_16x16x32_bf16 v[120:123], v[186:189], v[216:219], v[120:123]
	v_mfma_f32_16x16x32_bf16 v[116:119], v[194:197], v[216:219], v[116:119]
	v_mfma_f32_16x16x32_bf16 v[104:107], v[186:189], v[224:227], v[104:107]
	v_mfma_f32_16x16x32_bf16 v[100:103], v[194:197], v[224:227], v[100:103]
	v_mfma_f32_16x16x32_bf16 v[88:91], v[186:189], v[236:239], v[88:91]
	v_mfma_f32_16x16x32_bf16 v[84:87], v[194:197], v[236:239], v[84:87]
	v_mfma_f32_16x16x32_bf16 v[72:75], v[186:189], v[244:247], v[72:75]
	v_mfma_f32_16x16x32_bf16 v[68:71], v[194:197], v[244:247], v[68:71]
	s_setprio 0
	s_barrier
	s_add_i32 s14, s48, s6
	v_lshl_add_u64 v[146:147], s[42:43], 0, v[134:135]
	s_mov_b32 m0, s14
	ds_read_b128 v[212:215], v151 offset:16384
	ds_read_b128 v[216:219], v151 offset:17408
	ds_read_b128 v[220:223], v151 offset:18432
	ds_read_b128 v[224:227], v151 offset:19456
	ds_read_b128 v[228:231], v151 offset:20480
	ds_read_b128 v[236:239], v151 offset:21504
	ds_read_b128 v[240:243], v151 offset:22528
	ds_read_b128 v[244:247], v151 offset:23552
	global_load_lds_dwordx4 v[146:147], off
	s_add_i32 m0, s14, 0x2000
	s_add_u32 s48, s42, 0x40000
	v_lshl_add_u64 v[152:153], s[42:43], 0, v[0:1]
	s_addc_u32 s49, s43, 0
	s_add_i32 s12, s12, s6
	global_load_lds_dwordx4 v[152:153], off
	v_lshl_add_u64 v[160:161], s[48:49], 0, v[134:135]
	s_mov_b32 m0, s12
	v_lshl_add_u64 v[198:199], s[44:45], 0, v[132:133]
	global_load_lds_dwordx4 v[160:161], off
	v_lshl_add_u64 v[160:161], s[48:49], 0, v[0:1]
	s_add_i32 m0, s12, 0x2000
	s_nop 0
	global_load_lds_dwordx4 v[160:161], off
	v_lshl_add_u64 v[160:161], s[44:45], 0, v[136:137]
	s_mov_b32 m0, s7
	s_nop 0
	global_load_lds_dwordx4 v[160:161], off
	s_mov_b32 m0, s8
	s_nop 0
	global_load_lds_dwordx4 v[198:199], off
	s_waitcnt vmcnt(8)
	s_waitcnt lgkmcnt(0)
	s_barrier
; #define PG8_STAGE(bufoff, gbase, voff) do { _Pragma("unroll") for (int _i = 0; _i < 2; ++_i) \
;         __builtin_amdgcn_global_load_lds((const unsigned*)((const char*)(gbase) + (voff)[_i]), (PG8_LAS unsigned*)(lds + (bufoff) + ldsw + _i * 8192), 16, 0, 0); } while (0)
; #define PG8_LDA(dst, b, h) do { _Pragma("unroll") for (int m = 0; m < 4; ++m) _Pragma("unroll") for (int k = 0; k < 2; ++k) dst[m][k] = *(const PG8_LAS bf16x8*)(lds + PG8_SA(b, h) + aoff + m * 2048 + k * 1024); } while (0)
; #define PG8_LDB(dst, b, h) do { _Pragma("unroll") for (int n = 0; n < 2; ++n) _Pragma("unroll") for (int k = 0; k < 2; ++k) dst[n][k] = *(const PG8_LAS bf16x8*)(lds + PG8_SB(b, h) + boff + n * 2048 + k * 1024); } while (0)
; #define PG8_MMA(ai, bj, At, Bt) do { __builtin_amdgcn_s_setprio(1); _Pragma("unroll") for (int m = 0; m < 4; ++m) _Pragma("unroll") for (int n = 0; n < 2; ++n) _Pragma("unroll") for (int k = 0; k < 2; ++k) \
;         acc[ai][bj][m][n] = __builtin_amdgcn_mfma_f32_16x16x32_bf16(Bt[n][k], At[m][k], acc[ai][bj][m][n], 0, 0, 0); __builtin_amdgcn_s_setprio(0); } while (0)
; #define PG8_WAIT_V(n) asm volatile("s_waitcnt vmcnt(" #n ")" ::: "memory")
; #define PG8_WAIT_L(n) asm volatile("s_waitcnt lgkmcnt(" #n ")" ::: "memory")
; #define PG8_BAR __builtin_amdgcn_s_barrier()
; #define PG8_SCHED __builtin_amdgcn_sched_barrier(0)
; template <class Epi, class Sched, bool ALIGN_EPI = false, bool SP2 = false>
; __device__ __forceinline__ void gemm_phase(PG8_LAS unsigned char* lds, const Gemm g, const Sched& S, const Epi& E, const int tid) {
;     ...
;             PG8_WAIT_V(8); PG8_WAIT_L(0); PG8_BAR; PG8_MMA(1, 0, At, B0); PG8_MMA(1, 1, At, B1); PG8_BAR; PG8_SCHED;
;             PG8_LDB(B0, 1, 0); PG8_LDB(B1, 1, 1); PG8_SCHED; PG8_LDA(At, 1, 0); PG8_STAGE(PG8_SA(0, 1), a2 + hstep, voffA);
;             PG8_WAIT_V(8); PG8_WAIT_L(0); PG8_BAR; PG8_MMA(0, 0, At, B0); PG8_MMA(0, 1, At, B1); PG8_BAR; PG8_SCHED;
	s_setprio 1
	s_waitcnt lgkmcnt(0)
	v_mfma_f32_16x16x32_bf16 v[64:67], v[142:145], v[212:215], v[64:67]
	v_mfma_f32_16x16x32_bf16 v[60:63], v[174:177], v[212:215], v[60:63]
	v_mfma_f32_16x16x32_bf16 v[48:51], v[142:145], v[220:223], v[48:51]
	v_mfma_f32_16x16x32_bf16 v[44:47], v[174:177], v[220:223], v[44:47]
	v_mfma_f32_16x16x32_bf16 v[32:35], v[142:145], v[228:231], v[32:35]
	v_mfma_f32_16x16x32_bf16 v[28:31], v[174:177], v[228:231], v[28:31]
	v_mfma_f32_16x16x32_bf16 v[16:19], v[142:145], v[240:243], v[16:19]
	v_mfma_f32_16x16x32_bf16 v[12:15], v[174:177], v[240:243], v[12:15]
	v_mfma_f32_16x16x32_bf16 v[64:67], v[170:173], v[216:219], v[64:67]
	v_mfma_f32_16x16x32_bf16 v[60:63], v[178:181], v[216:219], v[60:63]
	v_mfma_f32_16x16x32_bf16 v[48:51], v[170:173], v[224:227], v[48:51]
	v_mfma_f32_16x16x32_bf16 v[44:47], v[178:181], v[224:227], v[44:47]
	v_mfma_f32_16x16x32_bf16 v[32:35], v[170:173], v[236:239], v[32:35]
	v_mfma_f32_16x16x32_bf16 v[28:31], v[178:181], v[236:239], v[28:31]
	v_mfma_f32_16x16x32_bf16 v[16:19], v[170:173], v[244:247], v[16:19]
	v_mfma_f32_16x16x32_bf16 v[12:15], v[178:181], v[244:247], v[12:15]
	s_setprio 0
	s_setprio 1
	v_mfma_f32_16x16x32_bf16 v[56:59], v[182:185], v[212:215], v[56:59]
	v_mfma_f32_16x16x32_bf16 v[52:55], v[190:193], v[212:215], v[52:55]
	v_mfma_f32_16x16x32_bf16 v[40:43], v[182:185], v[220:223], v[40:43]
	v_mfma_f32_16x16x32_bf16 v[36:39], v[190:193], v[220:223], v[36:39]
	v_mfma_f32_16x16x32_bf16 v[24:27], v[182:185], v[228:231], v[24:27]
	v_mfma_f32_16x16x32_bf16 v[20:23], v[190:193], v[228:231], v[20:23]
	v_mfma_f32_16x16x32_bf16 v[8:11], v[182:185], v[240:243], v[8:11]
	v_mfma_f32_16x16x32_bf16 v[4:7], v[190:193], v[240:243], v[4:7]
	v_mfma_f32_16x16x32_bf16 v[56:59], v[186:189], v[216:219], v[56:59]
	v_mfma_f32_16x16x32_bf16 v[52:55], v[194:197], v[216:219], v[52:55]
	v_mfma_f32_16x16x32_bf16 v[40:43], v[186:189], v[224:227], v[40:43]
	v_mfma_f32_16x16x32_bf16 v[36:39], v[194:197], v[224:227], v[36:39]
	v_mfma_f32_16x16x32_bf16 v[24:27], v[186:189], v[236:239], v[24:27]
	v_mfma_f32_16x16x32_bf16 v[20:23], v[194:197], v[236:239], v[20:23]
	v_mfma_f32_16x16x32_bf16 v[8:11], v[186:189], v[244:247], v[8:11]
	v_mfma_f32_16x16x32_bf16 v[4:7], v[194:197], v[244:247], v[4:7]
	s_setprio 0
	s_barrier
	s_add_i32 s12, 0, 0x18000
	v_add_u32_e32 v2, s12, v149
	s_add_i32 s14, 0, 0x1c000
	ds_read_b128 v[142:145], v2
	ds_read_b128 v[170:173], v2 offset:1024
	ds_read_b128 v[174:177], v2 offset:2048
	ds_read_b128 v[178:181], v2 offset:3072
	v_add_u32_e32 v2, s14, v149
	ds_read_b128 v[182:185], v2
	ds_read_b128 v[186:189], v2 offset:1024
	ds_read_b128 v[190:193], v2 offset:2048
	ds_read_b128 v[194:197], v2 offset:3072
	s_add_u32 s44, s44, 0x40000
	s_addc_u32 s45, s45, 0
	s_mov_b32 m0, s9
	v_lshl_add_u64 v[248:249], s[44:45], 0, v[136:137]
	ds_read_b128 v[212:215], v151 offset:32768
	ds_read_b128 v[216:219], v151 offset:33792
	ds_read_b128 v[220:223], v151 offset:34816
	ds_read_b128 v[224:227], v151 offset:35840
	ds_read_b128 v[228:231], v151 offset:36864
	ds_read_b128 v[236:239], v151 offset:37888
	ds_read_b128 v[240:243], v151 offset:38912
	ds_read_b128 v[244:247], v151 offset:39936
	global_load_lds_dwordx4 v[248:249], off
	v_lshl_add_u64 v[248:249], s[44:45], 0, v[132:133]
	s_mov_b32 m0, s30
	s_nop 0
	global_load_lds_dwordx4 v[248:249], off
	s_waitcnt vmcnt(8)
	s_waitcnt lgkmcnt(0)
	s_barrier
	s_setprio 1
	s_waitcnt lgkmcnt(0)
	v_mfma_f32_16x16x32_bf16 v[128:131], v[142:145], v[212:215], v[128:131]
	v_mfma_f32_16x16x32_bf16 v[124:127], v[174:177], v[212:215], v[124:127]
	v_mfma_f32_16x16x32_bf16 v[112:115], v[142:145], v[220:223], v[112:115]
	v_mfma_f32_16x16x32_bf16 v[108:111], v[174:177], v[220:223], v[108:111]
	v_mfma_f32_16x16x32_bf16 v[96:99], v[142:145], v[228:231], v[96:99]
	v_mfma_f32_16x16x32_bf16 v[92:95], v[174:177], v[228:231], v[92:95]
	v_mfma_f32_16x16x32_bf16 v[80:83], v[142:145], v[240:243], v[80:83]
	v_mfma_f32_16x16x32_bf16 v[76:79], v[174:177], v[240:243], v[76:79]
	v_mfma_f32_16x16x32_bf16 v[128:131], v[170:173], v[216:219], v[128:131]
	v_mfma_f32_16x16x32_bf16 v[124:127], v[178:181], v[216:219], v[124:127]
	v_mfma_f32_16x16x32_bf16 v[112:115], v[170:173], v[224:227], v[112:115]
	v_mfma_f32_16x16x32_bf16 v[108:111], v[178:181], v[224:227], v[108:111]
	v_mfma_f32_16x16x32_bf16 v[96:99], v[170:173], v[236:239], v[96:99]
	v_mfma_f32_16x16x32_bf16 v[92:95], v[178:181], v[236:239], v[92:95]
	v_mfma_f32_16x16x32_bf16 v[80:83], v[170:173], v[244:247], v[80:83]
	v_mfma_f32_16x16x32_bf16 v[76:79], v[178:181], v[244:247], v[76:79]
	s_setprio 0
	s_setprio 1
	v_mfma_f32_16x16x32_bf16 v[120:123], v[182:185], v[212:215], v[120:123]
	v_mfma_f32_16x16x32_bf16 v[116:119], v[190:193], v[212:215], v[116:119]
	v_mfma_f32_16x16x32_bf16 v[104:107], v[182:185], v[220:223], v[104:107]
	v_mfma_f32_16x16x32_bf16 v[100:103], v[190:193], v[220:223], v[100:103]
	v_mfma_f32_16x16x32_bf16 v[88:91], v[182:185], v[228:231], v[88:91]
	v_mfma_f32_16x16x32_bf16 v[84:87], v[190:193], v[228:231], v[84:87]
	v_mfma_f32_16x16x32_bf16 v[72:75], v[182:185], v[240:243], v[72:75]
	v_mfma_f32_16x16x32_bf16 v[68:71], v[190:193], v[240:243], v[68:71]
	v_mfma_f32_16x16x32_bf16 v[120:123], v[186:189], v[216:219], v[120:123]
	v_mfma_f32_16x16x32_bf16 v[116:119], v[194:197], v[216:219], v[116:119]
	v_mfma_f32_16x16x32_bf16 v[104:107], v[186:189], v[224:227], v[104:107]
	v_mfma_f32_16x16x32_bf16 v[100:103], v[194:197], v[224:227], v[100:103]
	v_mfma_f32_16x16x32_bf16 v[88:91], v[186:189], v[236:239], v[88:91]
	v_mfma_f32_16x16x32_bf16 v[84:87], v[194:197], v[236:239], v[84:87]
	v_mfma_f32_16x16x32_bf16 v[72:75], v[186:189], v[244:247], v[72:75]
	v_mfma_f32_16x16x32_bf16 v[68:71], v[194:197], v[244:247], v[68:71]
	s_setprio 0
	s_barrier
; #define PG8_STAGE(bufoff, gbase, voff) do { _Pragma("unroll") for (int _i = 0; _i < 2; ++_i) \
;         __builtin_amdgcn_global_load_lds((const unsigned*)((const char*)(gbase) + (voff)[_i]), (PG8_LAS unsigned*)(lds + (bufoff) + ldsw + _i * 8192), 16, 0, 0); } while (0)
; #define PG8_LDA(dst, b, h) do { _Pragma("unroll") for (int m = 0; m < 4; ++m) _Pragma("unroll") for (int k = 0; k < 2; ++k) dst[m][k] = *(const PG8_LAS bf16x8*)(lds + PG8_SA(b, h) + aoff + m * 2048 + k * 1024); } while (0)
; #define PG8_MMA(ai, bj, At, Bt) do { __builtin_amdgcn_s_setprio(1); _Pragma("unroll") for (int m = 0; m < 4; ++m) _Pragma("unroll") for (int n = 0; n < 2; ++n) _Pragma("unroll") for (int k = 0; k < 2; ++k) \
;         acc[ai][bj][m][n] = __builtin_amdgcn_mfma_f32_16x16x32_bf16(Bt[n][k], At[m][k], acc[ai][bj][m][n], 0, 0, 0); __builtin_amdgcn_s_setprio(0); } while (0)
; #define PG8_WAIT_V(n) asm volatile("s_waitcnt vmcnt(" #n ")" ::: "memory")
; #define PG8_WAIT_L(n) asm volatile("s_waitcnt lgkmcnt(" #n ")" ::: "memory")
; #define PG8_BAR __builtin_amdgcn_s_barrier()
; #define PG8_SCHED __builtin_amdgcn_sched_barrier(0)
; template <class Epi, class Sched, bool ALIGN_EPI = false, bool SP2 = false>
; __device__ __forceinline__ void gemm_phase(PG8_LAS unsigned char* lds, const Gemm g, const Sched& S, const Epi& E, const int tid) {
;     ...
;         for (int t = 0; t < nt; t += 2) {
;             const bool last = (t == nt - 2);
;     ...
;             PG8_LDA(At, 1, 1); PG8_STAGE(PG8_SB(1, 0), b3, voffB); PG8_STAGE(PG8_SB(1, 1), b3 + hstep, voffB); PG8_STAGE(PG8_SA(1, 0), a3, voffA);
;             PG8_WAIT_V(8); PG8_WAIT_L(0); PG8_BAR; PG8_MMA(1, 0, At, B0); PG8_MMA(1, 1, At, B1); PG8_BAR; PG8_SCHED;
	s_add_i32 s12, s12, s6
	v_lshl_add_u64 v[146:147], v[146:147], 0, s[18:19]
	s_mov_b32 m0, s12
	ds_read_b128 v[212:215], v151 offset:49152
	ds_read_b128 v[216:219], v151 offset:50176
	ds_read_b128 v[220:223], v151 offset:51200
	ds_read_b128 v[224:227], v151 offset:52224
	ds_read_b128 v[228:231], v151 offset:53248
	ds_read_b128 v[236:239], v151 offset:54272
	ds_read_b128 v[240:243], v151 offset:55296
	ds_read_b128 v[244:247], v151 offset:56320
	global_load_lds_dwordx4 v[146:147], off
	s_add_i32 m0, s12, 0x2000
	s_add_u32 s42, s42, 0x40080
	v_lshl_add_u64 v[146:147], v[152:153], 0, s[18:19]
	s_addc_u32 s43, s43, 0
	s_add_i32 s12, s14, s6
	global_load_lds_dwordx4 v[146:147], off
	v_lshl_add_u64 v[146:147], s[42:43], 0, v[134:135]
	s_mov_b32 m0, s12
	s_nop 0
	global_load_lds_dwordx4 v[146:147], off
	v_lshl_add_u64 v[146:147], s[42:43], 0, v[0:1]
	s_add_i32 m0, s12, 0x2000
	s_nop 0
	global_load_lds_dwordx4 v[146:147], off
	v_lshl_add_u64 v[146:147], v[160:161], 0, s[18:19]
	s_mov_b32 m0, s54
	s_nop 0
	global_load_lds_dwordx4 v[146:147], off
	v_lshl_add_u64 v[146:147], v[198:199], 0, s[18:19]
	s_mov_b32 m0, s55
	s_nop 0
	global_load_lds_dwordx4 v[146:147], off
	s_waitcnt vmcnt(8)
	s_waitcnt lgkmcnt(0)
	s_barrier
	s_setprio 1
	s_waitcnt lgkmcnt(0)
	v_mfma_f32_16x16x32_bf16 v[64:67], v[142:145], v[212:215], v[64:67]
	v_mfma_f32_16x16x32_bf16 v[60:63], v[174:177], v[212:215], v[60:63]
	v_mfma_f32_16x16x32_bf16 v[48:51], v[142:145], v[220:223], v[48:51]
	v_mfma_f32_16x16x32_bf16 v[44:47], v[174:177], v[220:223], v[44:47]
	v_mfma_f32_16x16x32_bf16 v[32:35], v[142:145], v[228:231], v[32:35]
	v_mfma_f32_16x16x32_bf16 v[28:31], v[174:177], v[228:231], v[28:31]
	v_mfma_f32_16x16x32_bf16 v[16:19], v[142:145], v[240:243], v[16:19]
	v_mfma_f32_16x16x32_bf16 v[12:15], v[174:177], v[240:243], v[12:15]
	v_mfma_f32_16x16x32_bf16 v[64:67], v[170:173], v[216:219], v[64:67]
	v_mfma_f32_16x16x32_bf16 v[60:63], v[178:181], v[216:219], v[60:63]
	v_mfma_f32_16x16x32_bf16 v[48:51], v[170:173], v[224:227], v[48:51]
	v_mfma_f32_16x16x32_bf16 v[44:47], v[178:181], v[224:227], v[44:47]
	v_mfma_f32_16x16x32_bf16 v[32:35], v[170:173], v[236:239], v[32:35]
	v_mfma_f32_16x16x32_bf16 v[28:31], v[178:181], v[236:239], v[28:31]
	v_mfma_f32_16x16x32_bf16 v[16:19], v[170:173], v[244:247], v[16:19]
	v_mfma_f32_16x16x32_bf16 v[12:15], v[178:181], v[244:247], v[12:15]
	s_setprio 0
	s_setprio 1
	v_mfma_f32_16x16x32_bf16 v[56:59], v[182:185], v[212:215], v[56:59]
	v_mfma_f32_16x16x32_bf16 v[52:55], v[190:193], v[212:215], v[52:55]
	s_add_i32 s47, s47, 2
	v_mfma_f32_16x16x32_bf16 v[40:43], v[182:185], v[220:223], v[40:43]
	s_add_u32 s36, s36, 0x100
	v_mfma_f32_16x16x32_bf16 v[36:39], v[190:193], v[220:223], v[36:39]
	s_addc_u32 s37, s37, 0
	v_mfma_f32_16x16x32_bf16 v[24:27], v[182:185], v[228:231], v[24:27]
	s_add_u32 s29, s29, 0x100
	v_mfma_f32_16x16x32_bf16 v[20:23], v[190:193], v[228:231], v[20:23]
	s_addc_u32 s46, s46, 0
	v_mfma_f32_16x16x32_bf16 v[8:11], v[182:185], v[240:243], v[8:11]
	s_cmp_gt_u32 s47, 13
	v_mfma_f32_16x16x32_bf16 v[4:7], v[190:193], v[240:243], v[4:7]
	v_mfma_f32_16x16x32_bf16 v[56:59], v[186:189], v[216:219], v[56:59]
	v_mfma_f32_16x16x32_bf16 v[52:55], v[194:197], v[216:219], v[52:55]
	v_mfma_f32_16x16x32_bf16 v[40:43], v[186:189], v[224:227], v[40:43]
	v_mfma_f32_16x16x32_bf16 v[36:39], v[194:197], v[224:227], v[36:39]
	v_mfma_f32_16x16x32_bf16 v[24:27], v[186:189], v[236:239], v[24:27]
	v_mfma_f32_16x16x32_bf16 v[20:23], v[194:197], v[236:239], v[20:23]
	v_mfma_f32_16x16x32_bf16 v[8:11], v[186:189], v[244:247], v[8:11]
	v_mfma_f32_16x16x32_bf16 v[4:7], v[194:197], v[244:247], v[4:7]
	s_setprio 0
	s_barrier
	s_cbranch_scc0 .LBB0_154
	s_and_b64 vcc, exec, s[20:21]
	s_cbranch_vccz .LBB0_157
	s_barrier

; #define PG8_STAGE(bufoff, gbase, voff) do { _Pragma("unroll") for (int _i = 0; _i < 2; ++_i) \
;         __builtin_amdgcn_global_load_lds((const unsigned*)((const char*)(gbase) + (voff)[_i]), (PG8_LAS unsigned*)(lds + (bufoff) + ldsw + _i * 8192), 16, 0, 0); } while (0)
; #define PG8_LDA(dst, b, h) do { _Pragma("unroll") for (int m = 0; m < 4; ++m) _Pragma("unroll") for (int k = 0; k < 2; ++k) dst[m][k] = *(const PG8_LAS bf16x8*)(lds + PG8_SA(b, h) + aoff + m * 2048 + k * 1024); } while (0)
; #define PG8_LDB(dst, b, h) do { _Pragma("unroll") for (int n = 0; n < 2; ++n) _Pragma("unroll") for (int k = 0; k < 2; ++k) dst[n][k] = *(const PG8_LAS bf16x8*)(lds + PG8_SB(b, h) + boff + n * 2048 + k * 1024); } while (0)
; #define PG8_MMA(ai, bj, At, Bt) do { __builtin_amdgcn_s_setprio(1); _Pragma("unroll") for (int m = 0; m < 4; ++m) _Pragma("unroll") for (int n = 0; n < 2; ++n) _Pragma("unroll") for (int k = 0; k < 2; ++k) \
;         acc[ai][bj][m][n] = __builtin_amdgcn_mfma_f32_16x16x32_bf16(Bt[n][k], At[m][k], acc[ai][bj][m][n], 0, 0, 0); __builtin_amdgcn_s_setprio(0); } while (0)
; #define PG8_WAIT_V(n) asm volatile("s_waitcnt vmcnt(" #n ")" ::: "memory")
; #define PG8_WAIT_L(n) asm volatile("s_waitcnt lgkmcnt(" #n ")" ::: "memory")
; #define PG8_BAR __builtin_amdgcn_s_barrier()
; template <class Epi, class Sched, bool ALIGN_EPI = false, bool SP2 = false>
; __device__ __forceinline__ void gemm_phase(PG8_LAS unsigned char* lds, const Gemm g, const Sched& S, const Epi& E, const int tid) {
;     ...
;         for (int t = 0; t < nt; t += 2) {
;             const bool last = (t == nt - 2);
;             const char* a1 = cA + (size_t)(t + 1) * kstep;
;             const char* a2 = last ? nA : cA + (size_t)(t + 2) * kstep; const char* b2 = last ? nB : cB + (size_t)(t + 2) * kstep;
;             const char* a3 = a2 + kstep; const char* b3 = b2 + kstep;
;             if (last && has_next) S.a_ready(nxt);
;             if constexpr (SP2) {
;             PG8_LDB(B0, 0, 0); PG8_LDB(B1, 0, 1); PG8_SCHED; PG8_LDA(At, 0, 0); PG8_STAGE(PG8_SA(1, 1), a1 + hstep, voffA);
;             PG8_WAIT_V(8); PG8_WAIT_L(0); PG8_BAR; PG8_MMA(0, 0, At, B0); PG8_MMA(0, 1, At, B1); PG8_BAR; PG8_SCHED;
;             PG8_LDA(At, 0, 1); PG8_STAGE(PG8_SB(0, 0), b2, voffB); PG8_STAGE(PG8_SB(0, 1), b2 + hstep, voffB); PG8_STAGE(PG8_SA(0, 0), a2, voffA);
.LBB0_269:
	s_add_i32 s42, 0, 0x10000
	v_add_u32_e32 v2, s42, v170
	ds_read_b128 v[132:135], v2
	ds_read_b128 v[136:139], v2 offset:1024
	ds_read_b128 v[150:153], v2 offset:2048
	ds_read_b128 v[174:177], v2 offset:3072
	s_add_u32 s12, s24, 0xfff80080
	s_addc_u32 s14, s25, -1
	s_cmp_eq_u32 s23, 28
	s_cselect_b32 s37, s8, s14
	s_cselect_b32 s36, s9, s12
	s_cselect_b32 s29, s13, s22
	s_cselect_b32 s28, s15, s21
	s_add_i32 s12, 0, 0x14000
	v_add_u32_e32 v2, s12, v170
	ds_read_b128 v[178:181], v2
	ds_read_b128 v[182:185], v2 offset:1024
	ds_read_b128 v[186:189], v2 offset:2048
	ds_read_b128 v[190:193], v2 offset:3072
	v_lshl_add_u64 v[160:161], s[24:25], 0, v[146:147]
	s_add_i32 m0, s54, 0xc000
	ds_read_b128 v[194:197], v172
	ds_read_b128 v[212:215], v172 offset:1024
	ds_read_b128 v[216:219], v172 offset:2048
	ds_read_b128 v[220:223], v172 offset:3072
	ds_read_b128 v[224:227], v172 offset:4096
	ds_read_b128 v[228:231], v172 offset:5120
	ds_read_b128 v[236:239], v172 offset:6144
	ds_read_b128 v[240:243], v172 offset:7168
	global_load_lds_dwordx4 v[160:161], off
	v_lshl_add_u64 v[160:161], s[24:25], 0, v[148:149]
	s_add_i32 m0, s54, 0xe000
	s_nop 0
	global_load_lds_dwordx4 v[160:161], off
	s_waitcnt vmcnt(8)
	s_waitcnt lgkmcnt(0)
	s_barrier
	s_setprio 1
	s_waitcnt lgkmcnt(0)
	v_mfma_f32_16x16x32_bf16 v[128:131], v[132:135], v[194:197], v[128:131]
	v_mfma_f32_16x16x32_bf16 v[124:127], v[150:153], v[194:197], v[124:127]
	v_mfma_f32_16x16x32_bf16 v[112:115], v[132:135], v[216:219], v[112:115]
	v_mfma_f32_16x16x32_bf16 v[108:111], v[150:153], v[216:219], v[108:111]
	v_mfma_f32_16x16x32_bf16 v[96:99], v[132:135], v[224:227], v[96:99]
	v_mfma_f32_16x16x32_bf16 v[92:95], v[150:153], v[224:227], v[92:95]
	v_mfma_f32_16x16x32_bf16 v[80:83], v[132:135], v[236:239], v[80:83]
	v_mfma_f32_16x16x32_bf16 v[76:79], v[150:153], v[236:239], v[76:79]
	v_mfma_f32_16x16x32_bf16 v[128:131], v[136:139], v[212:215], v[128:131]
	v_mfma_f32_16x16x32_bf16 v[124:127], v[174:177], v[212:215], v[124:127]
	v_mfma_f32_16x16x32_bf16 v[112:115], v[136:139], v[220:223], v[112:115]
	v_mfma_f32_16x16x32_bf16 v[108:111], v[174:177], v[220:223], v[108:111]
	v_mfma_f32_16x16x32_bf16 v[96:99], v[136:139], v[228:231], v[96:99]
	v_mfma_f32_16x16x32_bf16 v[92:95], v[174:177], v[228:231], v[92:95]
	v_mfma_f32_16x16x32_bf16 v[80:83], v[136:139], v[240:243], v[80:83]
	v_mfma_f32_16x16x32_bf16 v[76:79], v[174:177], v[240:243], v[76:79]
	s_setprio 0
	s_setprio 1
	v_mfma_f32_16x16x32_bf16 v[120:123], v[178:181], v[194:197], v[120:123]
	v_mfma_f32_16x16x32_bf16 v[116:119], v[186:189], v[194:197], v[116:119]
	v_mfma_f32_16x16x32_bf16 v[104:107], v[178:181], v[216:219], v[104:107]
	v_mfma_f32_16x16x32_bf16 v[100:103], v[186:189], v[216:219], v[100:103]
	v_mfma_f32_16x16x32_bf16 v[88:91], v[178:181], v[224:227], v[88:91]
	v_mfma_f32_16x16x32_bf16 v[84:87], v[186:189], v[224:227], v[84:87]
	v_mfma_f32_16x16x32_bf16 v[72:75], v[178:181], v[236:239], v[72:75]
	v_mfma_f32_16x16x32_bf16 v[68:71], v[186:189], v[236:239], v[68:71]
	v_mfma_f32_16x16x32_bf16 v[120:123], v[182:185], v[212:215], v[120:123]
	v_mfma_f32_16x16x32_bf16 v[116:119], v[190:193], v[212:215], v[116:119]
	v_mfma_f32_16x16x32_bf16 v[104:107], v[182:185], v[220:223], v[104:107]
	v_mfma_f32_16x16x32_bf16 v[100:103], v[190:193], v[220:223], v[100:103]
	v_mfma_f32_16x16x32_bf16 v[88:91], v[182:185], v[228:231], v[88:91]
	v_mfma_f32_16x16x32_bf16 v[84:87], v[190:193], v[228:231], v[84:87]
	v_mfma_f32_16x16x32_bf16 v[72:75], v[182:185], v[240:243], v[72:75]
	v_mfma_f32_16x16x32_bf16 v[68:71], v[190:193], v[240:243], v[68:71]
	s_setprio 0
	s_barrier
	s_add_i32 s14, s42, s53
	v_lshl_add_u64 v[160:161], s[28:29], 0, v[142:143]
	s_mov_b32 m0, s14
	ds_read_b128 v[194:197], v172 offset:16384
	ds_read_b128 v[212:215], v172 offset:17408
	ds_read_b128 v[216:219], v172 offset:18432
	ds_read_b128 v[220:223], v172 offset:19456
	ds_read_b128 v[224:227], v172 offset:20480
	ds_read_b128 v[228:231], v172 offset:21504
	ds_read_b128 v[236:239], v172 offset:22528
	ds_read_b128 v[240:243], v172 offset:23552
	global_load_lds_dwordx4 v[160:161], off
	s_add_i32 m0, s14, 0x2000
	s_add_u32 s42, s28, 0x80000
	v_lshl_add_u64 v[198:199], s[28:29], 0, v[0:1]
	s_addc_u32 s43, s29, 0
	s_add_i32 s12, s12, s53
	global_load_lds_dwordx4 v[198:199], off
	v_lshl_add_u64 v[244:245], s[42:43], 0, v[142:143]
	s_mov_b32 m0, s12
	v_lshl_add_u64 v[246:247], s[36:37], 0, v[140:141]
	global_load_lds_dwordx4 v[244:245], off
	v_lshl_add_u64 v[244:245], s[42:43], 0, v[0:1]
	s_add_i32 m0, s12, 0x2000
	s_nop 0
	global_load_lds_dwordx4 v[244:245], off
	v_lshl_add_u64 v[244:245], s[36:37], 0, v[144:145]
	s_mov_b32 m0, s54
	s_nop 0
	global_load_lds_dwordx4 v[244:245], off
	s_mov_b32 m0, s55
	s_nop 0
	global_load_lds_dwordx4 v[246:247], off
	s_waitcnt vmcnt(8)
	s_waitcnt lgkmcnt(0)
	s_barrier
; #define PG8_STAGE(bufoff, gbase, voff) do { _Pragma("unroll") for (int _i = 0; _i < 2; ++_i) \
;         __builtin_amdgcn_global_load_lds((const unsigned*)((const char*)(gbase) + (voff)[_i]), (PG8_LAS unsigned*)(lds + (bufoff) + ldsw + _i * 8192), 16, 0, 0); } while (0)
; #define PG8_LDA(dst, b, h) do { _Pragma("unroll") for (int m = 0; m < 4; ++m) _Pragma("unroll") for (int k = 0; k < 2; ++k) dst[m][k] = *(const PG8_LAS bf16x8*)(lds + PG8_SA(b, h) + aoff + m * 2048 + k * 1024); } while (0)
; #define PG8_LDB(dst, b, h) do { _Pragma("unroll") for (int n = 0; n < 2; ++n) _Pragma("unroll") for (int k = 0; k < 2; ++k) dst[n][k] = *(const PG8_LAS bf16x8*)(lds + PG8_SB(b, h) + boff + n * 2048 + k * 1024); } while (0)
; #define PG8_MMA(ai, bj, At, Bt) do { __builtin_amdgcn_s_setprio(1); _Pragma("unroll") for (int m = 0; m < 4; ++m) _Pragma("unroll") for (int n = 0; n < 2; ++n) _Pragma("unroll") for (int k = 0; k < 2; ++k) \
;         acc[ai][bj][m][n] = __builtin_amdgcn_mfma_f32_16x16x32_bf16(Bt[n][k], At[m][k], acc[ai][bj][m][n], 0, 0, 0); __builtin_amdgcn_s_setprio(0); } while (0)
; #define PG8_WAIT_V(n) asm volatile("s_waitcnt vmcnt(" #n ")" ::: "memory")
; #define PG8_WAIT_L(n) asm volatile("s_waitcnt lgkmcnt(" #n ")" ::: "memory")
; #define PG8_BAR __builtin_amdgcn_s_barrier()
; #define PG8_SCHED __builtin_amdgcn_sched_barrier(0)
; template <class Epi, class Sched, bool ALIGN_EPI = false, bool SP2 = false>
; __device__ __forceinline__ void gemm_phase(PG8_LAS unsigned char* lds, const Gemm g, const Sched& S, const Epi& E, const int tid) {
;     ...
;             PG8_WAIT_V(8); PG8_WAIT_L(0); PG8_BAR; PG8_MMA(1, 0, At, B0); PG8_MMA(1, 1, At, B1); PG8_BAR; PG8_SCHED;
;             PG8_LDB(B0, 1, 0); PG8_LDB(B1, 1, 1); PG8_SCHED; PG8_LDA(At, 1, 0); PG8_STAGE(PG8_SA(0, 1), a2 + hstep, voffA);
;             PG8_WAIT_V(8); PG8_WAIT_L(0); PG8_BAR; PG8_MMA(0, 0, At, B0); PG8_MMA(0, 1, At, B1); PG8_BAR; PG8_SCHED;
	s_setprio 1
	s_waitcnt lgkmcnt(0)
	v_mfma_f32_16x16x32_bf16 v[64:67], v[132:135], v[194:197], v[64:67]
	v_mfma_f32_16x16x32_bf16 v[60:63], v[150:153], v[194:197], v[60:63]
	v_mfma_f32_16x16x32_bf16 v[48:51], v[132:135], v[216:219], v[48:51]
	v_mfma_f32_16x16x32_bf16 v[44:47], v[150:153], v[216:219], v[44:47]
	v_mfma_f32_16x16x32_bf16 v[32:35], v[132:135], v[224:227], v[32:35]
	v_mfma_f32_16x16x32_bf16 v[28:31], v[150:153], v[224:227], v[28:31]
	v_mfma_f32_16x16x32_bf16 v[16:19], v[132:135], v[236:239], v[16:19]
	v_mfma_f32_16x16x32_bf16 v[12:15], v[150:153], v[236:239], v[12:15]
	v_mfma_f32_16x16x32_bf16 v[64:67], v[136:139], v[212:215], v[64:67]
	v_mfma_f32_16x16x32_bf16 v[60:63], v[174:177], v[212:215], v[60:63]
	v_mfma_f32_16x16x32_bf16 v[48:51], v[136:139], v[220:223], v[48:51]
	v_mfma_f32_16x16x32_bf16 v[44:47], v[174:177], v[220:223], v[44:47]
	v_mfma_f32_16x16x32_bf16 v[32:35], v[136:139], v[228:231], v[32:35]
	v_mfma_f32_16x16x32_bf16 v[28:31], v[174:177], v[228:231], v[28:31]
	v_mfma_f32_16x16x32_bf16 v[16:19], v[136:139], v[240:243], v[16:19]
	v_mfma_f32_16x16x32_bf16 v[12:15], v[174:177], v[240:243], v[12:15]
	s_setprio 0
	s_setprio 1
	v_mfma_f32_16x16x32_bf16 v[56:59], v[178:181], v[194:197], v[56:59]
	v_mfma_f32_16x16x32_bf16 v[52:55], v[186:189], v[194:197], v[52:55]
	v_mfma_f32_16x16x32_bf16 v[40:43], v[178:181], v[216:219], v[40:43]
	v_mfma_f32_16x16x32_bf16 v[36:39], v[186:189], v[216:219], v[36:39]
	v_mfma_f32_16x16x32_bf16 v[24:27], v[178:181], v[224:227], v[24:27]
	v_mfma_f32_16x16x32_bf16 v[20:23], v[186:189], v[224:227], v[20:23]
	v_mfma_f32_16x16x32_bf16 v[8:11], v[178:181], v[236:239], v[8:11]
	v_mfma_f32_16x16x32_bf16 v[4:7], v[186:189], v[236:239], v[4:7]
	v_mfma_f32_16x16x32_bf16 v[56:59], v[182:185], v[212:215], v[56:59]
	v_mfma_f32_16x16x32_bf16 v[52:55], v[190:193], v[212:215], v[52:55]
	v_mfma_f32_16x16x32_bf16 v[40:43], v[182:185], v[220:223], v[40:43]
	v_mfma_f32_16x16x32_bf16 v[36:39], v[190:193], v[220:223], v[36:39]
	v_mfma_f32_16x16x32_bf16 v[24:27], v[182:185], v[228:231], v[24:27]
	v_mfma_f32_16x16x32_bf16 v[20:23], v[190:193], v[228:231], v[20:23]
	v_mfma_f32_16x16x32_bf16 v[8:11], v[182:185], v[240:243], v[8:11]
	v_mfma_f32_16x16x32_bf16 v[4:7], v[190:193], v[240:243], v[4:7]
	s_setprio 0
	s_barrier
	s_add_i32 s12, 0, 0x18000
	v_add_u32_e32 v2, s12, v170
	s_add_i32 s14, 0, 0x1c000
	ds_read_b128 v[132:135], v2
	ds_read_b128 v[136:139], v2 offset:1024
	ds_read_b128 v[150:153], v2 offset:2048
	ds_read_b128 v[174:177], v2 offset:3072
	v_add_u32_e32 v2, s14, v170
	ds_read_b128 v[178:181], v2
	ds_read_b128 v[182:185], v2 offset:1024
	ds_read_b128 v[186:189], v2 offset:2048
	ds_read_b128 v[190:193], v2 offset:3072
	s_add_u32 s36, s36, 0x80000
	s_addc_u32 s37, s37, 0
	s_mov_b32 m0, s93
	v_lshl_add_u64 v[248:249], s[36:37], 0, v[144:145]
	ds_read_b128 v[194:197], v172 offset:32768
	ds_read_b128 v[212:215], v172 offset:33792
	ds_read_b128 v[216:219], v172 offset:34816
	ds_read_b128 v[220:223], v172 offset:35840
	ds_read_b128 v[224:227], v172 offset:36864
	ds_read_b128 v[228:231], v172 offset:37888
	ds_read_b128 v[236:239], v172 offset:38912
	ds_read_b128 v[240:243], v172 offset:39936
	global_load_lds_dwordx4 v[248:249], off
	v_lshl_add_u64 v[248:249], s[36:37], 0, v[140:141]
	s_mov_b32 m0, s4
	s_nop 0
	global_load_lds_dwordx4 v[248:249], off
	s_waitcnt vmcnt(8)
	s_waitcnt lgkmcnt(0)
	s_barrier
	s_setprio 1
	s_waitcnt lgkmcnt(0)
	v_mfma_f32_16x16x32_bf16 v[128:131], v[132:135], v[194:197], v[128:131]
	v_mfma_f32_16x16x32_bf16 v[124:127], v[150:153], v[194:197], v[124:127]
	v_mfma_f32_16x16x32_bf16 v[112:115], v[132:135], v[216:219], v[112:115]
	v_mfma_f32_16x16x32_bf16 v[108:111], v[150:153], v[216:219], v[108:111]
	v_mfma_f32_16x16x32_bf16 v[96:99], v[132:135], v[224:227], v[96:99]
	v_mfma_f32_16x16x32_bf16 v[92:95], v[150:153], v[224:227], v[92:95]
	v_mfma_f32_16x16x32_bf16 v[80:83], v[132:135], v[236:239], v[80:83]
	v_mfma_f32_16x16x32_bf16 v[76:79], v[150:153], v[236:239], v[76:79]
	v_mfma_f32_16x16x32_bf16 v[128:131], v[136:139], v[212:215], v[128:131]
	v_mfma_f32_16x16x32_bf16 v[124:127], v[174:177], v[212:215], v[124:127]
	v_mfma_f32_16x16x32_bf16 v[112:115], v[136:139], v[220:223], v[112:115]
	v_mfma_f32_16x16x32_bf16 v[108:111], v[174:177], v[220:223], v[108:111]
	v_mfma_f32_16x16x32_bf16 v[96:99], v[136:139], v[228:231], v[96:99]
	v_mfma_f32_16x16x32_bf16 v[92:95], v[174:177], v[228:231], v[92:95]
	v_mfma_f32_16x16x32_bf16 v[80:83], v[136:139], v[240:243], v[80:83]
	v_mfma_f32_16x16x32_bf16 v[76:79], v[174:177], v[240:243], v[76:79]
	s_setprio 0
	s_setprio 1
	v_mfma_f32_16x16x32_bf16 v[120:123], v[178:181], v[194:197], v[120:123]
	v_mfma_f32_16x16x32_bf16 v[116:119], v[186:189], v[194:197], v[116:119]
	v_mfma_f32_16x16x32_bf16 v[104:107], v[178:181], v[216:219], v[104:107]
	v_mfma_f32_16x16x32_bf16 v[100:103], v[186:189], v[216:219], v[100:103]
	v_mfma_f32_16x16x32_bf16 v[88:91], v[178:181], v[224:227], v[88:91]
	v_mfma_f32_16x16x32_bf16 v[84:87], v[186:189], v[224:227], v[84:87]
	v_mfma_f32_16x16x32_bf16 v[72:75], v[178:181], v[236:239], v[72:75]
	v_mfma_f32_16x16x32_bf16 v[68:71], v[186:189], v[236:239], v[68:71]
	v_mfma_f32_16x16x32_bf16 v[120:123], v[182:185], v[212:215], v[120:123]
	v_mfma_f32_16x16x32_bf16 v[116:119], v[190:193], v[212:215], v[116:119]
	v_mfma_f32_16x16x32_bf16 v[104:107], v[182:185], v[220:223], v[104:107]
	v_mfma_f32_16x16x32_bf16 v[100:103], v[190:193], v[220:223], v[100:103]
	v_mfma_f32_16x16x32_bf16 v[88:91], v[182:185], v[228:231], v[88:91]
	v_mfma_f32_16x16x32_bf16 v[84:87], v[190:193], v[228:231], v[84:87]
	v_mfma_f32_16x16x32_bf16 v[72:75], v[182:185], v[240:243], v[72:75]
	v_mfma_f32_16x16x32_bf16 v[68:71], v[190:193], v[240:243], v[68:71]
	s_setprio 0
	s_barrier
; #define PG8_STAGE(bufoff, gbase, voff) do { _Pragma("unroll") for (int _i = 0; _i < 2; ++_i) \
;         __builtin_amdgcn_global_load_lds((const unsigned*)((const char*)(gbase) + (voff)[_i]), (PG8_LAS unsigned*)(lds + (bufoff) + ldsw + _i * 8192), 16, 0, 0); } while (0)
; #define PG8_LDA(dst, b, h) do { _Pragma("unroll") for (int m = 0; m < 4; ++m) _Pragma("unroll") for (int k = 0; k < 2; ++k) dst[m][k] = *(const PG8_LAS bf16x8*)(lds + PG8_SA(b, h) + aoff + m * 2048 + k * 1024); } while (0)
; #define PG8_MMA(ai, bj, At, Bt) do { __builtin_amdgcn_s_setprio(1); _Pragma("unroll") for (int m = 0; m < 4; ++m) _Pragma("unroll") for (int n = 0; n < 2; ++n) _Pragma("unroll") for (int k = 0; k < 2; ++k) \
;         acc[ai][bj][m][n] = __builtin_amdgcn_mfma_f32_16x16x32_bf16(Bt[n][k], At[m][k], acc[ai][bj][m][n], 0, 0, 0); __builtin_amdgcn_s_setprio(0); } while (0)
; #define PG8_WAIT_V(n) asm volatile("s_waitcnt vmcnt(" #n ")" ::: "memory")
; #define PG8_WAIT_L(n) asm volatile("s_waitcnt lgkmcnt(" #n ")" ::: "memory")
; #define PG8_BAR __builtin_amdgcn_s_barrier()
; #define PG8_SCHED __builtin_amdgcn_sched_barrier(0)
; template <class Epi, class Sched, bool ALIGN_EPI = false, bool SP2 = false>
; __device__ __forceinline__ void gemm_phase(PG8_LAS unsigned char* lds, const Gemm g, const Sched& S, const Epi& E, const int tid) {
;     ...
;         for (int t = 0; t < nt; t += 2) {
;             const bool last = (t == nt - 2);
;     ...
;             PG8_LDA(At, 1, 1); PG8_STAGE(PG8_SB(1, 0), b3, voffB); PG8_STAGE(PG8_SB(1, 1), b3 + hstep, voffB); PG8_STAGE(PG8_SA(1, 0), a3, voffA);
;             PG8_WAIT_V(8); PG8_WAIT_L(0); PG8_BAR; PG8_MMA(1, 0, At, B0); PG8_MMA(1, 1, At, B1); PG8_BAR; PG8_SCHED;
	s_add_i32 s12, s12, s53
	v_lshl_add_u64 v[160:161], v[160:161], 0, s[18:19]
	s_mov_b32 m0, s12
	ds_read_b128 v[194:197], v172 offset:49152
	ds_read_b128 v[212:215], v172 offset:50176
	ds_read_b128 v[216:219], v172 offset:51200
	ds_read_b128 v[220:223], v172 offset:52224
	ds_read_b128 v[224:227], v172 offset:53248
	ds_read_b128 v[228:231], v172 offset:54272
	ds_read_b128 v[236:239], v172 offset:55296
	ds_read_b128 v[240:243], v172 offset:56320
	global_load_lds_dwordx4 v[160:161], off
	s_add_i32 m0, s12, 0x2000
	s_add_u32 s28, s28, 0x80080
	v_lshl_add_u64 v[160:161], v[198:199], 0, s[18:19]
	s_addc_u32 s29, s29, 0
	s_add_i32 s12, s14, s53
	global_load_lds_dwordx4 v[160:161], off
	v_lshl_add_u64 v[160:161], s[28:29], 0, v[142:143]
	s_mov_b32 m0, s12
	s_nop 0
	global_load_lds_dwordx4 v[160:161], off
	v_lshl_add_u64 v[160:161], s[28:29], 0, v[0:1]
	s_add_i32 m0, s12, 0x2000
	s_nop 0
	global_load_lds_dwordx4 v[160:161], off
	v_lshl_add_u64 v[160:161], v[244:245], 0, s[18:19]
	s_mov_b32 m0, s5
	s_nop 0
	global_load_lds_dwordx4 v[160:161], off
	v_lshl_add_u64 v[160:161], v[246:247], 0, s[18:19]
	s_mov_b32 m0, s6
	s_nop 0
	global_load_lds_dwordx4 v[160:161], off
	s_waitcnt vmcnt(8)
	s_waitcnt lgkmcnt(0)
	s_barrier
	s_setprio 1
	s_waitcnt lgkmcnt(0)
	v_mfma_f32_16x16x32_bf16 v[64:67], v[132:135], v[194:197], v[64:67]
	v_mfma_f32_16x16x32_bf16 v[60:63], v[150:153], v[194:197], v[60:63]
	v_mfma_f32_16x16x32_bf16 v[48:51], v[132:135], v[216:219], v[48:51]
	v_mfma_f32_16x16x32_bf16 v[44:47], v[150:153], v[216:219], v[44:47]
	v_mfma_f32_16x16x32_bf16 v[32:35], v[132:135], v[224:227], v[32:35]
	v_mfma_f32_16x16x32_bf16 v[28:31], v[150:153], v[224:227], v[28:31]
	v_mfma_f32_16x16x32_bf16 v[16:19], v[132:135], v[236:239], v[16:19]
	v_mfma_f32_16x16x32_bf16 v[12:15], v[150:153], v[236:239], v[12:15]
	v_mfma_f32_16x16x32_bf16 v[64:67], v[136:139], v[212:215], v[64:67]
	v_mfma_f32_16x16x32_bf16 v[60:63], v[174:177], v[212:215], v[60:63]
	v_mfma_f32_16x16x32_bf16 v[48:51], v[136:139], v[220:223], v[48:51]
	v_mfma_f32_16x16x32_bf16 v[44:47], v[174:177], v[220:223], v[44:47]
	v_mfma_f32_16x16x32_bf16 v[32:35], v[136:139], v[228:231], v[32:35]
	v_mfma_f32_16x16x32_bf16 v[28:31], v[174:177], v[228:231], v[28:31]
	v_mfma_f32_16x16x32_bf16 v[16:19], v[136:139], v[240:243], v[16:19]
	v_mfma_f32_16x16x32_bf16 v[12:15], v[174:177], v[240:243], v[12:15]
	s_setprio 0
	s_setprio 1
	v_mfma_f32_16x16x32_bf16 v[56:59], v[178:181], v[194:197], v[56:59]
	v_mfma_f32_16x16x32_bf16 v[52:55], v[186:189], v[194:197], v[52:55]
	s_add_i32 s23, s23, 2
	v_mfma_f32_16x16x32_bf16 v[40:43], v[178:181], v[216:219], v[40:43]
	s_add_u32 s24, s24, 0x100
	v_mfma_f32_16x16x32_bf16 v[36:39], v[186:189], v[216:219], v[36:39]
	s_addc_u32 s25, s25, 0
	v_mfma_f32_16x16x32_bf16 v[24:27], v[178:181], v[224:227], v[24:27]
	s_add_u32 s21, s21, 0x100
	v_mfma_f32_16x16x32_bf16 v[20:23], v[186:189], v[224:227], v[20:23]
	s_addc_u32 s22, s22, 0
	v_mfma_f32_16x16x32_bf16 v[8:11], v[178:181], v[236:239], v[8:11]
	s_cmp_gt_u32 s23, 29
	v_mfma_f32_16x16x32_bf16 v[4:7], v[186:189], v[236:239], v[4:7]
	v_mfma_f32_16x16x32_bf16 v[56:59], v[182:185], v[212:215], v[56:59]
	v_mfma_f32_16x16x32_bf16 v[52:55], v[190:193], v[212:215], v[52:55]
	v_mfma_f32_16x16x32_bf16 v[40:43], v[182:185], v[220:223], v[40:43]
	v_mfma_f32_16x16x32_bf16 v[36:39], v[190:193], v[220:223], v[36:39]
	v_mfma_f32_16x16x32_bf16 v[24:27], v[182:185], v[228:231], v[24:27]
	v_mfma_f32_16x16x32_bf16 v[20:23], v[190:193], v[228:231], v[20:23]
	v_mfma_f32_16x16x32_bf16 v[8:11], v[182:185], v[240:243], v[8:11]
	v_mfma_f32_16x16x32_bf16 v[4:7], v[190:193], v[240:243], v[4:7]
	s_setprio 0
	s_barrier
	s_cbranch_scc0 .LBB0_269
	s_and_b64 vcc, exec, s[34:35]
	s_cbranch_vccz .LBB0_272
	s_barrier

; #define PG8_STAGE(bufoff, gbase, voff) do { _Pragma("unroll") for (int _i = 0; _i < 2; ++_i) \
;         __builtin_amdgcn_global_load_lds((const unsigned*)((const char*)(gbase) + (voff)[_i]), (PG8_LAS unsigned*)(lds + (bufoff) + ldsw + _i * 8192), 16, 0, 0); } while (0)
; #define PG8_LDA(dst, b, h) do { _Pragma("unroll") for (int m = 0; m < 4; ++m) _Pragma("unroll") for (int k = 0; k < 2; ++k) dst[m][k] = *(const PG8_LAS bf16x8*)(lds + PG8_SA(b, h) + aoff + m * 2048 + k * 1024); } while (0)
; #define PG8_LDB(dst, b, h) do { _Pragma("unroll") for (int n = 0; n < 2; ++n) _Pragma("unroll") for (int k = 0; k < 2; ++k) dst[n][k] = *(const PG8_LAS bf16x8*)(lds + PG8_SB(b, h) + boff + n * 2048 + k * 1024); } while (0)
; #define PG8_MMA(ai, bj, At, Bt) do { __builtin_amdgcn_s_setprio(1); _Pragma("unroll") for (int m = 0; m < 4; ++m) _Pragma("unroll") for (int n = 0; n < 2; ++n) _Pragma("unroll") for (int k = 0; k < 2; ++k) \
;         acc[ai][bj][m][n] = __builtin_amdgcn_mfma_f32_16x16x32_bf16(Bt[n][k], At[m][k], acc[ai][bj][m][n], 0, 0, 0); __builtin_amdgcn_s_setprio(0); } while (0)
; #define PG8_WAIT_V(n) asm volatile("s_waitcnt vmcnt(" #n ")" ::: "memory")
; #define PG8_WAIT_L(n) asm volatile("s_waitcnt lgkmcnt(" #n ")" ::: "memory")
; #define PG8_BAR __builtin_amdgcn_s_barrier()
; template <class Epi, class Sched, bool ALIGN_EPI = false, bool SP2 = false>
; __device__ __forceinline__ void gemm_phase(PG8_LAS unsigned char* lds, const Gemm g, const Sched& S, const Epi& E, const int tid) {
;     ...
;         for (int t = 0; t < nt; t += 2) {
;             const bool last = (t == nt - 2);
;             const char* a1 = cA + (size_t)(t + 1) * kstep;
;             const char* a2 = last ? nA : cA + (size_t)(t + 2) * kstep; const char* b2 = last ? nB : cB + (size_t)(t + 2) * kstep;
;             const char* a3 = a2 + kstep; const char* b3 = b2 + kstep;
;             if (last && has_next) S.a_ready(nxt);
;             if constexpr (SP2) {
;             PG8_LDB(B0, 0, 0); PG8_LDB(B1, 0, 1); PG8_SCHED; PG8_LDA(At, 0, 0); PG8_STAGE(PG8_SA(1, 1), a1 + hstep, voffA);
;             PG8_WAIT_V(8); PG8_WAIT_L(0); PG8_BAR; PG8_MMA(0, 0, At, B0); PG8_MMA(0, 1, At, B1); PG8_BAR; PG8_SCHED;
;             PG8_LDA(At, 0, 1); PG8_STAGE(PG8_SB(0, 0), b2, voffB); PG8_STAGE(PG8_SB(0, 1), b2 + hstep, voffB); PG8_STAGE(PG8_SA(0, 0), a2, voffA);
.LBB0_975:
	s_add_i32 s51, 0, 0x10000
	v_add_u32_e32 v2, s51, v152
	ds_read_b128 v[142:145], v2
	ds_read_b128 v[146:149], v2 offset:1024
	ds_read_b128 v[170:173], v2 offset:2048
	ds_read_b128 v[174:177], v2 offset:3072
	s_add_u32 s12, s36, 0xfffc0080
	s_addc_u32 s14, s37, -1
	s_cmp_eq_u32 s50, 12
	s_cselect_b32 s45, s13, s14
	s_cselect_b32 s44, s15, s12
	s_cselect_b32 s43, s22, s35
	s_cselect_b32 s42, s23, s29
	s_add_i32 s12, 0, 0x14000
	v_add_u32_e32 v2, s12, v152
	ds_read_b128 v[178:181], v2
	ds_read_b128 v[182:185], v2 offset:1024
	ds_read_b128 v[186:189], v2 offset:2048
	ds_read_b128 v[190:193], v2 offset:3072
	v_lshl_add_u64 v[160:161], s[36:37], 0, v[138:139]
	s_add_i32 m0, s7, 0xc000
	ds_read_b128 v[194:197], v153
	ds_read_b128 v[212:215], v153 offset:1024
	ds_read_b128 v[216:219], v153 offset:2048
	ds_read_b128 v[220:223], v153 offset:3072
	ds_read_b128 v[224:227], v153 offset:4096
	ds_read_b128 v[228:231], v153 offset:5120
	ds_read_b128 v[236:239], v153 offset:6144
	ds_read_b128 v[240:243], v153 offset:7168
	global_load_lds_dwordx4 v[160:161], off
	v_lshl_add_u64 v[160:161], s[36:37], 0, v[140:141]
	s_add_i32 m0, s7, 0xe000
	s_nop 0
	global_load_lds_dwordx4 v[160:161], off
	s_waitcnt vmcnt(8)
	s_waitcnt lgkmcnt(0)
	s_barrier
	s_setprio 1
	s_waitcnt lgkmcnt(0)
	v_mfma_f32_16x16x32_bf16 v[128:131], v[142:145], v[194:197], v[128:131]
	v_mfma_f32_16x16x32_bf16 v[124:127], v[170:173], v[194:197], v[124:127]
	v_mfma_f32_16x16x32_bf16 v[112:115], v[142:145], v[216:219], v[112:115]
	v_mfma_f32_16x16x32_bf16 v[108:111], v[170:173], v[216:219], v[108:111]
	v_mfma_f32_16x16x32_bf16 v[96:99], v[142:145], v[224:227], v[96:99]
	v_mfma_f32_16x16x32_bf16 v[92:95], v[170:173], v[224:227], v[92:95]
	v_mfma_f32_16x16x32_bf16 v[80:83], v[142:145], v[236:239], v[80:83]
	v_mfma_f32_16x16x32_bf16 v[76:79], v[170:173], v[236:239], v[76:79]
	v_mfma_f32_16x16x32_bf16 v[128:131], v[146:149], v[212:215], v[128:131]
	v_mfma_f32_16x16x32_bf16 v[124:127], v[174:177], v[212:215], v[124:127]
	v_mfma_f32_16x16x32_bf16 v[112:115], v[146:149], v[220:223], v[112:115]
	v_mfma_f32_16x16x32_bf16 v[108:111], v[174:177], v[220:223], v[108:111]
	v_mfma_f32_16x16x32_bf16 v[96:99], v[146:149], v[228:231], v[96:99]
	v_mfma_f32_16x16x32_bf16 v[92:95], v[174:177], v[228:231], v[92:95]
	v_mfma_f32_16x16x32_bf16 v[80:83], v[146:149], v[240:243], v[80:83]
	v_mfma_f32_16x16x32_bf16 v[76:79], v[174:177], v[240:243], v[76:79]
	s_setprio 0
	s_setprio 1
	v_mfma_f32_16x16x32_bf16 v[120:123], v[178:181], v[194:197], v[120:123]
	v_mfma_f32_16x16x32_bf16 v[116:119], v[186:189], v[194:197], v[116:119]
	v_mfma_f32_16x16x32_bf16 v[104:107], v[178:181], v[216:219], v[104:107]
	v_mfma_f32_16x16x32_bf16 v[100:103], v[186:189], v[216:219], v[100:103]
	v_mfma_f32_16x16x32_bf16 v[88:91], v[178:181], v[224:227], v[88:91]
	v_mfma_f32_16x16x32_bf16 v[84:87], v[186:189], v[224:227], v[84:87]
	v_mfma_f32_16x16x32_bf16 v[72:75], v[178:181], v[236:239], v[72:75]
	v_mfma_f32_16x16x32_bf16 v[68:71], v[186:189], v[236:239], v[68:71]
	v_mfma_f32_16x16x32_bf16 v[120:123], v[182:185], v[212:215], v[120:123]
	v_mfma_f32_16x16x32_bf16 v[116:119], v[190:193], v[212:215], v[116:119]
	v_mfma_f32_16x16x32_bf16 v[104:107], v[182:185], v[220:223], v[104:107]
	v_mfma_f32_16x16x32_bf16 v[100:103], v[190:193], v[220:223], v[100:103]
	v_mfma_f32_16x16x32_bf16 v[88:91], v[182:185], v[228:231], v[88:91]
	v_mfma_f32_16x16x32_bf16 v[84:87], v[190:193], v[228:231], v[84:87]
	v_mfma_f32_16x16x32_bf16 v[72:75], v[182:185], v[240:243], v[72:75]
	v_mfma_f32_16x16x32_bf16 v[68:71], v[190:193], v[240:243], v[68:71]
	s_setprio 0
	s_barrier
	s_add_i32 s14, s51, s6
	v_lshl_add_u64 v[160:161], s[42:43], 0, v[134:135]
	s_mov_b32 m0, s14
	ds_read_b128 v[194:197], v153 offset:16384
	ds_read_b128 v[212:215], v153 offset:17408
	ds_read_b128 v[216:219], v153 offset:18432
	ds_read_b128 v[220:223], v153 offset:19456
	ds_read_b128 v[224:227], v153 offset:20480
	ds_read_b128 v[228:231], v153 offset:21504
	ds_read_b128 v[236:239], v153 offset:22528
	ds_read_b128 v[240:243], v153 offset:23552
	global_load_lds_dwordx4 v[160:161], off
	s_add_i32 m0, s14, 0x2000
	s_add_u32 s52, s42, 0x40000
	v_lshl_add_u64 v[198:199], s[42:43], 0, v[0:1]
	s_addc_u32 s53, s43, 0
	s_add_i32 s12, s12, s6
	global_load_lds_dwordx4 v[198:199], off
	v_lshl_add_u64 v[244:245], s[52:53], 0, v[134:135]
	s_mov_b32 m0, s12
	v_lshl_add_u64 v[246:247], s[44:45], 0, v[132:133]
	global_load_lds_dwordx4 v[244:245], off
	v_lshl_add_u64 v[244:245], s[52:53], 0, v[0:1]
	s_add_i32 m0, s12, 0x2000
	s_nop 0
	global_load_lds_dwordx4 v[244:245], off
	v_lshl_add_u64 v[244:245], s[44:45], 0, v[136:137]
	s_mov_b32 m0, s7
	s_nop 0
	global_load_lds_dwordx4 v[244:245], off
	s_mov_b32 m0, s8
	s_nop 0
	global_load_lds_dwordx4 v[246:247], off
	s_waitcnt vmcnt(8)
	s_waitcnt lgkmcnt(0)
	s_barrier
; #define PG8_STAGE(bufoff, gbase, voff) do { _Pragma("unroll") for (int _i = 0; _i < 2; ++_i) \
;         __builtin_amdgcn_global_load_lds((const unsigned*)((const char*)(gbase) + (voff)[_i]), (PG8_LAS unsigned*)(lds + (bufoff) + ldsw + _i * 8192), 16, 0, 0); } while (0)
; #define PG8_LDA(dst, b, h) do { _Pragma("unroll") for (int m = 0; m < 4; ++m) _Pragma("unroll") for (int k = 0; k < 2; ++k) dst[m][k] = *(const PG8_LAS bf16x8*)(lds + PG8_SA(b, h) + aoff + m * 2048 + k * 1024); } while (0)
; #define PG8_LDB(dst, b, h) do { _Pragma("unroll") for (int n = 0; n < 2; ++n) _Pragma("unroll") for (int k = 0; k < 2; ++k) dst[n][k] = *(const PG8_LAS bf16x8*)(lds + PG8_SB(b, h) + boff + n * 2048 + k * 1024); } while (0)
; #define PG8_MMA(ai, bj, At, Bt) do { __builtin_amdgcn_s_setprio(1); _Pragma("unroll") for (int m = 0; m < 4; ++m) _Pragma("unroll") for (int n = 0; n < 2; ++n) _Pragma("unroll") for (int k = 0; k < 2; ++k) \
;         acc[ai][bj][m][n] = __builtin_amdgcn_mfma_f32_16x16x32_bf16(Bt[n][k], At[m][k], acc[ai][bj][m][n], 0, 0, 0); __builtin_amdgcn_s_setprio(0); } while (0)
; #define PG8_WAIT_V(n) asm volatile("s_waitcnt vmcnt(" #n ")" ::: "memory")
; #define PG8_WAIT_L(n) asm volatile("s_waitcnt lgkmcnt(" #n ")" ::: "memory")
; #define PG8_BAR __builtin_amdgcn_s_barrier()
; #define PG8_SCHED __builtin_amdgcn_sched_barrier(0)
; template <class Epi, class Sched, bool ALIGN_EPI = false, bool SP2 = false>
; __device__ __forceinline__ void gemm_phase(PG8_LAS unsigned char* lds, const Gemm g, const Sched& S, const Epi& E, const int tid) {
;     ...
;             PG8_WAIT_V(8); PG8_WAIT_L(0); PG8_BAR; PG8_MMA(1, 0, At, B0); PG8_MMA(1, 1, At, B1); PG8_BAR; PG8_SCHED;
;             PG8_LDB(B0, 1, 0); PG8_LDB(B1, 1, 1); PG8_SCHED; PG8_LDA(At, 1, 0); PG8_STAGE(PG8_SA(0, 1), a2 + hstep, voffA);
;             PG8_WAIT_V(8); PG8_WAIT_L(0); PG8_BAR; PG8_MMA(0, 0, At, B0); PG8_MMA(0, 1, At, B1); PG8_BAR; PG8_SCHED;
	s_setprio 1
	s_waitcnt lgkmcnt(0)
	v_mfma_f32_16x16x32_bf16 v[64:67], v[142:145], v[194:197], v[64:67]
	v_mfma_f32_16x16x32_bf16 v[60:63], v[170:173], v[194:197], v[60:63]
	v_mfma_f32_16x16x32_bf16 v[48:51], v[142:145], v[216:219], v[48:51]
	v_mfma_f32_16x16x32_bf16 v[44:47], v[170:173], v[216:219], v[44:47]
	v_mfma_f32_16x16x32_bf16 v[32:35], v[142:145], v[224:227], v[32:35]
	v_mfma_f32_16x16x32_bf16 v[28:31], v[170:173], v[224:227], v[28:31]
	v_mfma_f32_16x16x32_bf16 v[16:19], v[142:145], v[236:239], v[16:19]
	v_mfma_f32_16x16x32_bf16 v[12:15], v[170:173], v[236:239], v[12:15]
	v_mfma_f32_16x16x32_bf16 v[64:67], v[146:149], v[212:215], v[64:67]
	v_mfma_f32_16x16x32_bf16 v[60:63], v[174:177], v[212:215], v[60:63]
	v_mfma_f32_16x16x32_bf16 v[48:51], v[146:149], v[220:223], v[48:51]
	v_mfma_f32_16x16x32_bf16 v[44:47], v[174:177], v[220:223], v[44:47]
	v_mfma_f32_16x16x32_bf16 v[32:35], v[146:149], v[228:231], v[32:35]
	v_mfma_f32_16x16x32_bf16 v[28:31], v[174:177], v[228:231], v[28:31]
	v_mfma_f32_16x16x32_bf16 v[16:19], v[146:149], v[240:243], v[16:19]
	v_mfma_f32_16x16x32_bf16 v[12:15], v[174:177], v[240:243], v[12:15]
	s_setprio 0
	s_setprio 1
	v_mfma_f32_16x16x32_bf16 v[56:59], v[178:181], v[194:197], v[56:59]
	v_mfma_f32_16x16x32_bf16 v[52:55], v[186:189], v[194:197], v[52:55]
	v_mfma_f32_16x16x32_bf16 v[40:43], v[178:181], v[216:219], v[40:43]
	v_mfma_f32_16x16x32_bf16 v[36:39], v[186:189], v[216:219], v[36:39]
	v_mfma_f32_16x16x32_bf16 v[24:27], v[178:181], v[224:227], v[24:27]
	v_mfma_f32_16x16x32_bf16 v[20:23], v[186:189], v[224:227], v[20:23]
	v_mfma_f32_16x16x32_bf16 v[8:11], v[178:181], v[236:239], v[8:11]
	v_mfma_f32_16x16x32_bf16 v[4:7], v[186:189], v[236:239], v[4:7]
	v_mfma_f32_16x16x32_bf16 v[56:59], v[182:185], v[212:215], v[56:59]
	v_mfma_f32_16x16x32_bf16 v[52:55], v[190:193], v[212:215], v[52:55]
	v_mfma_f32_16x16x32_bf16 v[40:43], v[182:185], v[220:223], v[40:43]
	v_mfma_f32_16x16x32_bf16 v[36:39], v[190:193], v[220:223], v[36:39]
	v_mfma_f32_16x16x32_bf16 v[24:27], v[182:185], v[228:231], v[24:27]
	v_mfma_f32_16x16x32_bf16 v[20:23], v[190:193], v[228:231], v[20:23]
	v_mfma_f32_16x16x32_bf16 v[8:11], v[182:185], v[240:243], v[8:11]
	v_mfma_f32_16x16x32_bf16 v[4:7], v[190:193], v[240:243], v[4:7]
	s_setprio 0
	s_barrier
	s_add_i32 s12, 0, 0x18000
	v_add_u32_e32 v2, s12, v152
	s_add_i32 s14, 0, 0x1c000
	ds_read_b128 v[142:145], v2
	ds_read_b128 v[146:149], v2 offset:1024
	ds_read_b128 v[170:173], v2 offset:2048
	ds_read_b128 v[174:177], v2 offset:3072
	v_add_u32_e32 v2, s14, v152
	ds_read_b128 v[178:181], v2
	ds_read_b128 v[182:185], v2 offset:1024
	ds_read_b128 v[186:189], v2 offset:2048
	ds_read_b128 v[190:193], v2 offset:3072
	s_add_u32 s44, s44, 0x40000
	s_addc_u32 s45, s45, 0
	s_mov_b32 m0, s9
	v_lshl_add_u64 v[248:249], s[44:45], 0, v[136:137]
	ds_read_b128 v[194:197], v153 offset:32768
	ds_read_b128 v[212:215], v153 offset:33792
	ds_read_b128 v[216:219], v153 offset:34816
	ds_read_b128 v[220:223], v153 offset:35840
	ds_read_b128 v[224:227], v153 offset:36864
	ds_read_b128 v[228:231], v153 offset:37888
	ds_read_b128 v[236:239], v153 offset:38912
	ds_read_b128 v[240:243], v153 offset:39936
	global_load_lds_dwordx4 v[248:249], off
	v_lshl_add_u64 v[248:249], s[44:45], 0, v[132:133]
	s_mov_b32 m0, s30
	s_nop 0
	global_load_lds_dwordx4 v[248:249], off
	s_waitcnt vmcnt(8)
	s_waitcnt lgkmcnt(0)
	s_barrier
	s_setprio 1
	s_waitcnt lgkmcnt(0)
	v_mfma_f32_16x16x32_bf16 v[128:131], v[142:145], v[194:197], v[128:131]
	v_mfma_f32_16x16x32_bf16 v[124:127], v[170:173], v[194:197], v[124:127]
	v_mfma_f32_16x16x32_bf16 v[112:115], v[142:145], v[216:219], v[112:115]
	v_mfma_f32_16x16x32_bf16 v[108:111], v[170:173], v[216:219], v[108:111]
	v_mfma_f32_16x16x32_bf16 v[96:99], v[142:145], v[224:227], v[96:99]
	v_mfma_f32_16x16x32_bf16 v[92:95], v[170:173], v[224:227], v[92:95]
	v_mfma_f32_16x16x32_bf16 v[80:83], v[142:145], v[236:239], v[80:83]
	v_mfma_f32_16x16x32_bf16 v[76:79], v[170:173], v[236:239], v[76:79]
	v_mfma_f32_16x16x32_bf16 v[128:131], v[146:149], v[212:215], v[128:131]
	v_mfma_f32_16x16x32_bf16 v[124:127], v[174:177], v[212:215], v[124:127]
	v_mfma_f32_16x16x32_bf16 v[112:115], v[146:149], v[220:223], v[112:115]
	v_mfma_f32_16x16x32_bf16 v[108:111], v[174:177], v[220:223], v[108:111]
	v_mfma_f32_16x16x32_bf16 v[96:99], v[146:149], v[228:231], v[96:99]
	v_mfma_f32_16x16x32_bf16 v[92:95], v[174:177], v[228:231], v[92:95]
	v_mfma_f32_16x16x32_bf16 v[80:83], v[146:149], v[240:243], v[80:83]
	v_mfma_f32_16x16x32_bf16 v[76:79], v[174:177], v[240:243], v[76:79]
	s_setprio 0
	s_setprio 1
	v_mfma_f32_16x16x32_bf16 v[120:123], v[178:181], v[194:197], v[120:123]
	v_mfma_f32_16x16x32_bf16 v[116:119], v[186:189], v[194:197], v[116:119]
	v_mfma_f32_16x16x32_bf16 v[104:107], v[178:181], v[216:219], v[104:107]
	v_mfma_f32_16x16x32_bf16 v[100:103], v[186:189], v[216:219], v[100:103]
	v_mfma_f32_16x16x32_bf16 v[88:91], v[178:181], v[224:227], v[88:91]
	v_mfma_f32_16x16x32_bf16 v[84:87], v[186:189], v[224:227], v[84:87]
	v_mfma_f32_16x16x32_bf16 v[72:75], v[178:181], v[236:239], v[72:75]
	v_mfma_f32_16x16x32_bf16 v[68:71], v[186:189], v[236:239], v[68:71]
	v_mfma_f32_16x16x32_bf16 v[120:123], v[182:185], v[212:215], v[120:123]
	v_mfma_f32_16x16x32_bf16 v[116:119], v[190:193], v[212:215], v[116:119]
	v_mfma_f32_16x16x32_bf16 v[104:107], v[182:185], v[220:223], v[104:107]
	v_mfma_f32_16x16x32_bf16 v[100:103], v[190:193], v[220:223], v[100:103]
	v_mfma_f32_16x16x32_bf16 v[88:91], v[182:185], v[228:231], v[88:91]
	v_mfma_f32_16x16x32_bf16 v[84:87], v[190:193], v[228:231], v[84:87]
	v_mfma_f32_16x16x32_bf16 v[72:75], v[182:185], v[240:243], v[72:75]
	v_mfma_f32_16x16x32_bf16 v[68:71], v[190:193], v[240:243], v[68:71]
	s_setprio 0
	s_barrier
; #define PG8_STAGE(bufoff, gbase, voff) do { _Pragma("unroll") for (int _i = 0; _i < 2; ++_i) \
;         __builtin_amdgcn_global_load_lds((const unsigned*)((const char*)(gbase) + (voff)[_i]), (PG8_LAS unsigned*)(lds + (bufoff) + ldsw + _i * 8192), 16, 0, 0); } while (0)
; #define PG8_LDA(dst, b, h) do { _Pragma("unroll") for (int m = 0; m < 4; ++m) _Pragma("unroll") for (int k = 0; k < 2; ++k) dst[m][k] = *(const PG8_LAS bf16x8*)(lds + PG8_SA(b, h) + aoff + m * 2048 + k * 1024); } while (0)
; #define PG8_MMA(ai, bj, At, Bt) do { __builtin_amdgcn_s_setprio(1); _Pragma("unroll") for (int m = 0; m < 4; ++m) _Pragma("unroll") for (int n = 0; n < 2; ++n) _Pragma("unroll") for (int k = 0; k < 2; ++k) \
;         acc[ai][bj][m][n] = __builtin_amdgcn_mfma_f32_16x16x32_bf16(Bt[n][k], At[m][k], acc[ai][bj][m][n], 0, 0, 0); __builtin_amdgcn_s_setprio(0); } while (0)
; #define PG8_WAIT_V(n) asm volatile("s_waitcnt vmcnt(" #n ")" ::: "memory")
; #define PG8_WAIT_L(n) asm volatile("s_waitcnt lgkmcnt(" #n ")" ::: "memory")
; #define PG8_BAR __builtin_amdgcn_s_barrier()
; #define PG8_SCHED __builtin_amdgcn_sched_barrier(0)
; template <class Epi, class Sched, bool ALIGN_EPI = false, bool SP2 = false>
; __device__ __forceinline__ void gemm_phase(PG8_LAS unsigned char* lds, const Gemm g, const Sched& S, const Epi& E, const int tid) {
;     ...
;         for (int t = 0; t < nt; t += 2) {
;             const bool last = (t == nt - 2);
;     ...
;             PG8_LDA(At, 1, 1); PG8_STAGE(PG8_SB(1, 0), b3, voffB); PG8_STAGE(PG8_SB(1, 1), b3 + hstep, voffB); PG8_STAGE(PG8_SA(1, 0), a3, voffA);
;             PG8_WAIT_V(8); PG8_WAIT_L(0); PG8_BAR; PG8_MMA(1, 0, At, B0); PG8_MMA(1, 1, At, B1); PG8_BAR; PG8_SCHED;
	s_add_i32 s12, s12, s6
	v_lshl_add_u64 v[160:161], v[160:161], 0, s[18:19]
	s_mov_b32 m0, s12
	ds_read_b128 v[194:197], v153 offset:49152
	ds_read_b128 v[212:215], v153 offset:50176
	ds_read_b128 v[216:219], v153 offset:51200
	ds_read_b128 v[220:223], v153 offset:52224
	ds_read_b128 v[224:227], v153 offset:53248
	ds_read_b128 v[228:231], v153 offset:54272
	ds_read_b128 v[236:239], v153 offset:55296
	ds_read_b128 v[240:243], v153 offset:56320
	global_load_lds_dwordx4 v[160:161], off
	s_add_i32 m0, s12, 0x2000
	s_add_u32 s42, s42, 0x40080
	v_lshl_add_u64 v[160:161], v[198:199], 0, s[18:19]
	s_addc_u32 s43, s43, 0
	s_add_i32 s12, s14, s6
	global_load_lds_dwordx4 v[160:161], off
	v_lshl_add_u64 v[160:161], s[42:43], 0, v[134:135]
	s_mov_b32 m0, s12
	s_nop 0
	global_load_lds_dwordx4 v[160:161], off
	v_lshl_add_u64 v[160:161], s[42:43], 0, v[0:1]
	s_add_i32 m0, s12, 0x2000
	s_nop 0
	global_load_lds_dwordx4 v[160:161], off
	v_lshl_add_u64 v[160:161], v[244:245], 0, s[18:19]
	s_mov_b32 m0, s55
	s_nop 0
	global_load_lds_dwordx4 v[160:161], off
	v_lshl_add_u64 v[160:161], v[246:247], 0, s[18:19]
	s_mov_b32 m0, s60
	s_nop 0
	global_load_lds_dwordx4 v[160:161], off
	s_waitcnt vmcnt(8)
	s_waitcnt lgkmcnt(0)
	s_barrier
	s_setprio 1
	s_waitcnt lgkmcnt(0)
	v_mfma_f32_16x16x32_bf16 v[64:67], v[142:145], v[194:197], v[64:67]
	v_mfma_f32_16x16x32_bf16 v[60:63], v[170:173], v[194:197], v[60:63]
	v_mfma_f32_16x16x32_bf16 v[48:51], v[142:145], v[216:219], v[48:51]
	v_mfma_f32_16x16x32_bf16 v[44:47], v[170:173], v[216:219], v[44:47]
	v_mfma_f32_16x16x32_bf16 v[32:35], v[142:145], v[224:227], v[32:35]
	v_mfma_f32_16x16x32_bf16 v[28:31], v[170:173], v[224:227], v[28:31]
	v_mfma_f32_16x16x32_bf16 v[16:19], v[142:145], v[236:239], v[16:19]
	v_mfma_f32_16x16x32_bf16 v[12:15], v[170:173], v[236:239], v[12:15]
	v_mfma_f32_16x16x32_bf16 v[64:67], v[146:149], v[212:215], v[64:67]
	v_mfma_f32_16x16x32_bf16 v[60:63], v[174:177], v[212:215], v[60:63]
	v_mfma_f32_16x16x32_bf16 v[48:51], v[146:149], v[220:223], v[48:51]
	v_mfma_f32_16x16x32_bf16 v[44:47], v[174:177], v[220:223], v[44:47]
	v_mfma_f32_16x16x32_bf16 v[32:35], v[146:149], v[228:231], v[32:35]
	v_mfma_f32_16x16x32_bf16 v[28:31], v[174:177], v[228:231], v[28:31]
	v_mfma_f32_16x16x32_bf16 v[16:19], v[146:149], v[240:243], v[16:19]
	v_mfma_f32_16x16x32_bf16 v[12:15], v[174:177], v[240:243], v[12:15]
	s_setprio 0
	s_setprio 1
	v_mfma_f32_16x16x32_bf16 v[56:59], v[178:181], v[194:197], v[56:59]
	v_mfma_f32_16x16x32_bf16 v[52:55], v[186:189], v[194:197], v[52:55]
	s_add_i32 s50, s50, 2
	v_mfma_f32_16x16x32_bf16 v[40:43], v[178:181], v[216:219], v[40:43]
	s_add_u32 s36, s36, 0x100
	v_mfma_f32_16x16x32_bf16 v[36:39], v[186:189], v[216:219], v[36:39]
	s_addc_u32 s37, s37, 0
	v_mfma_f32_16x16x32_bf16 v[24:27], v[178:181], v[224:227], v[24:27]
	s_add_u32 s29, s29, 0x100
	v_mfma_f32_16x16x32_bf16 v[20:23], v[186:189], v[224:227], v[20:23]
	s_addc_u32 s35, s35, 0
	v_mfma_f32_16x16x32_bf16 v[8:11], v[178:181], v[236:239], v[8:11]
	s_cmp_gt_u32 s50, 13
	v_mfma_f32_16x16x32_bf16 v[4:7], v[186:189], v[236:239], v[4:7]
	v_mfma_f32_16x16x32_bf16 v[56:59], v[182:185], v[212:215], v[56:59]
	v_mfma_f32_16x16x32_bf16 v[52:55], v[190:193], v[212:215], v[52:55]
	v_mfma_f32_16x16x32_bf16 v[40:43], v[182:185], v[220:223], v[40:43]
	v_mfma_f32_16x16x32_bf16 v[36:39], v[190:193], v[220:223], v[36:39]
	v_mfma_f32_16x16x32_bf16 v[24:27], v[182:185], v[228:231], v[24:27]
	v_mfma_f32_16x16x32_bf16 v[20:23], v[190:193], v[228:231], v[20:23]
	v_mfma_f32_16x16x32_bf16 v[8:11], v[182:185], v[240:243], v[8:11]
	v_mfma_f32_16x16x32_bf16 v[4:7], v[190:193], v[240:243], v[4:7]
	s_setprio 0
	s_barrier
	s_cbranch_scc0 .LBB0_975
	s_and_b64 vcc, exec, s[24:25]
	s_cbranch_vccz .LBB0_978
	s_barrier

; #define PG8_STAGE(bufoff, gbase, voff) do { _Pragma("unroll") for (int _i = 0; _i < 2; ++_i) \
;         __builtin_amdgcn_global_load_lds((const unsigned*)((const char*)(gbase) + (voff)[_i]), (PG8_LAS unsigned*)(lds + (bufoff) + ldsw + _i * 8192), 16, 0, 0); } while (0)
; #define PG8_LDA(dst, b, h) do { _Pragma("unroll") for (int m = 0; m < 4; ++m) _Pragma("unroll") for (int k = 0; k < 2; ++k) dst[m][k] = *(const PG8_LAS bf16x8*)(lds + PG8_SA(b, h) + aoff + m * 2048 + k * 1024); } while (0)
; #define PG8_LDB(dst, b, h) do { _Pragma("unroll") for (int n = 0; n < 2; ++n) _Pragma("unroll") for (int k = 0; k < 2; ++k) dst[n][k] = *(const PG8_LAS bf16x8*)(lds + PG8_SB(b, h) + boff + n * 2048 + k * 1024); } while (0)
; #define PG8_MMA(ai, bj, At, Bt) do { __builtin_amdgcn_s_setprio(1); _Pragma("unroll") for (int m = 0; m < 4; ++m) _Pragma("unroll") for (int n = 0; n < 2; ++n) _Pragma("unroll") for (int k = 0; k < 2; ++k) \
;         acc[ai][bj][m][n] = __builtin_amdgcn_mfma_f32_16x16x32_bf16(Bt[n][k], At[m][k], acc[ai][bj][m][n], 0, 0, 0); __builtin_amdgcn_s_setprio(0); } while (0)
; #define PG8_WAIT_V(n) asm volatile("s_waitcnt vmcnt(" #n ")" ::: "memory")
; #define PG8_WAIT_L(n) asm volatile("s_waitcnt lgkmcnt(" #n ")" ::: "memory")
; #define PG8_BAR __builtin_amdgcn_s_barrier()
; template <class Epi, class Sched, bool ALIGN_EPI = false, bool SP2 = false>
; __device__ __forceinline__ void gemm_phase(PG8_LAS unsigned char* lds, const Gemm g, const Sched& S, const Epi& E, const int tid) {
;     ...
;         for (int t = 0; t < nt; t += 2) {
;             const bool last = (t == nt - 2);
;             const char* a1 = cA + (size_t)(t + 1) * kstep;
;             const char* a2 = last ? nA : cA + (size_t)(t + 2) * kstep; const char* b2 = last ? nB : cB + (size_t)(t + 2) * kstep;
;             const char* a3 = a2 + kstep; const char* b3 = b2 + kstep;
;             if (last && has_next) S.a_ready(nxt);
;             if constexpr (SP2) {
;             PG8_LDB(B0, 0, 0); PG8_LDB(B1, 0, 1); PG8_SCHED; PG8_LDA(At, 0, 0); PG8_STAGE(PG8_SA(1, 1), a1 + hstep, voffA);
;             PG8_WAIT_V(8); PG8_WAIT_L(0); PG8_BAR; PG8_MMA(0, 0, At, B0); PG8_MMA(0, 1, At, B1); PG8_BAR; PG8_SCHED;
;             PG8_LDA(At, 0, 1); PG8_STAGE(PG8_SB(0, 0), b2, voffB); PG8_STAGE(PG8_SB(0, 1), b2 + hstep, voffB); PG8_STAGE(PG8_SA(0, 0), a2, voffA);
.LBB0_1149:
	s_add_i32 s51, 0, 0x10000
	v_add_u32_e32 v2, s51, v147
	ds_read_b128 v[138:141], v2
	ds_read_b128 v[170:173], v2 offset:1024
	ds_read_b128 v[174:177], v2 offset:2048
	ds_read_b128 v[178:181], v2 offset:3072
	s_add_u32 s12, s36, 0xfffc0080
	s_addc_u32 s14, s37, -1
	s_cmp_eq_u32 s49, 12
	s_cselect_b32 s47, s13, s14
	s_cselect_b32 s46, s15, s12
	s_cselect_b32 s45, s22, s48
	s_cselect_b32 s44, s23, s35
	s_add_i32 s12, 0, 0x14000
	v_add_u32_e32 v2, s12, v147
	ds_read_b128 v[182:185], v2
	ds_read_b128 v[186:189], v2 offset:1024
	ds_read_b128 v[190:193], v2 offset:2048
	ds_read_b128 v[194:197], v2 offset:3072
	v_lshl_add_u64 v[142:143], s[36:37], 0, v[134:135]
	s_add_i32 m0, s7, 0xc000
	ds_read_b128 v[212:215], v152
	ds_read_b128 v[216:219], v152 offset:1024
	ds_read_b128 v[220:223], v152 offset:2048
	ds_read_b128 v[224:227], v152 offset:3072
	ds_read_b128 v[228:231], v152 offset:4096
	ds_read_b128 v[236:239], v152 offset:5120
	ds_read_b128 v[240:243], v152 offset:6144
	ds_read_b128 v[244:247], v152 offset:7168
	global_load_lds_dwordx4 v[142:143], off
	v_lshl_add_u64 v[142:143], s[36:37], 0, v[136:137]
	s_add_i32 m0, s7, 0xe000
	s_nop 0
	global_load_lds_dwordx4 v[142:143], off
	s_waitcnt vmcnt(8)
	s_waitcnt lgkmcnt(0)
	s_barrier
	s_setprio 1
	s_waitcnt lgkmcnt(0)
	v_mfma_f32_16x16x32_bf16 v[128:131], v[138:141], v[212:215], v[128:131]
	v_mfma_f32_16x16x32_bf16 v[124:127], v[174:177], v[212:215], v[124:127]
	v_mfma_f32_16x16x32_bf16 v[112:115], v[138:141], v[220:223], v[112:115]
	v_mfma_f32_16x16x32_bf16 v[108:111], v[174:177], v[220:223], v[108:111]
	v_mfma_f32_16x16x32_bf16 v[96:99], v[138:141], v[228:231], v[96:99]
	v_mfma_f32_16x16x32_bf16 v[92:95], v[174:177], v[228:231], v[92:95]
	v_mfma_f32_16x16x32_bf16 v[80:83], v[138:141], v[240:243], v[80:83]
	v_mfma_f32_16x16x32_bf16 v[76:79], v[174:177], v[240:243], v[76:79]
	v_mfma_f32_16x16x32_bf16 v[128:131], v[170:173], v[216:219], v[128:131]
	v_mfma_f32_16x16x32_bf16 v[124:127], v[178:181], v[216:219], v[124:127]
	v_mfma_f32_16x16x32_bf16 v[112:115], v[170:173], v[224:227], v[112:115]
	v_mfma_f32_16x16x32_bf16 v[108:111], v[178:181], v[224:227], v[108:111]
	v_mfma_f32_16x16x32_bf16 v[96:99], v[170:173], v[236:239], v[96:99]
	v_mfma_f32_16x16x32_bf16 v[92:95], v[178:181], v[236:239], v[92:95]
	v_mfma_f32_16x16x32_bf16 v[80:83], v[170:173], v[244:247], v[80:83]
	v_mfma_f32_16x16x32_bf16 v[76:79], v[178:181], v[244:247], v[76:79]
	s_setprio 0
	s_setprio 1
	v_mfma_f32_16x16x32_bf16 v[120:123], v[182:185], v[212:215], v[120:123]
	v_mfma_f32_16x16x32_bf16 v[116:119], v[190:193], v[212:215], v[116:119]
	v_mfma_f32_16x16x32_bf16 v[104:107], v[182:185], v[220:223], v[104:107]
	v_mfma_f32_16x16x32_bf16 v[100:103], v[190:193], v[220:223], v[100:103]
	v_mfma_f32_16x16x32_bf16 v[88:91], v[182:185], v[228:231], v[88:91]
	v_mfma_f32_16x16x32_bf16 v[84:87], v[190:193], v[228:231], v[84:87]
	v_mfma_f32_16x16x32_bf16 v[72:75], v[182:185], v[240:243], v[72:75]
	v_mfma_f32_16x16x32_bf16 v[68:71], v[190:193], v[240:243], v[68:71]
	v_mfma_f32_16x16x32_bf16 v[120:123], v[186:189], v[216:219], v[120:123]
	v_mfma_f32_16x16x32_bf16 v[116:119], v[194:197], v[216:219], v[116:119]
	v_mfma_f32_16x16x32_bf16 v[104:107], v[186:189], v[224:227], v[104:107]
	v_mfma_f32_16x16x32_bf16 v[100:103], v[194:197], v[224:227], v[100:103]
	v_mfma_f32_16x16x32_bf16 v[88:91], v[186:189], v[236:239], v[88:91]
	v_mfma_f32_16x16x32_bf16 v[84:87], v[194:197], v[236:239], v[84:87]
	v_mfma_f32_16x16x32_bf16 v[72:75], v[186:189], v[244:247], v[72:75]
	v_mfma_f32_16x16x32_bf16 v[68:71], v[194:197], v[244:247], v[68:71]
	s_setprio 0
	s_barrier
	s_add_i32 s14, s51, s6
	v_lshl_add_u64 v[142:143], s[44:45], 0, v[132:133]
	s_mov_b32 m0, s14
	ds_read_b128 v[212:215], v152 offset:16384
	ds_read_b128 v[216:219], v152 offset:17408
	ds_read_b128 v[220:223], v152 offset:18432
	ds_read_b128 v[224:227], v152 offset:19456
	ds_read_b128 v[228:231], v152 offset:20480
	ds_read_b128 v[236:239], v152 offset:21504
	ds_read_b128 v[240:243], v152 offset:22528
	ds_read_b128 v[244:247], v152 offset:23552
	global_load_lds_dwordx4 v[142:143], off
	s_add_i32 m0, s14, 0x2000
	s_add_u32 s52, s44, 0x40000
	v_lshl_add_u64 v[160:161], s[44:45], 0, v[0:1]
	s_addc_u32 s53, s45, 0
	s_add_i32 s12, s12, s6
	global_load_lds_dwordx4 v[160:161], off
	v_lshl_add_u64 v[198:199], s[52:53], 0, v[132:133]
	s_mov_b32 m0, s12
	v_lshl_add_u64 v[248:249], s[46:47], 0, v[0:1]
	global_load_lds_dwordx4 v[198:199], off
	v_lshl_add_u64 v[198:199], s[52:53], 0, v[0:1]
	s_add_i32 m0, s12, 0x2000
	s_nop 0
	global_load_lds_dwordx4 v[198:199], off
	v_lshl_add_u64 v[198:199], s[46:47], 0, v[132:133]
	s_mov_b32 m0, s7
	s_nop 0
	global_load_lds_dwordx4 v[198:199], off
	s_mov_b32 m0, s30
	s_nop 0
	global_load_lds_dwordx4 v[248:249], off
	s_waitcnt vmcnt(8)
	s_waitcnt lgkmcnt(0)
	s_barrier
; #define PG8_STAGE(bufoff, gbase, voff) do { _Pragma("unroll") for (int _i = 0; _i < 2; ++_i) \
;         __builtin_amdgcn_global_load_lds((const unsigned*)((const char*)(gbase) + (voff)[_i]), (PG8_LAS unsigned*)(lds + (bufoff) + ldsw + _i * 8192), 16, 0, 0); } while (0)
; #define PG8_LDA(dst, b, h) do { _Pragma("unroll") for (int m = 0; m < 4; ++m) _Pragma("unroll") for (int k = 0; k < 2; ++k) dst[m][k] = *(const PG8_LAS bf16x8*)(lds + PG8_SA(b, h) + aoff + m * 2048 + k * 1024); } while (0)
; #define PG8_LDB(dst, b, h) do { _Pragma("unroll") for (int n = 0; n < 2; ++n) _Pragma("unroll") for (int k = 0; k < 2; ++k) dst[n][k] = *(const PG8_LAS bf16x8*)(lds + PG8_SB(b, h) + boff + n * 2048 + k * 1024); } while (0)
; #define PG8_MMA(ai, bj, At, Bt) do { __builtin_amdgcn_s_setprio(1); _Pragma("unroll") for (int m = 0; m < 4; ++m) _Pragma("unroll") for (int n = 0; n < 2; ++n) _Pragma("unroll") for (int k = 0; k < 2; ++k) \
;         acc[ai][bj][m][n] = __builtin_amdgcn_mfma_f32_16x16x32_bf16(Bt[n][k], At[m][k], acc[ai][bj][m][n], 0, 0, 0); __builtin_amdgcn_s_setprio(0); } while (0)
; #define PG8_WAIT_V(n) asm volatile("s_waitcnt vmcnt(" #n ")" ::: "memory")
; #define PG8_WAIT_L(n) asm volatile("s_waitcnt lgkmcnt(" #n ")" ::: "memory")
; #define PG8_BAR __builtin_amdgcn_s_barrier()
; #define PG8_SCHED __builtin_amdgcn_sched_barrier(0)
; template <class Epi, class Sched, bool ALIGN_EPI = false, bool SP2 = false>
; __device__ __forceinline__ void gemm_phase(PG8_LAS unsigned char* lds, const Gemm g, const Sched& S, const Epi& E, const int tid) {
;     ...
;             PG8_WAIT_V(8); PG8_WAIT_L(0); PG8_BAR; PG8_MMA(1, 0, At, B0); PG8_MMA(1, 1, At, B1); PG8_BAR; PG8_SCHED;
;             PG8_LDB(B0, 1, 0); PG8_LDB(B1, 1, 1); PG8_SCHED; PG8_LDA(At, 1, 0); PG8_STAGE(PG8_SA(0, 1), a2 + hstep, voffA);
;             PG8_WAIT_V(8); PG8_WAIT_L(0); PG8_BAR; PG8_MMA(0, 0, At, B0); PG8_MMA(0, 1, At, B1); PG8_BAR; PG8_SCHED;
	s_setprio 1
	s_waitcnt lgkmcnt(0)
	v_mfma_f32_16x16x32_bf16 v[64:67], v[138:141], v[212:215], v[64:67]
	v_mfma_f32_16x16x32_bf16 v[60:63], v[174:177], v[212:215], v[60:63]
	v_mfma_f32_16x16x32_bf16 v[48:51], v[138:141], v[220:223], v[48:51]
	v_mfma_f32_16x16x32_bf16 v[44:47], v[174:177], v[220:223], v[44:47]
	v_mfma_f32_16x16x32_bf16 v[32:35], v[138:141], v[228:231], v[32:35]
	v_mfma_f32_16x16x32_bf16 v[28:31], v[174:177], v[228:231], v[28:31]
	v_mfma_f32_16x16x32_bf16 v[16:19], v[138:141], v[240:243], v[16:19]
	v_mfma_f32_16x16x32_bf16 v[12:15], v[174:177], v[240:243], v[12:15]
	v_mfma_f32_16x16x32_bf16 v[64:67], v[170:173], v[216:219], v[64:67]
	v_mfma_f32_16x16x32_bf16 v[60:63], v[178:181], v[216:219], v[60:63]
	v_mfma_f32_16x16x32_bf16 v[48:51], v[170:173], v[224:227], v[48:51]
	v_mfma_f32_16x16x32_bf16 v[44:47], v[178:181], v[224:227], v[44:47]
	v_mfma_f32_16x16x32_bf16 v[32:35], v[170:173], v[236:239], v[32:35]
	v_mfma_f32_16x16x32_bf16 v[28:31], v[178:181], v[236:239], v[28:31]
	v_mfma_f32_16x16x32_bf16 v[16:19], v[170:173], v[244:247], v[16:19]
	v_mfma_f32_16x16x32_bf16 v[12:15], v[178:181], v[244:247], v[12:15]
	s_setprio 0
	s_setprio 1
	v_mfma_f32_16x16x32_bf16 v[56:59], v[182:185], v[212:215], v[56:59]
	v_mfma_f32_16x16x32_bf16 v[52:55], v[190:193], v[212:215], v[52:55]
	v_mfma_f32_16x16x32_bf16 v[40:43], v[182:185], v[220:223], v[40:43]
	v_mfma_f32_16x16x32_bf16 v[36:39], v[190:193], v[220:223], v[36:39]
	v_mfma_f32_16x16x32_bf16 v[24:27], v[182:185], v[228:231], v[24:27]
	v_mfma_f32_16x16x32_bf16 v[20:23], v[190:193], v[228:231], v[20:23]
	v_mfma_f32_16x16x32_bf16 v[8:11], v[182:185], v[240:243], v[8:11]
	v_mfma_f32_16x16x32_bf16 v[4:7], v[190:193], v[240:243], v[4:7]
	v_mfma_f32_16x16x32_bf16 v[56:59], v[186:189], v[216:219], v[56:59]
	v_mfma_f32_16x16x32_bf16 v[52:55], v[194:197], v[216:219], v[52:55]
	v_mfma_f32_16x16x32_bf16 v[40:43], v[186:189], v[224:227], v[40:43]
	v_mfma_f32_16x16x32_bf16 v[36:39], v[194:197], v[224:227], v[36:39]
	v_mfma_f32_16x16x32_bf16 v[24:27], v[186:189], v[236:239], v[24:27]
	v_mfma_f32_16x16x32_bf16 v[20:23], v[194:197], v[236:239], v[20:23]
	v_mfma_f32_16x16x32_bf16 v[8:11], v[186:189], v[244:247], v[8:11]
	v_mfma_f32_16x16x32_bf16 v[4:7], v[194:197], v[244:247], v[4:7]
	s_setprio 0
	s_barrier
	s_add_i32 s12, 0, 0x18000
	v_add_u32_e32 v2, s12, v147
	s_add_i32 s14, 0, 0x1c000
	ds_read_b128 v[138:141], v2
	ds_read_b128 v[170:173], v2 offset:1024
	ds_read_b128 v[174:177], v2 offset:2048
	ds_read_b128 v[178:181], v2 offset:3072
	v_add_u32_e32 v2, s14, v147
	ds_read_b128 v[182:185], v2
	ds_read_b128 v[186:189], v2 offset:1024
	ds_read_b128 v[190:193], v2 offset:2048
	ds_read_b128 v[194:197], v2 offset:3072
	s_add_u32 s46, s46, 0x40000
	s_addc_u32 s47, s47, 0
	s_mov_b32 m0, s54
	v_lshl_add_u64 v[250:251], s[46:47], 0, v[132:133]
	ds_read_b128 v[212:215], v152 offset:32768
	ds_read_b128 v[216:219], v152 offset:33792
	ds_read_b128 v[220:223], v152 offset:34816
	ds_read_b128 v[224:227], v152 offset:35840
	ds_read_b128 v[228:231], v152 offset:36864
	ds_read_b128 v[236:239], v152 offset:37888
	ds_read_b128 v[240:243], v152 offset:38912
	ds_read_b128 v[244:247], v152 offset:39936
	global_load_lds_dwordx4 v[250:251], off
	v_lshl_add_u64 v[250:251], s[46:47], 0, v[0:1]
	s_mov_b32 m0, s55
	s_nop 0
	global_load_lds_dwordx4 v[250:251], off
	s_waitcnt vmcnt(8)
	s_waitcnt lgkmcnt(0)
	s_barrier
	s_setprio 1
	s_waitcnt lgkmcnt(0)
	v_mfma_f32_16x16x32_bf16 v[128:131], v[138:141], v[212:215], v[128:131]
	v_mfma_f32_16x16x32_bf16 v[124:127], v[174:177], v[212:215], v[124:127]
	v_mfma_f32_16x16x32_bf16 v[112:115], v[138:141], v[220:223], v[112:115]
	v_mfma_f32_16x16x32_bf16 v[108:111], v[174:177], v[220:223], v[108:111]
	v_mfma_f32_16x16x32_bf16 v[96:99], v[138:141], v[228:231], v[96:99]
	v_mfma_f32_16x16x32_bf16 v[92:95], v[174:177], v[228:231], v[92:95]
	v_mfma_f32_16x16x32_bf16 v[80:83], v[138:141], v[240:243], v[80:83]
	v_mfma_f32_16x16x32_bf16 v[76:79], v[174:177], v[240:243], v[76:79]
	v_mfma_f32_16x16x32_bf16 v[128:131], v[170:173], v[216:219], v[128:131]
	v_mfma_f32_16x16x32_bf16 v[124:127], v[178:181], v[216:219], v[124:127]
	v_mfma_f32_16x16x32_bf16 v[112:115], v[170:173], v[224:227], v[112:115]
	v_mfma_f32_16x16x32_bf16 v[108:111], v[178:181], v[224:227], v[108:111]
	v_mfma_f32_16x16x32_bf16 v[96:99], v[170:173], v[236:239], v[96:99]
	v_mfma_f32_16x16x32_bf16 v[92:95], v[178:181], v[236:239], v[92:95]
	v_mfma_f32_16x16x32_bf16 v[80:83], v[170:173], v[244:247], v[80:83]
	v_mfma_f32_16x16x32_bf16 v[76:79], v[178:181], v[244:247], v[76:79]
	s_setprio 0
	s_setprio 1
	v_mfma_f32_16x16x32_bf16 v[120:123], v[182:185], v[212:215], v[120:123]
	v_mfma_f32_16x16x32_bf16 v[116:119], v[190:193], v[212:215], v[116:119]
	v_mfma_f32_16x16x32_bf16 v[104:107], v[182:185], v[220:223], v[104:107]
	v_mfma_f32_16x16x32_bf16 v[100:103], v[190:193], v[220:223], v[100:103]
	v_mfma_f32_16x16x32_bf16 v[88:91], v[182:185], v[228:231], v[88:91]
	v_mfma_f32_16x16x32_bf16 v[84:87], v[190:193], v[228:231], v[84:87]
	v_mfma_f32_16x16x32_bf16 v[72:75], v[182:185], v[240:243], v[72:75]
	v_mfma_f32_16x16x32_bf16 v[68:71], v[190:193], v[240:243], v[68:71]
	v_mfma_f32_16x16x32_bf16 v[120:123], v[186:189], v[216:219], v[120:123]
	v_mfma_f32_16x16x32_bf16 v[116:119], v[194:197], v[216:219], v[116:119]
	v_mfma_f32_16x16x32_bf16 v[104:107], v[186:189], v[224:227], v[104:107]
	v_mfma_f32_16x16x32_bf16 v[100:103], v[194:197], v[224:227], v[100:103]
	v_mfma_f32_16x16x32_bf16 v[88:91], v[186:189], v[236:239], v[88:91]
	v_mfma_f32_16x16x32_bf16 v[84:87], v[194:197], v[236:239], v[84:87]
	v_mfma_f32_16x16x32_bf16 v[72:75], v[186:189], v[244:247], v[72:75]
	v_mfma_f32_16x16x32_bf16 v[68:71], v[194:197], v[244:247], v[68:71]
	s_setprio 0
	s_barrier
; #define PG8_STAGE(bufoff, gbase, voff) do { _Pragma("unroll") for (int _i = 0; _i < 2; ++_i) \
;         __builtin_amdgcn_global_load_lds((const unsigned*)((const char*)(gbase) + (voff)[_i]), (PG8_LAS unsigned*)(lds + (bufoff) + ldsw + _i * 8192), 16, 0, 0); } while (0)
; #define PG8_LDA(dst, b, h) do { _Pragma("unroll") for (int m = 0; m < 4; ++m) _Pragma("unroll") for (int k = 0; k < 2; ++k) dst[m][k] = *(const PG8_LAS bf16x8*)(lds + PG8_SA(b, h) + aoff + m * 2048 + k * 1024); } while (0)
; #define PG8_MMA(ai, bj, At, Bt) do { __builtin_amdgcn_s_setprio(1); _Pragma("unroll") for (int m = 0; m < 4; ++m) _Pragma("unroll") for (int n = 0; n < 2; ++n) _Pragma("unroll") for (int k = 0; k < 2; ++k) \
;         acc[ai][bj][m][n] = __builtin_amdgcn_mfma_f32_16x16x32_bf16(Bt[n][k], At[m][k], acc[ai][bj][m][n], 0, 0, 0); __builtin_amdgcn_s_setprio(0); } while (0)
; #define PG8_WAIT_V(n) asm volatile("s_waitcnt vmcnt(" #n ")" ::: "memory")
; #define PG8_WAIT_L(n) asm volatile("s_waitcnt lgkmcnt(" #n ")" ::: "memory")
; #define PG8_BAR __builtin_amdgcn_s_barrier()
; #define PG8_SCHED __builtin_amdgcn_sched_barrier(0)
; template <class Epi, class Sched, bool ALIGN_EPI = false, bool SP2 = false>
; __device__ __forceinline__ void gemm_phase(PG8_LAS unsigned char* lds, const Gemm g, const Sched& S, const Epi& E, const int tid) {
;     ...
;         for (int t = 0; t < nt; t += 2) {
;             const bool last = (t == nt - 2);
;     ...
;             PG8_LDA(At, 1, 1); PG8_STAGE(PG8_SB(1, 0), b3, voffB); PG8_STAGE(PG8_SB(1, 1), b3 + hstep, voffB); PG8_STAGE(PG8_SA(1, 0), a3, voffA);
;             PG8_WAIT_V(8); PG8_WAIT_L(0); PG8_BAR; PG8_MMA(1, 0, At, B0); PG8_MMA(1, 1, At, B1); PG8_BAR; PG8_SCHED;
	s_add_i32 s12, s12, s6
	v_lshl_add_u64 v[142:143], v[142:143], 0, s[18:19]
	s_mov_b32 m0, s12
	ds_read_b128 v[212:215], v152 offset:49152
	ds_read_b128 v[216:219], v152 offset:50176
	ds_read_b128 v[220:223], v152 offset:51200
	ds_read_b128 v[224:227], v152 offset:52224
	ds_read_b128 v[228:231], v152 offset:53248
	ds_read_b128 v[236:239], v152 offset:54272
	ds_read_b128 v[240:243], v152 offset:55296
	ds_read_b128 v[244:247], v152 offset:56320
	global_load_lds_dwordx4 v[142:143], off
	s_add_i32 m0, s12, 0x2000
	s_add_u32 s44, s44, 0x40080
	v_lshl_add_u64 v[142:143], v[160:161], 0, s[18:19]
	s_addc_u32 s45, s45, 0
	s_add_i32 s12, s14, s6
	global_load_lds_dwordx4 v[142:143], off
	v_lshl_add_u64 v[142:143], s[44:45], 0, v[132:133]
	s_mov_b32 m0, s12
	s_nop 0
	global_load_lds_dwordx4 v[142:143], off
	v_lshl_add_u64 v[142:143], s[44:45], 0, v[0:1]
	s_add_i32 m0, s12, 0x2000
	s_nop 0
	global_load_lds_dwordx4 v[142:143], off
	v_lshl_add_u64 v[142:143], v[198:199], 0, s[18:19]
	s_mov_b32 m0, s8
	s_nop 0
	global_load_lds_dwordx4 v[142:143], off
	v_lshl_add_u64 v[142:143], v[248:249], 0, s[18:19]
	s_mov_b32 m0, s9
	s_nop 0
	global_load_lds_dwordx4 v[142:143], off
	s_waitcnt vmcnt(8)
	s_waitcnt lgkmcnt(0)
	s_barrier
	s_setprio 1
	s_waitcnt lgkmcnt(0)
	v_mfma_f32_16x16x32_bf16 v[64:67], v[138:141], v[212:215], v[64:67]
	v_mfma_f32_16x16x32_bf16 v[60:63], v[174:177], v[212:215], v[60:63]
	v_mfma_f32_16x16x32_bf16 v[48:51], v[138:141], v[220:223], v[48:51]
	v_mfma_f32_16x16x32_bf16 v[44:47], v[174:177], v[220:223], v[44:47]
	v_mfma_f32_16x16x32_bf16 v[32:35], v[138:141], v[228:231], v[32:35]
	v_mfma_f32_16x16x32_bf16 v[28:31], v[174:177], v[228:231], v[28:31]
	v_mfma_f32_16x16x32_bf16 v[16:19], v[138:141], v[240:243], v[16:19]
	v_mfma_f32_16x16x32_bf16 v[12:15], v[174:177], v[240:243], v[12:15]
	v_mfma_f32_16x16x32_bf16 v[64:67], v[170:173], v[216:219], v[64:67]
	v_mfma_f32_16x16x32_bf16 v[60:63], v[178:181], v[216:219], v[60:63]
	v_mfma_f32_16x16x32_bf16 v[48:51], v[170:173], v[224:227], v[48:51]
	v_mfma_f32_16x16x32_bf16 v[44:47], v[178:181], v[224:227], v[44:47]
	v_mfma_f32_16x16x32_bf16 v[32:35], v[170:173], v[236:239], v[32:35]
	v_mfma_f32_16x16x32_bf16 v[28:31], v[178:181], v[236:239], v[28:31]
	v_mfma_f32_16x16x32_bf16 v[16:19], v[170:173], v[244:247], v[16:19]
	v_mfma_f32_16x16x32_bf16 v[12:15], v[178:181], v[244:247], v[12:15]
	s_setprio 0
	s_setprio 1
	v_mfma_f32_16x16x32_bf16 v[56:59], v[182:185], v[212:215], v[56:59]
	v_mfma_f32_16x16x32_bf16 v[52:55], v[190:193], v[212:215], v[52:55]
	s_add_i32 s49, s49, 2
	v_mfma_f32_16x16x32_bf16 v[40:43], v[182:185], v[220:223], v[40:43]
	s_add_u32 s36, s36, 0x100
	v_mfma_f32_16x16x32_bf16 v[36:39], v[190:193], v[220:223], v[36:39]
	s_addc_u32 s37, s37, 0
	v_mfma_f32_16x16x32_bf16 v[24:27], v[182:185], v[228:231], v[24:27]
	s_add_u32 s35, s35, 0x100
	v_mfma_f32_16x16x32_bf16 v[20:23], v[190:193], v[228:231], v[20:23]
	s_addc_u32 s48, s48, 0
	v_mfma_f32_16x16x32_bf16 v[8:11], v[182:185], v[240:243], v[8:11]
	s_cmp_gt_u32 s49, 13
	v_mfma_f32_16x16x32_bf16 v[4:7], v[190:193], v[240:243], v[4:7]
	v_mfma_f32_16x16x32_bf16 v[56:59], v[186:189], v[216:219], v[56:59]
	v_mfma_f32_16x16x32_bf16 v[52:55], v[194:197], v[216:219], v[52:55]
	v_mfma_f32_16x16x32_bf16 v[40:43], v[186:189], v[224:227], v[40:43]
	v_mfma_f32_16x16x32_bf16 v[36:39], v[194:197], v[224:227], v[36:39]
	v_mfma_f32_16x16x32_bf16 v[24:27], v[186:189], v[236:239], v[24:27]
	v_mfma_f32_16x16x32_bf16 v[20:23], v[194:197], v[236:239], v[20:23]
	v_mfma_f32_16x16x32_bf16 v[8:11], v[186:189], v[244:247], v[8:11]
	v_mfma_f32_16x16x32_bf16 v[4:7], v[194:197], v[244:247], v[4:7]
	s_setprio 0
	s_barrier
	s_cbranch_scc0 .LBB0_1149
	s_and_b64 vcc, exec, s[28:29]
	s_cbranch_vccz .LBB0_1152
	s_barrier

; #define PG8_STAGE(bufoff, gbase, voff) do { _Pragma("unroll") for (int _i = 0; _i < 2; ++_i) \
;         __builtin_amdgcn_global_load_lds((const unsigned*)((const char*)(gbase) + (voff)[_i]), (PG8_LAS unsigned*)(lds + (bufoff) + ldsw + _i * 8192), 16, 0, 0); } while (0)
; #define PG8_LDA(dst, b, h) do { _Pragma("unroll") for (int m = 0; m < 4; ++m) _Pragma("unroll") for (int k = 0; k < 2; ++k) dst[m][k] = *(const PG8_LAS bf16x8*)(lds + PG8_SA(b, h) + aoff + m * 2048 + k * 1024); } while (0)
; #define PG8_LDB(dst, b, h) do { _Pragma("unroll") for (int n = 0; n < 2; ++n) _Pragma("unroll") for (int k = 0; k < 2; ++k) dst[n][k] = *(const PG8_LAS bf16x8*)(lds + PG8_SB(b, h) + boff + n * 2048 + k * 1024); } while (0)
; #define PG8_MMA(ai, bj, At, Bt) do { __builtin_amdgcn_s_setprio(1); _Pragma("unroll") for (int m = 0; m < 4; ++m) _Pragma("unroll") for (int n = 0; n < 2; ++n) _Pragma("unroll") for (int k = 0; k < 2; ++k) \
;         acc[ai][bj][m][n] = __builtin_amdgcn_mfma_f32_16x16x32_bf16(Bt[n][k], At[m][k], acc[ai][bj][m][n], 0, 0, 0); __builtin_amdgcn_s_setprio(0); } while (0)
; #define PG8_WAIT_V(n) asm volatile("s_waitcnt vmcnt(" #n ")" ::: "memory")
; #define PG8_WAIT_L(n) asm volatile("s_waitcnt lgkmcnt(" #n ")" ::: "memory")
; #define PG8_BAR __builtin_amdgcn_s_barrier()
; template <class Epi, class Sched, bool ALIGN_EPI = false, bool SP2 = false>
; __device__ __forceinline__ void gemm_phase(PG8_LAS unsigned char* lds, const Gemm g, const Sched& S, const Epi& E, const int tid) {
;     ...
;         for (int t = 0; t < nt; t += 2) {
;             const bool last = (t == nt - 2);
;             const char* a1 = cA + (size_t)(t + 1) * kstep;
;             const char* a2 = last ? nA : cA + (size_t)(t + 2) * kstep; const char* b2 = last ? nB : cB + (size_t)(t + 2) * kstep;
;             const char* a3 = a2 + kstep; const char* b3 = b2 + kstep;
;             if (last && has_next) S.a_ready(nxt);
;             if constexpr (SP2) {
;             PG8_LDB(B0, 0, 0); PG8_LDB(B1, 0, 1); PG8_SCHED; PG8_LDA(At, 0, 0); PG8_STAGE(PG8_SA(1, 1), a1 + hstep, voffA);
;             PG8_WAIT_V(8); PG8_WAIT_L(0); PG8_BAR; PG8_MMA(0, 0, At, B0); PG8_MMA(0, 1, At, B1); PG8_BAR; PG8_SCHED;
;             PG8_LDA(At, 0, 1); PG8_STAGE(PG8_SB(0, 0), b2, voffB); PG8_STAGE(PG8_SB(0, 1), b2 + hstep, voffB); PG8_STAGE(PG8_SA(0, 0), a2, voffA);
.LBB0_1305:
	s_add_i32 s54, 0, 0x10000
	v_add_u32_e32 v152, s54, v141
	ds_read_b128 v[144:147], v152
	ds_read_b128 v[148:151], v152 offset:1024
	ds_read_b128 v[170:173], v152 offset:2048
	ds_read_b128 v[174:177], v152 offset:3072
	s_add_u32 s12, s42, 0xfff00080
	s_addc_u32 s44, s43, -1
	s_cmp_eq_u32 s53, 60
	s_cselect_b32 s47, s29, s44
	s_cselect_b32 s46, s49, s12
	s_cselect_b32 s45, s25, s52
	s_cselect_b32 s44, s50, s51
	s_add_i32 s12, 0, 0x14000
	v_add_u32_e32 v152, s12, v141
	ds_read_b128 v[178:181], v152
	ds_read_b128 v[182:185], v152 offset:1024
	ds_read_b128 v[186:189], v152 offset:2048
	ds_read_b128 v[190:193], v152 offset:3072
	v_lshl_add_u64 v[152:153], s[42:43], 0, v[136:137]
	s_add_i32 m0, s7, 0xc000
	ds_read_b128 v[194:197], v143
	ds_read_b128 v[212:215], v143 offset:1024
	ds_read_b128 v[216:219], v143 offset:2048
	ds_read_b128 v[220:223], v143 offset:3072
	ds_read_b128 v[224:227], v143 offset:4096
	ds_read_b128 v[228:231], v143 offset:5120
	ds_read_b128 v[236:239], v143 offset:6144
	ds_read_b128 v[240:243], v143 offset:7168
	global_load_lds_dwordx4 v[152:153], off
	v_lshl_add_u64 v[152:153], s[42:43], 0, v[138:139]
	s_add_i32 m0, s7, 0xe000
	s_nop 0
	global_load_lds_dwordx4 v[152:153], off
	s_waitcnt vmcnt(8)
	s_waitcnt lgkmcnt(0)
	s_barrier
	s_setprio 1
	s_waitcnt lgkmcnt(0)
	v_mfma_f32_16x16x32_bf16 v[128:131], v[144:147], v[194:197], v[128:131]
	v_mfma_f32_16x16x32_bf16 v[124:127], v[170:173], v[194:197], v[124:127]
	v_mfma_f32_16x16x32_bf16 v[120:123], v[144:147], v[216:219], v[120:123]
	v_mfma_f32_16x16x32_bf16 v[116:119], v[170:173], v[216:219], v[116:119]
	v_mfma_f32_16x16x32_bf16 v[104:107], v[144:147], v[224:227], v[104:107]
	v_mfma_f32_16x16x32_bf16 v[100:103], v[170:173], v[224:227], v[100:103]
	v_mfma_f32_16x16x32_bf16 v[88:91], v[144:147], v[236:239], v[88:91]
	v_mfma_f32_16x16x32_bf16 v[84:87], v[170:173], v[236:239], v[84:87]
	v_mfma_f32_16x16x32_bf16 v[128:131], v[148:151], v[212:215], v[128:131]
	v_mfma_f32_16x16x32_bf16 v[124:127], v[174:177], v[212:215], v[124:127]
	v_mfma_f32_16x16x32_bf16 v[120:123], v[148:151], v[220:223], v[120:123]
	v_mfma_f32_16x16x32_bf16 v[116:119], v[174:177], v[220:223], v[116:119]
	v_mfma_f32_16x16x32_bf16 v[104:107], v[148:151], v[228:231], v[104:107]
	v_mfma_f32_16x16x32_bf16 v[100:103], v[174:177], v[228:231], v[100:103]
	v_mfma_f32_16x16x32_bf16 v[88:91], v[148:151], v[240:243], v[88:91]
	v_mfma_f32_16x16x32_bf16 v[84:87], v[174:177], v[240:243], v[84:87]
	s_setprio 0
	s_setprio 1
	v_mfma_f32_16x16x32_bf16 v[112:115], v[178:181], v[194:197], v[112:115]
	v_mfma_f32_16x16x32_bf16 v[108:111], v[186:189], v[194:197], v[108:111]
	v_mfma_f32_16x16x32_bf16 v[96:99], v[178:181], v[216:219], v[96:99]
	v_mfma_f32_16x16x32_bf16 v[92:95], v[186:189], v[216:219], v[92:95]
	v_mfma_f32_16x16x32_bf16 v[80:83], v[178:181], v[224:227], v[80:83]
	v_mfma_f32_16x16x32_bf16 v[76:79], v[186:189], v[224:227], v[76:79]
	v_mfma_f32_16x16x32_bf16 v[72:75], v[178:181], v[236:239], v[72:75]
	v_mfma_f32_16x16x32_bf16 v[68:71], v[186:189], v[236:239], v[68:71]
	v_mfma_f32_16x16x32_bf16 v[112:115], v[182:185], v[212:215], v[112:115]
	v_mfma_f32_16x16x32_bf16 v[108:111], v[190:193], v[212:215], v[108:111]
	v_mfma_f32_16x16x32_bf16 v[96:99], v[182:185], v[220:223], v[96:99]
	v_mfma_f32_16x16x32_bf16 v[92:95], v[190:193], v[220:223], v[92:95]
	v_mfma_f32_16x16x32_bf16 v[80:83], v[182:185], v[228:231], v[80:83]
	v_mfma_f32_16x16x32_bf16 v[76:79], v[190:193], v[228:231], v[76:79]
	v_mfma_f32_16x16x32_bf16 v[72:75], v[182:185], v[240:243], v[72:75]
	v_mfma_f32_16x16x32_bf16 v[68:71], v[190:193], v[240:243], v[68:71]
	s_setprio 0
	s_barrier
	s_add_i32 s54, s54, s6
	v_lshl_add_u64 v[152:153], s[44:45], 0, v[2:3]
	s_mov_b32 m0, s54
	ds_read_b128 v[194:197], v143 offset:16384
	ds_read_b128 v[212:215], v143 offset:17408
	ds_read_b128 v[216:219], v143 offset:18432
	ds_read_b128 v[220:223], v143 offset:19456
	ds_read_b128 v[224:227], v143 offset:20480
	ds_read_b128 v[228:231], v143 offset:21504
	ds_read_b128 v[236:239], v143 offset:22528
	ds_read_b128 v[240:243], v143 offset:23552
	global_load_lds_dwordx4 v[152:153], off
	s_add_i32 m0, s54, 0x2000
	s_add_u32 s54, s44, 0x100000
	v_lshl_add_u64 v[160:161], s[44:45], 0, v[0:1]
	s_addc_u32 s55, s45, 0
	s_add_i32 s12, s12, s6
	global_load_lds_dwordx4 v[160:161], off
	v_lshl_add_u64 v[198:199], s[54:55], 0, v[2:3]
	s_mov_b32 m0, s12
	v_lshl_add_u64 v[244:245], s[46:47], 0, v[132:133]
	global_load_lds_dwordx4 v[198:199], off
	v_lshl_add_u64 v[198:199], s[54:55], 0, v[0:1]
	s_add_i32 m0, s12, 0x2000
	s_nop 0
	global_load_lds_dwordx4 v[198:199], off
	v_lshl_add_u64 v[198:199], s[46:47], 0, v[134:135]
	s_mov_b32 m0, s7
	s_nop 0
	global_load_lds_dwordx4 v[198:199], off
	s_mov_b32 m0, s8
	s_nop 0
	global_load_lds_dwordx4 v[244:245], off
	s_waitcnt vmcnt(8)
	s_waitcnt lgkmcnt(0)
	s_barrier
; #define PG8_STAGE(bufoff, gbase, voff) do { _Pragma("unroll") for (int _i = 0; _i < 2; ++_i) \
;         __builtin_amdgcn_global_load_lds((const unsigned*)((const char*)(gbase) + (voff)[_i]), (PG8_LAS unsigned*)(lds + (bufoff) + ldsw + _i * 8192), 16, 0, 0); } while (0)
; #define PG8_LDA(dst, b, h) do { _Pragma("unroll") for (int m = 0; m < 4; ++m) _Pragma("unroll") for (int k = 0; k < 2; ++k) dst[m][k] = *(const PG8_LAS bf16x8*)(lds + PG8_SA(b, h) + aoff + m * 2048 + k * 1024); } while (0)
; #define PG8_LDB(dst, b, h) do { _Pragma("unroll") for (int n = 0; n < 2; ++n) _Pragma("unroll") for (int k = 0; k < 2; ++k) dst[n][k] = *(const PG8_LAS bf16x8*)(lds + PG8_SB(b, h) + boff + n * 2048 + k * 1024); } while (0)
; #define PG8_MMA(ai, bj, At, Bt) do { __builtin_amdgcn_s_setprio(1); _Pragma("unroll") for (int m = 0; m < 4; ++m) _Pragma("unroll") for (int n = 0; n < 2; ++n) _Pragma("unroll") for (int k = 0; k < 2; ++k) \
;         acc[ai][bj][m][n] = __builtin_amdgcn_mfma_f32_16x16x32_bf16(Bt[n][k], At[m][k], acc[ai][bj][m][n], 0, 0, 0); __builtin_amdgcn_s_setprio(0); } while (0)
; #define PG8_WAIT_V(n) asm volatile("s_waitcnt vmcnt(" #n ")" ::: "memory")
; #define PG8_WAIT_L(n) asm volatile("s_waitcnt lgkmcnt(" #n ")" ::: "memory")
; #define PG8_BAR __builtin_amdgcn_s_barrier()
; #define PG8_SCHED __builtin_amdgcn_sched_barrier(0)
; template <class Epi, class Sched, bool ALIGN_EPI = false, bool SP2 = false>
; __device__ __forceinline__ void gemm_phase(PG8_LAS unsigned char* lds, const Gemm g, const Sched& S, const Epi& E, const int tid) {
;     ...
;             PG8_WAIT_V(8); PG8_WAIT_L(0); PG8_BAR; PG8_MMA(1, 0, At, B0); PG8_MMA(1, 1, At, B1); PG8_BAR; PG8_SCHED;
;             PG8_LDB(B0, 1, 0); PG8_LDB(B1, 1, 1); PG8_SCHED; PG8_LDA(At, 1, 0); PG8_STAGE(PG8_SA(0, 1), a2 + hstep, voffA);
;             PG8_WAIT_V(8); PG8_WAIT_L(0); PG8_BAR; PG8_MMA(0, 0, At, B0); PG8_MMA(0, 1, At, B1); PG8_BAR; PG8_SCHED;
	s_setprio 1
	s_waitcnt lgkmcnt(0)
	v_mfma_f32_16x16x32_bf16 v[64:67], v[144:147], v[194:197], v[64:67]
	v_mfma_f32_16x16x32_bf16 v[60:63], v[170:173], v[194:197], v[60:63]
	v_mfma_f32_16x16x32_bf16 v[56:59], v[144:147], v[216:219], v[56:59]
	v_mfma_f32_16x16x32_bf16 v[52:55], v[170:173], v[216:219], v[52:55]
	v_mfma_f32_16x16x32_bf16 v[40:43], v[144:147], v[224:227], v[40:43]
	v_mfma_f32_16x16x32_bf16 v[36:39], v[170:173], v[224:227], v[36:39]
	v_mfma_f32_16x16x32_bf16 v[24:27], v[144:147], v[236:239], v[24:27]
	v_mfma_f32_16x16x32_bf16 v[20:23], v[170:173], v[236:239], v[20:23]
	v_mfma_f32_16x16x32_bf16 v[64:67], v[148:151], v[212:215], v[64:67]
	v_mfma_f32_16x16x32_bf16 v[60:63], v[174:177], v[212:215], v[60:63]
	v_mfma_f32_16x16x32_bf16 v[56:59], v[148:151], v[220:223], v[56:59]
	v_mfma_f32_16x16x32_bf16 v[52:55], v[174:177], v[220:223], v[52:55]
	v_mfma_f32_16x16x32_bf16 v[40:43], v[148:151], v[228:231], v[40:43]
	v_mfma_f32_16x16x32_bf16 v[36:39], v[174:177], v[228:231], v[36:39]
	v_mfma_f32_16x16x32_bf16 v[24:27], v[148:151], v[240:243], v[24:27]
	v_mfma_f32_16x16x32_bf16 v[20:23], v[174:177], v[240:243], v[20:23]
	s_setprio 0
	s_setprio 1
	v_mfma_f32_16x16x32_bf16 v[48:51], v[178:181], v[194:197], v[48:51]
	v_mfma_f32_16x16x32_bf16 v[44:47], v[186:189], v[194:197], v[44:47]
	v_mfma_f32_16x16x32_bf16 v[32:35], v[178:181], v[216:219], v[32:35]
	v_mfma_f32_16x16x32_bf16 v[28:31], v[186:189], v[216:219], v[28:31]
	v_mfma_f32_16x16x32_bf16 v[16:19], v[178:181], v[224:227], v[16:19]
	v_mfma_f32_16x16x32_bf16 v[12:15], v[186:189], v[224:227], v[12:15]
	v_mfma_f32_16x16x32_bf16 v[8:11], v[178:181], v[236:239], v[8:11]
	v_mfma_f32_16x16x32_bf16 v[4:7], v[186:189], v[236:239], v[4:7]
	v_mfma_f32_16x16x32_bf16 v[48:51], v[182:185], v[212:215], v[48:51]
	v_mfma_f32_16x16x32_bf16 v[44:47], v[190:193], v[212:215], v[44:47]
	v_mfma_f32_16x16x32_bf16 v[32:35], v[182:185], v[220:223], v[32:35]
	v_mfma_f32_16x16x32_bf16 v[28:31], v[190:193], v[220:223], v[28:31]
	v_mfma_f32_16x16x32_bf16 v[16:19], v[182:185], v[228:231], v[16:19]
	v_mfma_f32_16x16x32_bf16 v[12:15], v[190:193], v[228:231], v[12:15]
	v_mfma_f32_16x16x32_bf16 v[8:11], v[182:185], v[240:243], v[8:11]
	v_mfma_f32_16x16x32_bf16 v[4:7], v[190:193], v[240:243], v[4:7]
	s_setprio 0
	s_barrier
	s_add_i32 s12, 0, 0x18000
	v_add_u32_e32 v169, s12, v141
	s_add_i32 s54, 0, 0x1c000
	ds_read_b128 v[144:147], v169
	ds_read_b128 v[148:151], v169 offset:1024
	ds_read_b128 v[170:173], v169 offset:2048
	ds_read_b128 v[174:177], v169 offset:3072
	v_add_u32_e32 v169, s54, v141
	ds_read_b128 v[178:181], v169
	ds_read_b128 v[182:185], v169 offset:1024
	ds_read_b128 v[186:189], v169 offset:2048
	ds_read_b128 v[190:193], v169 offset:3072
	s_add_u32 s46, s46, 0x100000
	s_addc_u32 s47, s47, 0
	s_mov_b32 m0, s9
	v_lshl_add_u64 v[246:247], s[46:47], 0, v[134:135]
	ds_read_b128 v[194:197], v143 offset:32768
	ds_read_b128 v[212:215], v143 offset:33792
	ds_read_b128 v[216:219], v143 offset:34816
	ds_read_b128 v[220:223], v143 offset:35840
	ds_read_b128 v[224:227], v143 offset:36864
	ds_read_b128 v[228:231], v143 offset:37888
	ds_read_b128 v[236:239], v143 offset:38912
	ds_read_b128 v[240:243], v143 offset:39936
	global_load_lds_dwordx4 v[246:247], off
	v_lshl_add_u64 v[246:247], s[46:47], 0, v[132:133]
	s_mov_b32 m0, s13
	s_nop 0
	global_load_lds_dwordx4 v[246:247], off
	s_waitcnt vmcnt(8)
	s_waitcnt lgkmcnt(0)
	s_barrier
	s_setprio 1
	s_waitcnt lgkmcnt(0)
	v_mfma_f32_16x16x32_bf16 v[128:131], v[144:147], v[194:197], v[128:131]
	v_mfma_f32_16x16x32_bf16 v[124:127], v[170:173], v[194:197], v[124:127]
	v_mfma_f32_16x16x32_bf16 v[120:123], v[144:147], v[216:219], v[120:123]
	v_mfma_f32_16x16x32_bf16 v[116:119], v[170:173], v[216:219], v[116:119]
	v_mfma_f32_16x16x32_bf16 v[104:107], v[144:147], v[224:227], v[104:107]
	v_mfma_f32_16x16x32_bf16 v[100:103], v[170:173], v[224:227], v[100:103]
	v_mfma_f32_16x16x32_bf16 v[88:91], v[144:147], v[236:239], v[88:91]
	v_mfma_f32_16x16x32_bf16 v[84:87], v[170:173], v[236:239], v[84:87]
	v_mfma_f32_16x16x32_bf16 v[128:131], v[148:151], v[212:215], v[128:131]
	v_mfma_f32_16x16x32_bf16 v[124:127], v[174:177], v[212:215], v[124:127]
	v_mfma_f32_16x16x32_bf16 v[120:123], v[148:151], v[220:223], v[120:123]
	v_mfma_f32_16x16x32_bf16 v[116:119], v[174:177], v[220:223], v[116:119]
	v_mfma_f32_16x16x32_bf16 v[104:107], v[148:151], v[228:231], v[104:107]
	v_mfma_f32_16x16x32_bf16 v[100:103], v[174:177], v[228:231], v[100:103]
	v_mfma_f32_16x16x32_bf16 v[88:91], v[148:151], v[240:243], v[88:91]
	v_mfma_f32_16x16x32_bf16 v[84:87], v[174:177], v[240:243], v[84:87]
	s_setprio 0
	s_setprio 1
	v_mfma_f32_16x16x32_bf16 v[112:115], v[178:181], v[194:197], v[112:115]
	v_mfma_f32_16x16x32_bf16 v[108:111], v[186:189], v[194:197], v[108:111]
	v_mfma_f32_16x16x32_bf16 v[96:99], v[178:181], v[216:219], v[96:99]
	v_mfma_f32_16x16x32_bf16 v[92:95], v[186:189], v[216:219], v[92:95]
	v_mfma_f32_16x16x32_bf16 v[80:83], v[178:181], v[224:227], v[80:83]
	v_mfma_f32_16x16x32_bf16 v[76:79], v[186:189], v[224:227], v[76:79]
	v_mfma_f32_16x16x32_bf16 v[72:75], v[178:181], v[236:239], v[72:75]
	v_mfma_f32_16x16x32_bf16 v[68:71], v[186:189], v[236:239], v[68:71]
	v_mfma_f32_16x16x32_bf16 v[112:115], v[182:185], v[212:215], v[112:115]
	v_mfma_f32_16x16x32_bf16 v[108:111], v[190:193], v[212:215], v[108:111]
	v_mfma_f32_16x16x32_bf16 v[96:99], v[182:185], v[220:223], v[96:99]
	v_mfma_f32_16x16x32_bf16 v[92:95], v[190:193], v[220:223], v[92:95]
	v_mfma_f32_16x16x32_bf16 v[80:83], v[182:185], v[228:231], v[80:83]
	v_mfma_f32_16x16x32_bf16 v[76:79], v[190:193], v[228:231], v[76:79]
	v_mfma_f32_16x16x32_bf16 v[72:75], v[182:185], v[240:243], v[72:75]
	v_mfma_f32_16x16x32_bf16 v[68:71], v[190:193], v[240:243], v[68:71]
	s_setprio 0
	s_barrier
; #define PG8_STAGE(bufoff, gbase, voff) do { _Pragma("unroll") for (int _i = 0; _i < 2; ++_i) \
;         __builtin_amdgcn_global_load_lds((const unsigned*)((const char*)(gbase) + (voff)[_i]), (PG8_LAS unsigned*)(lds + (bufoff) + ldsw + _i * 8192), 16, 0, 0); } while (0)
; #define PG8_LDA(dst, b, h) do { _Pragma("unroll") for (int m = 0; m < 4; ++m) _Pragma("unroll") for (int k = 0; k < 2; ++k) dst[m][k] = *(const PG8_LAS bf16x8*)(lds + PG8_SA(b, h) + aoff + m * 2048 + k * 1024); } while (0)
; #define PG8_MMA(ai, bj, At, Bt) do { __builtin_amdgcn_s_setprio(1); _Pragma("unroll") for (int m = 0; m < 4; ++m) _Pragma("unroll") for (int n = 0; n < 2; ++n) _Pragma("unroll") for (int k = 0; k < 2; ++k) \
;         acc[ai][bj][m][n] = __builtin_amdgcn_mfma_f32_16x16x32_bf16(Bt[n][k], At[m][k], acc[ai][bj][m][n], 0, 0, 0); __builtin_amdgcn_s_setprio(0); } while (0)
; #define PG8_WAIT_V(n) asm volatile("s_waitcnt vmcnt(" #n ")" ::: "memory")
; #define PG8_WAIT_L(n) asm volatile("s_waitcnt lgkmcnt(" #n ")" ::: "memory")
; #define PG8_BAR __builtin_amdgcn_s_barrier()
; #define PG8_SCHED __builtin_amdgcn_sched_barrier(0)
; template <class Epi, class Sched, bool ALIGN_EPI = false, bool SP2 = false>
; __device__ __forceinline__ void gemm_phase(PG8_LAS unsigned char* lds, const Gemm g, const Sched& S, const Epi& E, const int tid) {
;     ...
;         for (int t = 0; t < nt; t += 2) {
;             const bool last = (t == nt - 2);
;     ...
;             PG8_LDA(At, 1, 1); PG8_STAGE(PG8_SB(1, 0), b3, voffB); PG8_STAGE(PG8_SB(1, 1), b3 + hstep, voffB); PG8_STAGE(PG8_SA(1, 0), a3, voffA);
;             PG8_WAIT_V(8); PG8_WAIT_L(0); PG8_BAR; PG8_MMA(1, 0, At, B0); PG8_MMA(1, 1, At, B1); PG8_BAR; PG8_SCHED;
	s_add_i32 s12, s12, s6
	v_lshl_add_u64 v[152:153], v[152:153], 0, s[18:19]
	s_mov_b32 m0, s12
	ds_read_b128 v[194:197], v143 offset:49152
	ds_read_b128 v[212:215], v143 offset:50176
	ds_read_b128 v[216:219], v143 offset:51200
	ds_read_b128 v[220:223], v143 offset:52224
	ds_read_b128 v[224:227], v143 offset:53248
	ds_read_b128 v[228:231], v143 offset:54272
	ds_read_b128 v[236:239], v143 offset:55296
	ds_read_b128 v[240:243], v143 offset:56320
	global_load_lds_dwordx4 v[152:153], off
	s_add_i32 m0, s12, 0x2000
	s_add_u32 s44, s44, 0x100080
	v_lshl_add_u64 v[152:153], v[160:161], 0, s[18:19]
	s_addc_u32 s45, s45, 0
	s_add_i32 s12, s54, s6
	global_load_lds_dwordx4 v[152:153], off
	v_lshl_add_u64 v[152:153], s[44:45], 0, v[2:3]
	s_mov_b32 m0, s12
	s_nop 0
	global_load_lds_dwordx4 v[152:153], off
	v_lshl_add_u64 v[152:153], s[44:45], 0, v[0:1]
	s_add_i32 m0, s12, 0x2000
	s_nop 0
	global_load_lds_dwordx4 v[152:153], off
	v_lshl_add_u64 v[152:153], v[198:199], 0, s[18:19]
	s_mov_b32 m0, s15
	s_nop 0
	global_load_lds_dwordx4 v[152:153], off
	v_lshl_add_u64 v[152:153], v[244:245], 0, s[18:19]
	s_mov_b32 m0, s22
	s_nop 0
	global_load_lds_dwordx4 v[152:153], off
	s_waitcnt vmcnt(8)
	s_waitcnt lgkmcnt(0)
	s_barrier
	s_setprio 1
	s_waitcnt lgkmcnt(0)
	v_mfma_f32_16x16x32_bf16 v[64:67], v[144:147], v[194:197], v[64:67]
	v_mfma_f32_16x16x32_bf16 v[60:63], v[170:173], v[194:197], v[60:63]
	v_mfma_f32_16x16x32_bf16 v[56:59], v[144:147], v[216:219], v[56:59]
	v_mfma_f32_16x16x32_bf16 v[52:55], v[170:173], v[216:219], v[52:55]
	v_mfma_f32_16x16x32_bf16 v[40:43], v[144:147], v[224:227], v[40:43]
	v_mfma_f32_16x16x32_bf16 v[36:39], v[170:173], v[224:227], v[36:39]
	v_mfma_f32_16x16x32_bf16 v[24:27], v[144:147], v[236:239], v[24:27]
	v_mfma_f32_16x16x32_bf16 v[20:23], v[170:173], v[236:239], v[20:23]
	v_mfma_f32_16x16x32_bf16 v[64:67], v[148:151], v[212:215], v[64:67]
	v_mfma_f32_16x16x32_bf16 v[60:63], v[174:177], v[212:215], v[60:63]
	v_mfma_f32_16x16x32_bf16 v[56:59], v[148:151], v[220:223], v[56:59]
	v_mfma_f32_16x16x32_bf16 v[52:55], v[174:177], v[220:223], v[52:55]
	v_mfma_f32_16x16x32_bf16 v[40:43], v[148:151], v[228:231], v[40:43]
	v_mfma_f32_16x16x32_bf16 v[36:39], v[174:177], v[228:231], v[36:39]
	v_mfma_f32_16x16x32_bf16 v[24:27], v[148:151], v[240:243], v[24:27]
	v_mfma_f32_16x16x32_bf16 v[20:23], v[174:177], v[240:243], v[20:23]
	s_setprio 0
	s_setprio 1
	v_mfma_f32_16x16x32_bf16 v[48:51], v[178:181], v[194:197], v[48:51]
	v_mfma_f32_16x16x32_bf16 v[44:47], v[186:189], v[194:197], v[44:47]
	s_add_i32 s53, s53, 2
	v_mfma_f32_16x16x32_bf16 v[32:35], v[178:181], v[216:219], v[32:35]
	s_add_u32 s42, s42, 0x100
	v_mfma_f32_16x16x32_bf16 v[28:31], v[186:189], v[216:219], v[28:31]
	s_addc_u32 s43, s43, 0
	v_mfma_f32_16x16x32_bf16 v[16:19], v[178:181], v[224:227], v[16:19]
	s_add_u32 s51, s51, 0x100
	v_mfma_f32_16x16x32_bf16 v[12:15], v[186:189], v[224:227], v[12:15]
	s_addc_u32 s52, s52, 0
	v_mfma_f32_16x16x32_bf16 v[8:11], v[178:181], v[236:239], v[8:11]
	s_cmp_gt_u32 s53, 61
	v_mfma_f32_16x16x32_bf16 v[4:7], v[186:189], v[236:239], v[4:7]
	v_mfma_f32_16x16x32_bf16 v[48:51], v[182:185], v[212:215], v[48:51]
	v_mfma_f32_16x16x32_bf16 v[44:47], v[190:193], v[212:215], v[44:47]
	v_mfma_f32_16x16x32_bf16 v[32:35], v[182:185], v[220:223], v[32:35]
	v_mfma_f32_16x16x32_bf16 v[28:31], v[190:193], v[220:223], v[28:31]
	v_mfma_f32_16x16x32_bf16 v[16:19], v[182:185], v[228:231], v[16:19]
	v_mfma_f32_16x16x32_bf16 v[12:15], v[190:193], v[228:231], v[12:15]
	v_mfma_f32_16x16x32_bf16 v[8:11], v[182:185], v[240:243], v[8:11]
	v_mfma_f32_16x16x32_bf16 v[4:7], v[190:193], v[240:243], v[4:7]
	s_setprio 0
	s_barrier
	s_cbranch_scc0 .LBB0_1305
	s_and_b64 vcc, exec, s[20:21]
	s_cbranch_vccz .LBB0_1308
	s_barrier

; #define PG8_STAGE(bufoff, gbase, voff) do { _Pragma("unroll") for (int _i = 0; _i < 2; ++_i) \
;         __builtin_amdgcn_global_load_lds((const unsigned*)((const char*)(gbase) + (voff)[_i]), (PG8_LAS unsigned*)(lds + (bufoff) + ldsw + _i * 8192), 16, 0, 0); } while (0)
; #define PG8_LDA(dst, b, h) do { _Pragma("unroll") for (int m = 0; m < 4; ++m) _Pragma("unroll") for (int k = 0; k < 2; ++k) dst[m][k] = *(const PG8_LAS bf16x8*)(lds + PG8_SA(b, h) + aoff + m * 2048 + k * 1024); } while (0)
; #define PG8_LDB(dst, b, h) do { _Pragma("unroll") for (int n = 0; n < 2; ++n) _Pragma("unroll") for (int k = 0; k < 2; ++k) dst[n][k] = *(const PG8_LAS bf16x8*)(lds + PG8_SB(b, h) + boff + n * 2048 + k * 1024); } while (0)
; #define PG8_MMA(ai, bj, At, Bt) do { __builtin_amdgcn_s_setprio(1); _Pragma("unroll") for (int m = 0; m < 4; ++m) _Pragma("unroll") for (int n = 0; n < 2; ++n) _Pragma("unroll") for (int k = 0; k < 2; ++k) \
;         acc[ai][bj][m][n] = __builtin_amdgcn_mfma_f32_16x16x32_bf16(Bt[n][k], At[m][k], acc[ai][bj][m][n], 0, 0, 0); __builtin_amdgcn_s_setprio(0); } while (0)
; #define PG8_WAIT_V(n) asm volatile("s_waitcnt vmcnt(" #n ")" ::: "memory")
; #define PG8_WAIT_L(n) asm volatile("s_waitcnt lgkmcnt(" #n ")" ::: "memory")
; #define PG8_BAR __builtin_amdgcn_s_barrier()
; template <class Epi, class Sched, bool ALIGN_EPI = false, bool SP2 = false>
; __device__ __forceinline__ void gemm_phase(PG8_LAS unsigned char* lds, const Gemm g, const Sched& S, const Epi& E, const int tid) {
;     ...
;         for (int t = 0; t < nt; t += 2) {
;             const bool last = (t == nt - 2);
;             const char* a1 = cA + (size_t)(t + 1) * kstep;
;             const char* a2 = last ? nA : cA + (size_t)(t + 2) * kstep; const char* b2 = last ? nB : cB + (size_t)(t + 2) * kstep;
;             const char* a3 = a2 + kstep; const char* b3 = b2 + kstep;
;             if (last && has_next) S.a_ready(nxt);
;             if constexpr (SP2) {
;             PG8_LDB(B0, 0, 0); PG8_LDB(B1, 0, 1); PG8_SCHED; PG8_LDA(At, 0, 0); PG8_STAGE(PG8_SA(1, 1), a1 + hstep, voffA);
;             PG8_WAIT_V(8); PG8_WAIT_L(0); PG8_BAR; PG8_MMA(0, 0, At, B0); PG8_MMA(0, 1, At, B1); PG8_BAR; PG8_SCHED;
;             PG8_LDA(At, 0, 1); PG8_STAGE(PG8_SB(0, 0), b2, voffB); PG8_STAGE(PG8_SB(0, 1), b2 + hstep, voffB); PG8_STAGE(PG8_SA(0, 0), a2, voffA);
.LBB0_1477:
	s_add_i32 s52, 0, 0x10000
	v_add_u32_e32 v152, s52, v141
	ds_read_b128 v[144:147], v152
	ds_read_b128 v[148:151], v152 offset:1024
	ds_read_b128 v[170:173], v152 offset:2048
	ds_read_b128 v[174:177], v152 offset:3072
	s_add_u32 s12, s42, 0xfff00080
	s_addc_u32 s44, s43, -1
	s_cmp_eq_u32 s51, 60
	s_cselect_b32 s47, s29, s44
	s_cselect_b32 s46, s30, s12
	s_cselect_b32 s45, s25, s50
	s_cselect_b32 s44, s48, s49
	s_add_i32 s12, 0, 0x14000
	v_add_u32_e32 v152, s12, v141
	ds_read_b128 v[178:181], v152
	ds_read_b128 v[182:185], v152 offset:1024
	ds_read_b128 v[186:189], v152 offset:2048
	ds_read_b128 v[190:193], v152 offset:3072
	v_lshl_add_u64 v[152:153], s[42:43], 0, v[136:137]
	s_add_i32 m0, s5, 0xc000
	ds_read_b128 v[194:197], v143
	ds_read_b128 v[212:215], v143 offset:1024
	ds_read_b128 v[216:219], v143 offset:2048
	ds_read_b128 v[220:223], v143 offset:3072
	ds_read_b128 v[224:227], v143 offset:4096
	ds_read_b128 v[228:231], v143 offset:5120
	ds_read_b128 v[236:239], v143 offset:6144
	ds_read_b128 v[240:243], v143 offset:7168
	global_load_lds_dwordx4 v[152:153], off
	v_lshl_add_u64 v[152:153], s[42:43], 0, v[138:139]
	s_add_i32 m0, s5, 0xe000
	s_nop 0
	global_load_lds_dwordx4 v[152:153], off
	s_waitcnt vmcnt(8)
	s_waitcnt lgkmcnt(0)
	s_barrier
	s_setprio 1
	s_waitcnt lgkmcnt(0)
	v_mfma_f32_16x16x32_bf16 v[128:131], v[144:147], v[194:197], v[128:131]
	v_mfma_f32_16x16x32_bf16 v[124:127], v[170:173], v[194:197], v[124:127]
	v_mfma_f32_16x16x32_bf16 v[120:123], v[144:147], v[216:219], v[120:123]
	v_mfma_f32_16x16x32_bf16 v[116:119], v[170:173], v[216:219], v[116:119]
	v_mfma_f32_16x16x32_bf16 v[104:107], v[144:147], v[224:227], v[104:107]
	v_mfma_f32_16x16x32_bf16 v[100:103], v[170:173], v[224:227], v[100:103]
	v_mfma_f32_16x16x32_bf16 v[88:91], v[144:147], v[236:239], v[88:91]
	v_mfma_f32_16x16x32_bf16 v[84:87], v[170:173], v[236:239], v[84:87]
	v_mfma_f32_16x16x32_bf16 v[128:131], v[148:151], v[212:215], v[128:131]
	v_mfma_f32_16x16x32_bf16 v[124:127], v[174:177], v[212:215], v[124:127]
	v_mfma_f32_16x16x32_bf16 v[120:123], v[148:151], v[220:223], v[120:123]
	v_mfma_f32_16x16x32_bf16 v[116:119], v[174:177], v[220:223], v[116:119]
	v_mfma_f32_16x16x32_bf16 v[104:107], v[148:151], v[228:231], v[104:107]
	v_mfma_f32_16x16x32_bf16 v[100:103], v[174:177], v[228:231], v[100:103]
	v_mfma_f32_16x16x32_bf16 v[88:91], v[148:151], v[240:243], v[88:91]
	v_mfma_f32_16x16x32_bf16 v[84:87], v[174:177], v[240:243], v[84:87]
	s_setprio 0
	s_setprio 1
	v_mfma_f32_16x16x32_bf16 v[112:115], v[178:181], v[194:197], v[112:115]
	v_mfma_f32_16x16x32_bf16 v[108:111], v[186:189], v[194:197], v[108:111]
	v_mfma_f32_16x16x32_bf16 v[96:99], v[178:181], v[216:219], v[96:99]
	v_mfma_f32_16x16x32_bf16 v[92:95], v[186:189], v[216:219], v[92:95]
	v_mfma_f32_16x16x32_bf16 v[80:83], v[178:181], v[224:227], v[80:83]
	v_mfma_f32_16x16x32_bf16 v[76:79], v[186:189], v[224:227], v[76:79]
	v_mfma_f32_16x16x32_bf16 v[72:75], v[178:181], v[236:239], v[72:75]
	v_mfma_f32_16x16x32_bf16 v[68:71], v[186:189], v[236:239], v[68:71]
	v_mfma_f32_16x16x32_bf16 v[112:115], v[182:185], v[212:215], v[112:115]
	v_mfma_f32_16x16x32_bf16 v[108:111], v[190:193], v[212:215], v[108:111]
	v_mfma_f32_16x16x32_bf16 v[96:99], v[182:185], v[220:223], v[96:99]
	v_mfma_f32_16x16x32_bf16 v[92:95], v[190:193], v[220:223], v[92:95]
	v_mfma_f32_16x16x32_bf16 v[80:83], v[182:185], v[228:231], v[80:83]
	v_mfma_f32_16x16x32_bf16 v[76:79], v[190:193], v[228:231], v[76:79]
	v_mfma_f32_16x16x32_bf16 v[72:75], v[182:185], v[240:243], v[72:75]
	v_mfma_f32_16x16x32_bf16 v[68:71], v[190:193], v[240:243], v[68:71]
	s_setprio 0
	s_barrier
	s_add_i32 s52, s52, s4
	v_lshl_add_u64 v[152:153], s[44:45], 0, v[2:3]
	s_mov_b32 m0, s52
	ds_read_b128 v[194:197], v143 offset:16384
	ds_read_b128 v[212:215], v143 offset:17408
	ds_read_b128 v[216:219], v143 offset:18432
	ds_read_b128 v[220:223], v143 offset:19456
	ds_read_b128 v[224:227], v143 offset:20480
	ds_read_b128 v[228:231], v143 offset:21504
	ds_read_b128 v[236:239], v143 offset:22528
	ds_read_b128 v[240:243], v143 offset:23552
	global_load_lds_dwordx4 v[152:153], off
	s_add_i32 m0, s52, 0x2000
	s_add_u32 s52, s44, 0x100000
	v_lshl_add_u64 v[160:161], s[44:45], 0, v[0:1]
	s_addc_u32 s53, s45, 0
	s_add_i32 s12, s12, s4
	global_load_lds_dwordx4 v[160:161], off
	v_lshl_add_u64 v[198:199], s[52:53], 0, v[2:3]
	s_mov_b32 m0, s12
	v_lshl_add_u64 v[244:245], s[46:47], 0, v[132:133]
	global_load_lds_dwordx4 v[198:199], off
	v_lshl_add_u64 v[198:199], s[52:53], 0, v[0:1]
	s_add_i32 m0, s12, 0x2000
	s_nop 0
	global_load_lds_dwordx4 v[198:199], off
	v_lshl_add_u64 v[198:199], s[46:47], 0, v[134:135]
	s_mov_b32 m0, s5
	s_nop 0
	global_load_lds_dwordx4 v[198:199], off
	s_mov_b32 m0, s6
	s_nop 0
	global_load_lds_dwordx4 v[244:245], off
	s_waitcnt vmcnt(8)
	s_waitcnt lgkmcnt(0)
	s_barrier
; #define PG8_STAGE(bufoff, gbase, voff) do { _Pragma("unroll") for (int _i = 0; _i < 2; ++_i) \
;         __builtin_amdgcn_global_load_lds((const unsigned*)((const char*)(gbase) + (voff)[_i]), (PG8_LAS unsigned*)(lds + (bufoff) + ldsw + _i * 8192), 16, 0, 0); } while (0)
; #define PG8_LDA(dst, b, h) do { _Pragma("unroll") for (int m = 0; m < 4; ++m) _Pragma("unroll") for (int k = 0; k < 2; ++k) dst[m][k] = *(const PG8_LAS bf16x8*)(lds + PG8_SA(b, h) + aoff + m * 2048 + k * 1024); } while (0)
; #define PG8_LDB(dst, b, h) do { _Pragma("unroll") for (int n = 0; n < 2; ++n) _Pragma("unroll") for (int k = 0; k < 2; ++k) dst[n][k] = *(const PG8_LAS bf16x8*)(lds + PG8_SB(b, h) + boff + n * 2048 + k * 1024); } while (0)
; #define PG8_MMA(ai, bj, At, Bt) do { __builtin_amdgcn_s_setprio(1); _Pragma("unroll") for (int m = 0; m < 4; ++m) _Pragma("unroll") for (int n = 0; n < 2; ++n) _Pragma("unroll") for (int k = 0; k < 2; ++k) \
;         acc[ai][bj][m][n] = __builtin_amdgcn_mfma_f32_16x16x32_bf16(Bt[n][k], At[m][k], acc[ai][bj][m][n], 0, 0, 0); __builtin_amdgcn_s_setprio(0); } while (0)
; #define PG8_WAIT_V(n) asm volatile("s_waitcnt vmcnt(" #n ")" ::: "memory")
; #define PG8_WAIT_L(n) asm volatile("s_waitcnt lgkmcnt(" #n ")" ::: "memory")
; #define PG8_BAR __builtin_amdgcn_s_barrier()
; #define PG8_SCHED __builtin_amdgcn_sched_barrier(0)
; template <class Epi, class Sched, bool ALIGN_EPI = false, bool SP2 = false>
; __device__ __forceinline__ void gemm_phase(PG8_LAS unsigned char* lds, const Gemm g, const Sched& S, const Epi& E, const int tid) {
;     ...
;             PG8_WAIT_V(8); PG8_WAIT_L(0); PG8_BAR; PG8_MMA(1, 0, At, B0); PG8_MMA(1, 1, At, B1); PG8_BAR; PG8_SCHED;
;             PG8_LDB(B0, 1, 0); PG8_LDB(B1, 1, 1); PG8_SCHED; PG8_LDA(At, 1, 0); PG8_STAGE(PG8_SA(0, 1), a2 + hstep, voffA);
;             PG8_WAIT_V(8); PG8_WAIT_L(0); PG8_BAR; PG8_MMA(0, 0, At, B0); PG8_MMA(0, 1, At, B1); PG8_BAR; PG8_SCHED;
	s_setprio 1
	s_waitcnt lgkmcnt(0)
	v_mfma_f32_16x16x32_bf16 v[64:67], v[144:147], v[194:197], v[64:67]
	v_mfma_f32_16x16x32_bf16 v[60:63], v[170:173], v[194:197], v[60:63]
	v_mfma_f32_16x16x32_bf16 v[56:59], v[144:147], v[216:219], v[56:59]
	v_mfma_f32_16x16x32_bf16 v[52:55], v[170:173], v[216:219], v[52:55]
	v_mfma_f32_16x16x32_bf16 v[40:43], v[144:147], v[224:227], v[40:43]
	v_mfma_f32_16x16x32_bf16 v[36:39], v[170:173], v[224:227], v[36:39]
	v_mfma_f32_16x16x32_bf16 v[24:27], v[144:147], v[236:239], v[24:27]
	v_mfma_f32_16x16x32_bf16 v[20:23], v[170:173], v[236:239], v[20:23]
	v_mfma_f32_16x16x32_bf16 v[64:67], v[148:151], v[212:215], v[64:67]
	v_mfma_f32_16x16x32_bf16 v[60:63], v[174:177], v[212:215], v[60:63]
	v_mfma_f32_16x16x32_bf16 v[56:59], v[148:151], v[220:223], v[56:59]
	v_mfma_f32_16x16x32_bf16 v[52:55], v[174:177], v[220:223], v[52:55]
	v_mfma_f32_16x16x32_bf16 v[40:43], v[148:151], v[228:231], v[40:43]
	v_mfma_f32_16x16x32_bf16 v[36:39], v[174:177], v[228:231], v[36:39]
	v_mfma_f32_16x16x32_bf16 v[24:27], v[148:151], v[240:243], v[24:27]
	v_mfma_f32_16x16x32_bf16 v[20:23], v[174:177], v[240:243], v[20:23]
	s_setprio 0
	s_setprio 1
	v_mfma_f32_16x16x32_bf16 v[48:51], v[178:181], v[194:197], v[48:51]
	v_mfma_f32_16x16x32_bf16 v[44:47], v[186:189], v[194:197], v[44:47]
	v_mfma_f32_16x16x32_bf16 v[32:35], v[178:181], v[216:219], v[32:35]
	v_mfma_f32_16x16x32_bf16 v[28:31], v[186:189], v[216:219], v[28:31]
	v_mfma_f32_16x16x32_bf16 v[16:19], v[178:181], v[224:227], v[16:19]
	v_mfma_f32_16x16x32_bf16 v[12:15], v[186:189], v[224:227], v[12:15]
	v_mfma_f32_16x16x32_bf16 v[8:11], v[178:181], v[236:239], v[8:11]
	v_mfma_f32_16x16x32_bf16 v[4:7], v[186:189], v[236:239], v[4:7]
	v_mfma_f32_16x16x32_bf16 v[48:51], v[182:185], v[212:215], v[48:51]
	v_mfma_f32_16x16x32_bf16 v[44:47], v[190:193], v[212:215], v[44:47]
	v_mfma_f32_16x16x32_bf16 v[32:35], v[182:185], v[220:223], v[32:35]
	v_mfma_f32_16x16x32_bf16 v[28:31], v[190:193], v[220:223], v[28:31]
	v_mfma_f32_16x16x32_bf16 v[16:19], v[182:185], v[228:231], v[16:19]
	v_mfma_f32_16x16x32_bf16 v[12:15], v[190:193], v[228:231], v[12:15]
	v_mfma_f32_16x16x32_bf16 v[8:11], v[182:185], v[240:243], v[8:11]
	v_mfma_f32_16x16x32_bf16 v[4:7], v[190:193], v[240:243], v[4:7]
	s_setprio 0
	s_barrier
	s_add_i32 s12, 0, 0x18000
	v_add_u32_e32 v169, s12, v141
	s_add_i32 s52, 0, 0x1c000
	ds_read_b128 v[144:147], v169
	ds_read_b128 v[148:151], v169 offset:1024
	ds_read_b128 v[170:173], v169 offset:2048
	ds_read_b128 v[174:177], v169 offset:3072
	v_add_u32_e32 v169, s52, v141
	ds_read_b128 v[178:181], v169
	ds_read_b128 v[182:185], v169 offset:1024
	ds_read_b128 v[186:189], v169 offset:2048
	ds_read_b128 v[190:193], v169 offset:3072
	s_add_u32 s46, s46, 0x100000
	s_addc_u32 s47, s47, 0
	s_mov_b32 m0, s7
	v_lshl_add_u64 v[246:247], s[46:47], 0, v[134:135]
	ds_read_b128 v[194:197], v143 offset:32768
	ds_read_b128 v[212:215], v143 offset:33792
	ds_read_b128 v[216:219], v143 offset:34816
	ds_read_b128 v[220:223], v143 offset:35840
	ds_read_b128 v[224:227], v143 offset:36864
	ds_read_b128 v[228:231], v143 offset:37888
	ds_read_b128 v[236:239], v143 offset:38912
	ds_read_b128 v[240:243], v143 offset:39936
	global_load_lds_dwordx4 v[246:247], off
	v_lshl_add_u64 v[246:247], s[46:47], 0, v[132:133]
	s_mov_b32 m0, s8
	s_nop 0
	global_load_lds_dwordx4 v[246:247], off
	s_waitcnt vmcnt(8)
	s_waitcnt lgkmcnt(0)
	s_barrier
	s_setprio 1
	s_waitcnt lgkmcnt(0)
	v_mfma_f32_16x16x32_bf16 v[128:131], v[144:147], v[194:197], v[128:131]
	v_mfma_f32_16x16x32_bf16 v[124:127], v[170:173], v[194:197], v[124:127]
	v_mfma_f32_16x16x32_bf16 v[120:123], v[144:147], v[216:219], v[120:123]
	v_mfma_f32_16x16x32_bf16 v[116:119], v[170:173], v[216:219], v[116:119]
	v_mfma_f32_16x16x32_bf16 v[104:107], v[144:147], v[224:227], v[104:107]
	v_mfma_f32_16x16x32_bf16 v[100:103], v[170:173], v[224:227], v[100:103]
	v_mfma_f32_16x16x32_bf16 v[88:91], v[144:147], v[236:239], v[88:91]
	v_mfma_f32_16x16x32_bf16 v[84:87], v[170:173], v[236:239], v[84:87]
	v_mfma_f32_16x16x32_bf16 v[128:131], v[148:151], v[212:215], v[128:131]
	v_mfma_f32_16x16x32_bf16 v[124:127], v[174:177], v[212:215], v[124:127]
	v_mfma_f32_16x16x32_bf16 v[120:123], v[148:151], v[220:223], v[120:123]
	v_mfma_f32_16x16x32_bf16 v[116:119], v[174:177], v[220:223], v[116:119]
	v_mfma_f32_16x16x32_bf16 v[104:107], v[148:151], v[228:231], v[104:107]
	v_mfma_f32_16x16x32_bf16 v[100:103], v[174:177], v[228:231], v[100:103]
	v_mfma_f32_16x16x32_bf16 v[88:91], v[148:151], v[240:243], v[88:91]
	v_mfma_f32_16x16x32_bf16 v[84:87], v[174:177], v[240:243], v[84:87]
	s_setprio 0
	s_setprio 1
	v_mfma_f32_16x16x32_bf16 v[112:115], v[178:181], v[194:197], v[112:115]
	v_mfma_f32_16x16x32_bf16 v[108:111], v[186:189], v[194:197], v[108:111]
	v_mfma_f32_16x16x32_bf16 v[96:99], v[178:181], v[216:219], v[96:99]
	v_mfma_f32_16x16x32_bf16 v[92:95], v[186:189], v[216:219], v[92:95]
	v_mfma_f32_16x16x32_bf16 v[80:83], v[178:181], v[224:227], v[80:83]
	v_mfma_f32_16x16x32_bf16 v[76:79], v[186:189], v[224:227], v[76:79]
	v_mfma_f32_16x16x32_bf16 v[72:75], v[178:181], v[236:239], v[72:75]
	v_mfma_f32_16x16x32_bf16 v[68:71], v[186:189], v[236:239], v[68:71]
	v_mfma_f32_16x16x32_bf16 v[112:115], v[182:185], v[212:215], v[112:115]
	v_mfma_f32_16x16x32_bf16 v[108:111], v[190:193], v[212:215], v[108:111]
	v_mfma_f32_16x16x32_bf16 v[96:99], v[182:185], v[220:223], v[96:99]
	v_mfma_f32_16x16x32_bf16 v[92:95], v[190:193], v[220:223], v[92:95]
	v_mfma_f32_16x16x32_bf16 v[80:83], v[182:185], v[228:231], v[80:83]
	v_mfma_f32_16x16x32_bf16 v[76:79], v[190:193], v[228:231], v[76:79]
	v_mfma_f32_16x16x32_bf16 v[72:75], v[182:185], v[240:243], v[72:75]
	v_mfma_f32_16x16x32_bf16 v[68:71], v[190:193], v[240:243], v[68:71]
	s_setprio 0
	s_barrier
; #define PG8_STAGE(bufoff, gbase, voff) do { _Pragma("unroll") for (int _i = 0; _i < 2; ++_i) \
;         __builtin_amdgcn_global_load_lds((const unsigned*)((const char*)(gbase) + (voff)[_i]), (PG8_LAS unsigned*)(lds + (bufoff) + ldsw + _i * 8192), 16, 0, 0); } while (0)
; #define PG8_LDA(dst, b, h) do { _Pragma("unroll") for (int m = 0; m < 4; ++m) _Pragma("unroll") for (int k = 0; k < 2; ++k) dst[m][k] = *(const PG8_LAS bf16x8*)(lds + PG8_SA(b, h) + aoff + m * 2048 + k * 1024); } while (0)
; #define PG8_MMA(ai, bj, At, Bt) do { __builtin_amdgcn_s_setprio(1); _Pragma("unroll") for (int m = 0; m < 4; ++m) _Pragma("unroll") for (int n = 0; n < 2; ++n) _Pragma("unroll") for (int k = 0; k < 2; ++k) \
;         acc[ai][bj][m][n] = __builtin_amdgcn_mfma_f32_16x16x32_bf16(Bt[n][k], At[m][k], acc[ai][bj][m][n], 0, 0, 0); __builtin_amdgcn_s_setprio(0); } while (0)
; #define PG8_WAIT_V(n) asm volatile("s_waitcnt vmcnt(" #n ")" ::: "memory")
; #define PG8_WAIT_L(n) asm volatile("s_waitcnt lgkmcnt(" #n ")" ::: "memory")
; #define PG8_BAR __builtin_amdgcn_s_barrier()
; #define PG8_SCHED __builtin_amdgcn_sched_barrier(0)
; template <class Epi, class Sched, bool ALIGN_EPI = false, bool SP2 = false>
; __device__ __forceinline__ void gemm_phase(PG8_LAS unsigned char* lds, const Gemm g, const Sched& S, const Epi& E, const int tid) {
;     ...
;         for (int t = 0; t < nt; t += 2) {
;             const bool last = (t == nt - 2);
;     ...
;             PG8_LDA(At, 1, 1); PG8_STAGE(PG8_SB(1, 0), b3, voffB); PG8_STAGE(PG8_SB(1, 1), b3 + hstep, voffB); PG8_STAGE(PG8_SA(1, 0), a3, voffA);
;             PG8_WAIT_V(8); PG8_WAIT_L(0); PG8_BAR; PG8_MMA(1, 0, At, B0); PG8_MMA(1, 1, At, B1); PG8_BAR; PG8_SCHED;
	s_add_i32 s12, s12, s4
	v_lshl_add_u64 v[152:153], v[152:153], 0, s[18:19]
	s_mov_b32 m0, s12
	ds_read_b128 v[194:197], v143 offset:49152
	ds_read_b128 v[212:215], v143 offset:50176
	ds_read_b128 v[216:219], v143 offset:51200
	ds_read_b128 v[220:223], v143 offset:52224
	ds_read_b128 v[224:227], v143 offset:53248
	ds_read_b128 v[228:231], v143 offset:54272
	ds_read_b128 v[236:239], v143 offset:55296
	ds_read_b128 v[240:243], v143 offset:56320
	global_load_lds_dwordx4 v[152:153], off
	s_add_i32 m0, s12, 0x2000
	s_add_u32 s44, s44, 0x100080
	v_lshl_add_u64 v[152:153], v[160:161], 0, s[18:19]
	s_addc_u32 s45, s45, 0
	s_add_i32 s12, s52, s4
	global_load_lds_dwordx4 v[152:153], off
	v_lshl_add_u64 v[152:153], s[44:45], 0, v[2:3]
	s_mov_b32 m0, s12
	s_nop 0
	global_load_lds_dwordx4 v[152:153], off
	v_lshl_add_u64 v[152:153], s[44:45], 0, v[0:1]
	s_add_i32 m0, s12, 0x2000
	s_nop 0
	global_load_lds_dwordx4 v[152:153], off
	v_lshl_add_u64 v[152:153], v[198:199], 0, s[18:19]
	s_mov_b32 m0, s9
	s_nop 0
	global_load_lds_dwordx4 v[152:153], off
	v_lshl_add_u64 v[152:153], v[244:245], 0, s[18:19]
	s_mov_b32 m0, s13
	s_nop 0
	global_load_lds_dwordx4 v[152:153], off
	s_waitcnt vmcnt(8)
	s_waitcnt lgkmcnt(0)
	s_barrier
	s_setprio 1
	s_waitcnt lgkmcnt(0)
	v_mfma_f32_16x16x32_bf16 v[64:67], v[144:147], v[194:197], v[64:67]
	v_mfma_f32_16x16x32_bf16 v[60:63], v[170:173], v[194:197], v[60:63]
	v_mfma_f32_16x16x32_bf16 v[56:59], v[144:147], v[216:219], v[56:59]
	v_mfma_f32_16x16x32_bf16 v[52:55], v[170:173], v[216:219], v[52:55]
	v_mfma_f32_16x16x32_bf16 v[40:43], v[144:147], v[224:227], v[40:43]
	v_mfma_f32_16x16x32_bf16 v[36:39], v[170:173], v[224:227], v[36:39]
	v_mfma_f32_16x16x32_bf16 v[24:27], v[144:147], v[236:239], v[24:27]
	v_mfma_f32_16x16x32_bf16 v[20:23], v[170:173], v[236:239], v[20:23]
	v_mfma_f32_16x16x32_bf16 v[64:67], v[148:151], v[212:215], v[64:67]
	v_mfma_f32_16x16x32_bf16 v[60:63], v[174:177], v[212:215], v[60:63]
	v_mfma_f32_16x16x32_bf16 v[56:59], v[148:151], v[220:223], v[56:59]
	v_mfma_f32_16x16x32_bf16 v[52:55], v[174:177], v[220:223], v[52:55]
	v_mfma_f32_16x16x32_bf16 v[40:43], v[148:151], v[228:231], v[40:43]
	v_mfma_f32_16x16x32_bf16 v[36:39], v[174:177], v[228:231], v[36:39]
	v_mfma_f32_16x16x32_bf16 v[24:27], v[148:151], v[240:243], v[24:27]
	v_mfma_f32_16x16x32_bf16 v[20:23], v[174:177], v[240:243], v[20:23]
	s_setprio 0
	s_setprio 1
	v_mfma_f32_16x16x32_bf16 v[48:51], v[178:181], v[194:197], v[48:51]
	v_mfma_f32_16x16x32_bf16 v[44:47], v[186:189], v[194:197], v[44:47]
	s_add_i32 s51, s51, 2
	v_mfma_f32_16x16x32_bf16 v[32:35], v[178:181], v[216:219], v[32:35]
	s_add_u32 s42, s42, 0x100
	v_mfma_f32_16x16x32_bf16 v[28:31], v[186:189], v[216:219], v[28:31]
	s_addc_u32 s43, s43, 0
	v_mfma_f32_16x16x32_bf16 v[16:19], v[178:181], v[224:227], v[16:19]
	s_add_u32 s49, s49, 0x100
	v_mfma_f32_16x16x32_bf16 v[12:15], v[186:189], v[224:227], v[12:15]
	s_addc_u32 s50, s50, 0
	v_mfma_f32_16x16x32_bf16 v[8:11], v[178:181], v[236:239], v[8:11]
	s_cmp_gt_u32 s51, 61
	v_mfma_f32_16x16x32_bf16 v[4:7], v[186:189], v[236:239], v[4:7]
	v_mfma_f32_16x16x32_bf16 v[48:51], v[182:185], v[212:215], v[48:51]
	v_mfma_f32_16x16x32_bf16 v[44:47], v[190:193], v[212:215], v[44:47]
	v_mfma_f32_16x16x32_bf16 v[32:35], v[182:185], v[220:223], v[32:35]
	v_mfma_f32_16x16x32_bf16 v[28:31], v[190:193], v[220:223], v[28:31]
	v_mfma_f32_16x16x32_bf16 v[16:19], v[182:185], v[228:231], v[16:19]
	v_mfma_f32_16x16x32_bf16 v[12:15], v[190:193], v[228:231], v[12:15]
	v_mfma_f32_16x16x32_bf16 v[8:11], v[182:185], v[240:243], v[8:11]
	v_mfma_f32_16x16x32_bf16 v[4:7], v[190:193], v[240:243], v[4:7]
	s_setprio 0
	s_barrier
	s_cbranch_scc0 .LBB0_1477
	s_and_b64 vcc, exec, s[20:21]
	s_cbranch_vccz .LBB0_1480
	s_barrier

; #define PG8_STAGE(bufoff, gbase, voff) do { _Pragma("unroll") for (int _i = 0; _i < 2; ++_i) \
;         __builtin_amdgcn_global_load_lds((const unsigned*)((const char*)(gbase) + (voff)[_i]), (PG8_LAS unsigned*)(lds + (bufoff) + ldsw + _i * 8192), 16, 0, 0); } while (0)
; #define PG8_LDA(dst, b, h) do { _Pragma("unroll") for (int m = 0; m < 4; ++m) _Pragma("unroll") for (int k = 0; k < 2; ++k) dst[m][k] = *(const PG8_LAS bf16x8*)(lds + PG8_SA(b, h) + aoff + m * 2048 + k * 1024); } while (0)
; #define PG8_LDB(dst, b, h) do { _Pragma("unroll") for (int n = 0; n < 2; ++n) _Pragma("unroll") for (int k = 0; k < 2; ++k) dst[n][k] = *(const PG8_LAS bf16x8*)(lds + PG8_SB(b, h) + boff + n * 2048 + k * 1024); } while (0)
; #define PG8_MMA(ai, bj, At, Bt) do { __builtin_amdgcn_s_setprio(1); _Pragma("unroll") for (int m = 0; m < 4; ++m) _Pragma("unroll") for (int n = 0; n < 2; ++n) _Pragma("unroll") for (int k = 0; k < 2; ++k) \
;         acc[ai][bj][m][n] = __builtin_amdgcn_mfma_f32_16x16x32_bf16(Bt[n][k], At[m][k], acc[ai][bj][m][n], 0, 0, 0); __builtin_amdgcn_s_setprio(0); } while (0)
; #define PG8_WAIT_V(n) asm volatile("s_waitcnt vmcnt(" #n ")" ::: "memory")
; #define PG8_WAIT_L(n) asm volatile("s_waitcnt lgkmcnt(" #n ")" ::: "memory")
; #define PG8_BAR __builtin_amdgcn_s_barrier()
; template <class Epi, class Sched, bool ALIGN_EPI = false, bool SP2 = false>
; __device__ __forceinline__ void gemm_phase(PG8_LAS unsigned char* lds, const Gemm g, const Sched& S, const Epi& E, const int tid) {
;     ...
;         for (int t = 0; t < nt; t += 2) {
;             const bool last = (t == nt - 2);
;             const char* a1 = cA + (size_t)(t + 1) * kstep;
;             const char* a2 = last ? nA : cA + (size_t)(t + 2) * kstep; const char* b2 = last ? nB : cB + (size_t)(t + 2) * kstep;
;             const char* a3 = a2 + kstep; const char* b3 = b2 + kstep;
;             if (last && has_next) S.a_ready(nxt);
;             if constexpr (SP2) {
;             PG8_LDB(B0, 0, 0); PG8_LDB(B1, 0, 1); PG8_SCHED; PG8_LDA(At, 0, 0); PG8_STAGE(PG8_SA(1, 1), a1 + hstep, voffA);
;             PG8_WAIT_V(8); PG8_WAIT_L(0); PG8_BAR; PG8_MMA(0, 0, At, B0); PG8_MMA(0, 1, At, B1); PG8_BAR; PG8_SCHED;
;             PG8_LDA(At, 0, 1); PG8_STAGE(PG8_SB(0, 0), b2, voffB); PG8_STAGE(PG8_SB(0, 1), b2 + hstep, voffB); PG8_STAGE(PG8_SA(0, 0), a2, voffA);
.LBB0_1496:
	s_add_i32 s52, 0, 0x10000
	v_add_u32_e32 v152, s52, v141
	ds_read_b128 v[144:147], v152
	ds_read_b128 v[148:151], v152 offset:1024
	ds_read_b128 v[170:173], v152 offset:2048
	ds_read_b128 v[174:177], v152 offset:3072
	s_add_u32 s12, s42, 0xfffc0080
	s_addc_u32 s44, s43, -1
	s_cmp_eq_u32 s51, 12
	s_cselect_b32 s47, s29, s44
	s_cselect_b32 s46, s30, s12
	s_cselect_b32 s45, s25, s50
	s_cselect_b32 s44, s48, s49
	s_add_i32 s12, 0, 0x14000
	v_add_u32_e32 v152, s12, v141
	ds_read_b128 v[178:181], v152
	ds_read_b128 v[182:185], v152 offset:1024
	ds_read_b128 v[186:189], v152 offset:2048
	ds_read_b128 v[190:193], v152 offset:3072
	v_lshl_add_u64 v[152:153], s[42:43], 0, v[136:137]
	s_add_i32 m0, s5, 0xc000
	ds_read_b128 v[194:197], v143
	ds_read_b128 v[212:215], v143 offset:1024
	ds_read_b128 v[216:219], v143 offset:2048
	ds_read_b128 v[220:223], v143 offset:3072
	ds_read_b128 v[224:227], v143 offset:4096
	ds_read_b128 v[228:231], v143 offset:5120
	ds_read_b128 v[236:239], v143 offset:6144
	ds_read_b128 v[240:243], v143 offset:7168
	global_load_lds_dwordx4 v[152:153], off
	v_lshl_add_u64 v[152:153], s[42:43], 0, v[138:139]
	s_add_i32 m0, s5, 0xe000
	s_nop 0
	global_load_lds_dwordx4 v[152:153], off
	s_waitcnt vmcnt(8)
	s_waitcnt lgkmcnt(0)
	s_barrier
	s_setprio 1
	s_waitcnt lgkmcnt(0)
	v_mfma_f32_16x16x32_bf16 v[128:131], v[144:147], v[194:197], v[128:131]
	v_mfma_f32_16x16x32_bf16 v[124:127], v[170:173], v[194:197], v[124:127]
	v_mfma_f32_16x16x32_bf16 v[112:115], v[144:147], v[216:219], v[112:115]
	v_mfma_f32_16x16x32_bf16 v[108:111], v[170:173], v[216:219], v[108:111]
	v_mfma_f32_16x16x32_bf16 v[96:99], v[144:147], v[224:227], v[96:99]
	v_mfma_f32_16x16x32_bf16 v[92:95], v[170:173], v[224:227], v[92:95]
	v_mfma_f32_16x16x32_bf16 v[80:83], v[144:147], v[236:239], v[80:83]
	v_mfma_f32_16x16x32_bf16 v[76:79], v[170:173], v[236:239], v[76:79]
	v_mfma_f32_16x16x32_bf16 v[128:131], v[148:151], v[212:215], v[128:131]
	v_mfma_f32_16x16x32_bf16 v[124:127], v[174:177], v[212:215], v[124:127]
	v_mfma_f32_16x16x32_bf16 v[112:115], v[148:151], v[220:223], v[112:115]
	v_mfma_f32_16x16x32_bf16 v[108:111], v[174:177], v[220:223], v[108:111]
	v_mfma_f32_16x16x32_bf16 v[96:99], v[148:151], v[228:231], v[96:99]
	v_mfma_f32_16x16x32_bf16 v[92:95], v[174:177], v[228:231], v[92:95]
	v_mfma_f32_16x16x32_bf16 v[80:83], v[148:151], v[240:243], v[80:83]
	v_mfma_f32_16x16x32_bf16 v[76:79], v[174:177], v[240:243], v[76:79]
	s_setprio 0
	s_setprio 1
	v_mfma_f32_16x16x32_bf16 v[120:123], v[178:181], v[194:197], v[120:123]
	v_mfma_f32_16x16x32_bf16 v[116:119], v[186:189], v[194:197], v[116:119]
	v_mfma_f32_16x16x32_bf16 v[104:107], v[178:181], v[216:219], v[104:107]
	v_mfma_f32_16x16x32_bf16 v[100:103], v[186:189], v[216:219], v[100:103]
	v_mfma_f32_16x16x32_bf16 v[88:91], v[178:181], v[224:227], v[88:91]
	v_mfma_f32_16x16x32_bf16 v[84:87], v[186:189], v[224:227], v[84:87]
	v_mfma_f32_16x16x32_bf16 v[72:75], v[178:181], v[236:239], v[72:75]
	v_mfma_f32_16x16x32_bf16 v[68:71], v[186:189], v[236:239], v[68:71]
	v_mfma_f32_16x16x32_bf16 v[120:123], v[182:185], v[212:215], v[120:123]
	v_mfma_f32_16x16x32_bf16 v[116:119], v[190:193], v[212:215], v[116:119]
	v_mfma_f32_16x16x32_bf16 v[104:107], v[182:185], v[220:223], v[104:107]
	v_mfma_f32_16x16x32_bf16 v[100:103], v[190:193], v[220:223], v[100:103]
	v_mfma_f32_16x16x32_bf16 v[88:91], v[182:185], v[228:231], v[88:91]
	v_mfma_f32_16x16x32_bf16 v[84:87], v[190:193], v[228:231], v[84:87]
	v_mfma_f32_16x16x32_bf16 v[72:75], v[182:185], v[240:243], v[72:75]
	v_mfma_f32_16x16x32_bf16 v[68:71], v[190:193], v[240:243], v[68:71]
	s_setprio 0
	s_barrier
	s_add_i32 s52, s52, s4
	v_lshl_add_u64 v[152:153], s[44:45], 0, v[2:3]
	s_mov_b32 m0, s52
	ds_read_b128 v[194:197], v143 offset:16384
	ds_read_b128 v[212:215], v143 offset:17408
	ds_read_b128 v[216:219], v143 offset:18432
	ds_read_b128 v[220:223], v143 offset:19456
	ds_read_b128 v[224:227], v143 offset:20480
	ds_read_b128 v[228:231], v143 offset:21504
	ds_read_b128 v[236:239], v143 offset:22528
	ds_read_b128 v[240:243], v143 offset:23552
	global_load_lds_dwordx4 v[152:153], off
	s_add_i32 m0, s52, 0x2000
	s_add_u32 s52, s44, 0x40000
	v_lshl_add_u64 v[160:161], s[44:45], 0, v[0:1]
	s_addc_u32 s53, s45, 0
	s_add_i32 s12, s12, s4
	global_load_lds_dwordx4 v[160:161], off
	v_lshl_add_u64 v[198:199], s[52:53], 0, v[2:3]
	s_mov_b32 m0, s12
	v_lshl_add_u64 v[244:245], s[46:47], 0, v[132:133]
	global_load_lds_dwordx4 v[198:199], off
	v_lshl_add_u64 v[198:199], s[52:53], 0, v[0:1]
	s_add_i32 m0, s12, 0x2000
	s_nop 0
	global_load_lds_dwordx4 v[198:199], off
	v_lshl_add_u64 v[198:199], s[46:47], 0, v[134:135]
	s_mov_b32 m0, s5
	s_nop 0
	global_load_lds_dwordx4 v[198:199], off
	s_mov_b32 m0, s6
	s_nop 0
	global_load_lds_dwordx4 v[244:245], off
	s_waitcnt vmcnt(8)
	s_waitcnt lgkmcnt(0)
	s_barrier
; #define PG8_STAGE(bufoff, gbase, voff) do { _Pragma("unroll") for (int _i = 0; _i < 2; ++_i) \
;         __builtin_amdgcn_global_load_lds((const unsigned*)((const char*)(gbase) + (voff)[_i]), (PG8_LAS unsigned*)(lds + (bufoff) + ldsw + _i * 8192), 16, 0, 0); } while (0)
; #define PG8_LDA(dst, b, h) do { _Pragma("unroll") for (int m = 0; m < 4; ++m) _Pragma("unroll") for (int k = 0; k < 2; ++k) dst[m][k] = *(const PG8_LAS bf16x8*)(lds + PG8_SA(b, h) + aoff + m * 2048 + k * 1024); } while (0)
; #define PG8_LDB(dst, b, h) do { _Pragma("unroll") for (int n = 0; n < 2; ++n) _Pragma("unroll") for (int k = 0; k < 2; ++k) dst[n][k] = *(const PG8_LAS bf16x8*)(lds + PG8_SB(b, h) + boff + n * 2048 + k * 1024); } while (0)
; #define PG8_MMA(ai, bj, At, Bt) do { __builtin_amdgcn_s_setprio(1); _Pragma("unroll") for (int m = 0; m < 4; ++m) _Pragma("unroll") for (int n = 0; n < 2; ++n) _Pragma("unroll") for (int k = 0; k < 2; ++k) \
;         acc[ai][bj][m][n] = __builtin_amdgcn_mfma_f32_16x16x32_bf16(Bt[n][k], At[m][k], acc[ai][bj][m][n], 0, 0, 0); __builtin_amdgcn_s_setprio(0); } while (0)
; #define PG8_WAIT_V(n) asm volatile("s_waitcnt vmcnt(" #n ")" ::: "memory")
; #define PG8_WAIT_L(n) asm volatile("s_waitcnt lgkmcnt(" #n ")" ::: "memory")
; #define PG8_BAR __builtin_amdgcn_s_barrier()
; #define PG8_SCHED __builtin_amdgcn_sched_barrier(0)
; template <class Epi, class Sched, bool ALIGN_EPI = false, bool SP2 = false>
; __device__ __forceinline__ void gemm_phase(PG8_LAS unsigned char* lds, const Gemm g, const Sched& S, const Epi& E, const int tid) {
;     ...
;             PG8_WAIT_V(8); PG8_WAIT_L(0); PG8_BAR; PG8_MMA(1, 0, At, B0); PG8_MMA(1, 1, At, B1); PG8_BAR; PG8_SCHED;
;             PG8_LDB(B0, 1, 0); PG8_LDB(B1, 1, 1); PG8_SCHED; PG8_LDA(At, 1, 0); PG8_STAGE(PG8_SA(0, 1), a2 + hstep, voffA);
;             PG8_WAIT_V(8); PG8_WAIT_L(0); PG8_BAR; PG8_MMA(0, 0, At, B0); PG8_MMA(0, 1, At, B1); PG8_BAR; PG8_SCHED;
	s_setprio 1
	s_waitcnt lgkmcnt(0)
	v_mfma_f32_16x16x32_bf16 v[64:67], v[144:147], v[194:197], v[64:67]
	v_mfma_f32_16x16x32_bf16 v[60:63], v[170:173], v[194:197], v[60:63]
	v_mfma_f32_16x16x32_bf16 v[48:51], v[144:147], v[216:219], v[48:51]
	v_mfma_f32_16x16x32_bf16 v[44:47], v[170:173], v[216:219], v[44:47]
	v_mfma_f32_16x16x32_bf16 v[32:35], v[144:147], v[224:227], v[32:35]
	v_mfma_f32_16x16x32_bf16 v[28:31], v[170:173], v[224:227], v[28:31]
	v_mfma_f32_16x16x32_bf16 v[16:19], v[144:147], v[236:239], v[16:19]
	v_mfma_f32_16x16x32_bf16 v[12:15], v[170:173], v[236:239], v[12:15]
	v_mfma_f32_16x16x32_bf16 v[64:67], v[148:151], v[212:215], v[64:67]
	v_mfma_f32_16x16x32_bf16 v[60:63], v[174:177], v[212:215], v[60:63]
	v_mfma_f32_16x16x32_bf16 v[48:51], v[148:151], v[220:223], v[48:51]
	v_mfma_f32_16x16x32_bf16 v[44:47], v[174:177], v[220:223], v[44:47]
	v_mfma_f32_16x16x32_bf16 v[32:35], v[148:151], v[228:231], v[32:35]
	v_mfma_f32_16x16x32_bf16 v[28:31], v[174:177], v[228:231], v[28:31]
	v_mfma_f32_16x16x32_bf16 v[16:19], v[148:151], v[240:243], v[16:19]
	v_mfma_f32_16x16x32_bf16 v[12:15], v[174:177], v[240:243], v[12:15]
	s_setprio 0
	s_setprio 1
	v_mfma_f32_16x16x32_bf16 v[56:59], v[178:181], v[194:197], v[56:59]
	v_mfma_f32_16x16x32_bf16 v[52:55], v[186:189], v[194:197], v[52:55]
	v_mfma_f32_16x16x32_bf16 v[40:43], v[178:181], v[216:219], v[40:43]
	v_mfma_f32_16x16x32_bf16 v[36:39], v[186:189], v[216:219], v[36:39]
	v_mfma_f32_16x16x32_bf16 v[24:27], v[178:181], v[224:227], v[24:27]
	v_mfma_f32_16x16x32_bf16 v[20:23], v[186:189], v[224:227], v[20:23]
	v_mfma_f32_16x16x32_bf16 v[8:11], v[178:181], v[236:239], v[8:11]
	v_mfma_f32_16x16x32_bf16 v[4:7], v[186:189], v[236:239], v[4:7]
	v_mfma_f32_16x16x32_bf16 v[56:59], v[182:185], v[212:215], v[56:59]
	v_mfma_f32_16x16x32_bf16 v[52:55], v[190:193], v[212:215], v[52:55]
	v_mfma_f32_16x16x32_bf16 v[40:43], v[182:185], v[220:223], v[40:43]
	v_mfma_f32_16x16x32_bf16 v[36:39], v[190:193], v[220:223], v[36:39]
	v_mfma_f32_16x16x32_bf16 v[24:27], v[182:185], v[228:231], v[24:27]
	v_mfma_f32_16x16x32_bf16 v[20:23], v[190:193], v[228:231], v[20:23]
	v_mfma_f32_16x16x32_bf16 v[8:11], v[182:185], v[240:243], v[8:11]
	v_mfma_f32_16x16x32_bf16 v[4:7], v[190:193], v[240:243], v[4:7]
	s_setprio 0
	s_barrier
	s_add_i32 s12, 0, 0x18000
	v_add_u32_e32 v169, s12, v141
	s_add_i32 s52, 0, 0x1c000
	ds_read_b128 v[144:147], v169
	ds_read_b128 v[148:151], v169 offset:1024
	ds_read_b128 v[170:173], v169 offset:2048
	ds_read_b128 v[174:177], v169 offset:3072
	v_add_u32_e32 v169, s52, v141
	ds_read_b128 v[178:181], v169
	ds_read_b128 v[182:185], v169 offset:1024
	ds_read_b128 v[186:189], v169 offset:2048
	ds_read_b128 v[190:193], v169 offset:3072
	s_add_u32 s46, s46, 0x40000
	s_addc_u32 s47, s47, 0
	s_mov_b32 m0, s7
	v_lshl_add_u64 v[246:247], s[46:47], 0, v[134:135]
	ds_read_b128 v[194:197], v143 offset:32768
	ds_read_b128 v[212:215], v143 offset:33792
	ds_read_b128 v[216:219], v143 offset:34816
	ds_read_b128 v[220:223], v143 offset:35840
	ds_read_b128 v[224:227], v143 offset:36864
	ds_read_b128 v[228:231], v143 offset:37888
	ds_read_b128 v[236:239], v143 offset:38912
	ds_read_b128 v[240:243], v143 offset:39936
	global_load_lds_dwordx4 v[246:247], off
	v_lshl_add_u64 v[246:247], s[46:47], 0, v[132:133]
	s_mov_b32 m0, s8
	s_nop 0
	global_load_lds_dwordx4 v[246:247], off
	s_waitcnt vmcnt(8)
	s_waitcnt lgkmcnt(0)
	s_barrier
	s_setprio 1
	s_waitcnt lgkmcnt(0)
	v_mfma_f32_16x16x32_bf16 v[128:131], v[144:147], v[194:197], v[128:131]
	v_mfma_f32_16x16x32_bf16 v[124:127], v[170:173], v[194:197], v[124:127]
	v_mfma_f32_16x16x32_bf16 v[112:115], v[144:147], v[216:219], v[112:115]
	v_mfma_f32_16x16x32_bf16 v[108:111], v[170:173], v[216:219], v[108:111]
	v_mfma_f32_16x16x32_bf16 v[96:99], v[144:147], v[224:227], v[96:99]
	v_mfma_f32_16x16x32_bf16 v[92:95], v[170:173], v[224:227], v[92:95]
	v_mfma_f32_16x16x32_bf16 v[80:83], v[144:147], v[236:239], v[80:83]
	v_mfma_f32_16x16x32_bf16 v[76:79], v[170:173], v[236:239], v[76:79]
	v_mfma_f32_16x16x32_bf16 v[128:131], v[148:151], v[212:215], v[128:131]
	v_mfma_f32_16x16x32_bf16 v[124:127], v[174:177], v[212:215], v[124:127]
	v_mfma_f32_16x16x32_bf16 v[112:115], v[148:151], v[220:223], v[112:115]
	v_mfma_f32_16x16x32_bf16 v[108:111], v[174:177], v[220:223], v[108:111]
	v_mfma_f32_16x16x32_bf16 v[96:99], v[148:151], v[228:231], v[96:99]
	v_mfma_f32_16x16x32_bf16 v[92:95], v[174:177], v[228:231], v[92:95]
	v_mfma_f32_16x16x32_bf16 v[80:83], v[148:151], v[240:243], v[80:83]
	v_mfma_f32_16x16x32_bf16 v[76:79], v[174:177], v[240:243], v[76:79]
	s_setprio 0
	s_setprio 1
	v_mfma_f32_16x16x32_bf16 v[120:123], v[178:181], v[194:197], v[120:123]
	v_mfma_f32_16x16x32_bf16 v[116:119], v[186:189], v[194:197], v[116:119]
	v_mfma_f32_16x16x32_bf16 v[104:107], v[178:181], v[216:219], v[104:107]
	v_mfma_f32_16x16x32_bf16 v[100:103], v[186:189], v[216:219], v[100:103]
	v_mfma_f32_16x16x32_bf16 v[88:91], v[178:181], v[224:227], v[88:91]
	v_mfma_f32_16x16x32_bf16 v[84:87], v[186:189], v[224:227], v[84:87]
	v_mfma_f32_16x16x32_bf16 v[72:75], v[178:181], v[236:239], v[72:75]
	v_mfma_f32_16x16x32_bf16 v[68:71], v[186:189], v[236:239], v[68:71]
	v_mfma_f32_16x16x32_bf16 v[120:123], v[182:185], v[212:215], v[120:123]
	v_mfma_f32_16x16x32_bf16 v[116:119], v[190:193], v[212:215], v[116:119]
	v_mfma_f32_16x16x32_bf16 v[104:107], v[182:185], v[220:223], v[104:107]
	v_mfma_f32_16x16x32_bf16 v[100:103], v[190:193], v[220:223], v[100:103]
	v_mfma_f32_16x16x32_bf16 v[88:91], v[182:185], v[228:231], v[88:91]
	v_mfma_f32_16x16x32_bf16 v[84:87], v[190:193], v[228:231], v[84:87]
	v_mfma_f32_16x16x32_bf16 v[72:75], v[182:185], v[240:243], v[72:75]
	v_mfma_f32_16x16x32_bf16 v[68:71], v[190:193], v[240:243], v[68:71]
	s_setprio 0
	s_barrier
; #define PG8_STAGE(bufoff, gbase, voff) do { _Pragma("unroll") for (int _i = 0; _i < 2; ++_i) \
;         __builtin_amdgcn_global_load_lds((const unsigned*)((const char*)(gbase) + (voff)[_i]), (PG8_LAS unsigned*)(lds + (bufoff) + ldsw + _i * 8192), 16, 0, 0); } while (0)
; #define PG8_LDA(dst, b, h) do { _Pragma("unroll") for (int m = 0; m < 4; ++m) _Pragma("unroll") for (int k = 0; k < 2; ++k) dst[m][k] = *(const PG8_LAS bf16x8*)(lds + PG8_SA(b, h) + aoff + m * 2048 + k * 1024); } while (0)
; #define PG8_MMA(ai, bj, At, Bt) do { __builtin_amdgcn_s_setprio(1); _Pragma("unroll") for (int m = 0; m < 4; ++m) _Pragma("unroll") for (int n = 0; n < 2; ++n) _Pragma("unroll") for (int k = 0; k < 2; ++k) \
;         acc[ai][bj][m][n] = __builtin_amdgcn_mfma_f32_16x16x32_bf16(Bt[n][k], At[m][k], acc[ai][bj][m][n], 0, 0, 0); __builtin_amdgcn_s_setprio(0); } while (0)
; #define PG8_WAIT_V(n) asm volatile("s_waitcnt vmcnt(" #n ")" ::: "memory")
; #define PG8_WAIT_L(n) asm volatile("s_waitcnt lgkmcnt(" #n ")" ::: "memory")
; #define PG8_BAR __builtin_amdgcn_s_barrier()
; #define PG8_SCHED __builtin_amdgcn_sched_barrier(0)
; template <class Epi, class Sched, bool ALIGN_EPI = false, bool SP2 = false>
; __device__ __forceinline__ void gemm_phase(PG8_LAS unsigned char* lds, const Gemm g, const Sched& S, const Epi& E, const int tid) {
;     ...
;         for (int t = 0; t < nt; t += 2) {
;     ...
;             PG8_LDA(At, 1, 1); PG8_STAGE(PG8_SB(1, 0), b3, voffB); PG8_STAGE(PG8_SB(1, 1), b3 + hstep, voffB); PG8_STAGE(PG8_SA(1, 0), a3, voffA);
;             PG8_WAIT_V(8); PG8_WAIT_L(0); PG8_BAR; PG8_MMA(1, 0, At, B0); PG8_MMA(1, 1, At, B1); PG8_BAR; PG8_SCHED;
	s_add_i32 s12, s12, s4
	v_lshl_add_u64 v[152:153], v[152:153], 0, s[18:19]
	s_mov_b32 m0, s12
	ds_read_b128 v[194:197], v143 offset:49152
	ds_read_b128 v[212:215], v143 offset:50176
	ds_read_b128 v[216:219], v143 offset:51200
	ds_read_b128 v[220:223], v143 offset:52224
	ds_read_b128 v[224:227], v143 offset:53248
	ds_read_b128 v[228:231], v143 offset:54272
	ds_read_b128 v[236:239], v143 offset:55296
	ds_read_b128 v[240:243], v143 offset:56320
	global_load_lds_dwordx4 v[152:153], off
	s_add_i32 m0, s12, 0x2000
	s_add_u32 s44, s44, 0x40080
	v_lshl_add_u64 v[152:153], v[160:161], 0, s[18:19]
	s_addc_u32 s45, s45, 0
	s_add_i32 s12, s52, s4
	global_load_lds_dwordx4 v[152:153], off
	v_lshl_add_u64 v[152:153], s[44:45], 0, v[2:3]
	s_mov_b32 m0, s12
	s_nop 0
	global_load_lds_dwordx4 v[152:153], off
	v_lshl_add_u64 v[152:153], s[44:45], 0, v[0:1]
	s_add_i32 m0, s12, 0x2000
	s_nop 0
	global_load_lds_dwordx4 v[152:153], off
	v_lshl_add_u64 v[152:153], v[198:199], 0, s[18:19]
	s_mov_b32 m0, s9
	s_nop 0
	global_load_lds_dwordx4 v[152:153], off
	v_lshl_add_u64 v[152:153], v[244:245], 0, s[18:19]
	s_mov_b32 m0, s13
	s_nop 0
	global_load_lds_dwordx4 v[152:153], off
	s_waitcnt vmcnt(8)
	s_waitcnt lgkmcnt(0)
	s_barrier
	s_setprio 1
	s_waitcnt lgkmcnt(0)
	v_mfma_f32_16x16x32_bf16 v[64:67], v[144:147], v[194:197], v[64:67]
	v_mfma_f32_16x16x32_bf16 v[60:63], v[170:173], v[194:197], v[60:63]
	v_mfma_f32_16x16x32_bf16 v[48:51], v[144:147], v[216:219], v[48:51]
	v_mfma_f32_16x16x32_bf16 v[44:47], v[170:173], v[216:219], v[44:47]
	v_mfma_f32_16x16x32_bf16 v[32:35], v[144:147], v[224:227], v[32:35]
	v_mfma_f32_16x16x32_bf16 v[28:31], v[170:173], v[224:227], v[28:31]
	v_mfma_f32_16x16x32_bf16 v[16:19], v[144:147], v[236:239], v[16:19]
	v_mfma_f32_16x16x32_bf16 v[12:15], v[170:173], v[236:239], v[12:15]
	v_mfma_f32_16x16x32_bf16 v[64:67], v[148:151], v[212:215], v[64:67]
	v_mfma_f32_16x16x32_bf16 v[60:63], v[174:177], v[212:215], v[60:63]
	v_mfma_f32_16x16x32_bf16 v[48:51], v[148:151], v[220:223], v[48:51]
	v_mfma_f32_16x16x32_bf16 v[44:47], v[174:177], v[220:223], v[44:47]
	v_mfma_f32_16x16x32_bf16 v[32:35], v[148:151], v[228:231], v[32:35]
	v_mfma_f32_16x16x32_bf16 v[28:31], v[174:177], v[228:231], v[28:31]
	v_mfma_f32_16x16x32_bf16 v[16:19], v[148:151], v[240:243], v[16:19]
	v_mfma_f32_16x16x32_bf16 v[12:15], v[174:177], v[240:243], v[12:15]
	s_setprio 0
	s_setprio 1
	v_mfma_f32_16x16x32_bf16 v[56:59], v[178:181], v[194:197], v[56:59]
	v_mfma_f32_16x16x32_bf16 v[52:55], v[186:189], v[194:197], v[52:55]
	s_add_i32 s51, s51, 2
	v_mfma_f32_16x16x32_bf16 v[40:43], v[178:181], v[216:219], v[40:43]
	s_add_u32 s42, s42, 0x100
	v_mfma_f32_16x16x32_bf16 v[36:39], v[186:189], v[216:219], v[36:39]
	s_addc_u32 s43, s43, 0
	v_mfma_f32_16x16x32_bf16 v[24:27], v[178:181], v[224:227], v[24:27]
	s_add_u32 s49, s49, 0x100
	v_mfma_f32_16x16x32_bf16 v[20:23], v[186:189], v[224:227], v[20:23]
	s_addc_u32 s50, s50, 0
	v_mfma_f32_16x16x32_bf16 v[8:11], v[178:181], v[236:239], v[8:11]
	s_cmp_gt_u32 s51, 13
	v_mfma_f32_16x16x32_bf16 v[4:7], v[186:189], v[236:239], v[4:7]
	v_mfma_f32_16x16x32_bf16 v[56:59], v[182:185], v[212:215], v[56:59]
	v_mfma_f32_16x16x32_bf16 v[52:55], v[190:193], v[212:215], v[52:55]
	v_mfma_f32_16x16x32_bf16 v[40:43], v[182:185], v[220:223], v[40:43]
	v_mfma_f32_16x16x32_bf16 v[36:39], v[190:193], v[220:223], v[36:39]
	v_mfma_f32_16x16x32_bf16 v[24:27], v[182:185], v[228:231], v[24:27]
	v_mfma_f32_16x16x32_bf16 v[20:23], v[190:193], v[228:231], v[20:23]
	v_mfma_f32_16x16x32_bf16 v[8:11], v[182:185], v[240:243], v[8:11]
	v_mfma_f32_16x16x32_bf16 v[4:7], v[190:193], v[240:243], v[4:7]
	s_setprio 0
	s_barrier
	s_cbranch_scc0 .LBB0_1496
	s_and_b64 vcc, exec, s[20:21]
	s_cbranch_vccz .LBB0_1499
	s_barrier

; #define PG8_STAGE(bufoff, gbase, voff) do { _Pragma("unroll") for (int _i = 0; _i < 2; ++_i) \
;         __builtin_amdgcn_global_load_lds((const unsigned*)((const char*)(gbase) + (voff)[_i]), (PG8_LAS unsigned*)(lds + (bufoff) + ldsw + _i * 8192), 16, 0, 0); } while (0)
; #define PG8_LDA(dst, b, h) do { _Pragma("unroll") for (int m = 0; m < 4; ++m) _Pragma("unroll") for (int k = 0; k < 2; ++k) dst[m][k] = *(const PG8_LAS bf16x8*)(lds + PG8_SA(b, h) + aoff + m * 2048 + k * 1024); } while (0)
; #define PG8_LDB(dst, b, h) do { _Pragma("unroll") for (int n = 0; n < 2; ++n) _Pragma("unroll") for (int k = 0; k < 2; ++k) dst[n][k] = *(const PG8_LAS bf16x8*)(lds + PG8_SB(b, h) + boff + n * 2048 + k * 1024); } while (0)
; #define PG8_MMA(ai, bj, At, Bt) do { __builtin_amdgcn_s_setprio(1); _Pragma("unroll") for (int m = 0; m < 4; ++m) _Pragma("unroll") for (int n = 0; n < 2; ++n) _Pragma("unroll") for (int k = 0; k < 2; ++k) \
;         acc[ai][bj][m][n] = __builtin_amdgcn_mfma_f32_16x16x32_bf16(Bt[n][k], At[m][k], acc[ai][bj][m][n], 0, 0, 0); __builtin_amdgcn_s_setprio(0); } while (0)
; #define PG8_WAIT_V(n) asm volatile("s_waitcnt vmcnt(" #n ")" ::: "memory")
; #define PG8_WAIT_L(n) asm volatile("s_waitcnt lgkmcnt(" #n ")" ::: "memory")
; template <class Epi, class Sched, bool ALIGN_EPI = false, bool SP2 = false>
; __device__ __forceinline__ void gemm_phase(PG8_LAS unsigned char* lds, const Gemm g, const Sched& S, const Epi& E, const int tid) {
;     ...
;             const bool last = (t == nt - 2);
;             const char* a1 = cA + (size_t)(t + 1) * kstep;
;             const char* a2 = last ? nA : cA + (size_t)(t + 2) * kstep; const char* b2 = last ? nB : cB + (size_t)(t + 2) * kstep;
;             const char* a3 = a2 + kstep; const char* b3 = b2 + kstep;
;             if (last && has_next) S.a_ready(nxt);
;             if constexpr (SP2) {
;             PG8_LDB(B0, 0, 0); PG8_LDB(B1, 0, 1); PG8_SCHED; PG8_LDA(At, 0, 0); PG8_STAGE(PG8_SA(1, 1), a1 + hstep, voffA);
;             PG8_WAIT_V(8); PG8_WAIT_L(0); PG8_BAR; PG8_MMA(0, 0, At, B0); PG8_MMA(0, 1, At, B1); PG8_BAR; PG8_SCHED;
;             PG8_LDA(At, 0, 1); PG8_STAGE(PG8_SB(0, 0), b2, voffB); PG8_STAGE(PG8_SB(0, 1), b2 + hstep, voffB); PG8_STAGE(PG8_SA(0, 0), a2, voffA);
;             PG8_WAIT_V(8); PG8_WAIT_L(0); PG8_BAR; PG8_MMA(1, 0, At, B0); PG8_MMA(1, 1, At, B1); PG8_BAR; PG8_SCHED;
.LBB0_1545:
	s_add_i32 s50, 0, 0x10000
	v_add_u32_e32 v152, s50, v145
	ds_read_b128 v[148:151], v152
	ds_read_b128 v[170:173], v152 offset:1024
	ds_read_b128 v[174:177], v152 offset:2048
	ds_read_b128 v[178:181], v152 offset:3072
	s_add_u32 s12, s36, 0xfffc0080
	s_addc_u32 s42, s37, -1
	s_cmp_eq_u32 s49, 12
	s_cselect_b32 s45, s27, s42
	s_cselect_b32 s44, s30, s12
	s_cselect_b32 s43, s25, s48
	s_cselect_b32 s42, s46, s47
	s_add_i32 s12, 0, 0x14000
	v_add_u32_e32 v152, s12, v145
	ds_read_b128 v[182:185], v152
	ds_read_b128 v[186:189], v152 offset:1024
	ds_read_b128 v[190:193], v152 offset:2048
	ds_read_b128 v[194:197], v152 offset:3072
	v_lshl_add_u64 v[152:153], s[36:37], 0, v[136:137]
	s_add_i32 m0, s5, 0xc000
	ds_read_b128 v[212:215], v147
	ds_read_b128 v[216:219], v147 offset:1024
	ds_read_b128 v[220:223], v147 offset:2048
	ds_read_b128 v[224:227], v147 offset:3072
	ds_read_b128 v[228:231], v147 offset:4096
	ds_read_b128 v[236:239], v147 offset:5120
	ds_read_b128 v[240:243], v147 offset:6144
	ds_read_b128 v[244:247], v147 offset:7168
	global_load_lds_dwordx4 v[152:153], off
	v_lshl_add_u64 v[152:153], s[36:37], 0, v[138:139]
	s_add_i32 m0, s5, 0xe000
	s_nop 0
	global_load_lds_dwordx4 v[152:153], off
	s_waitcnt vmcnt(8)
	s_waitcnt lgkmcnt(0)
	s_barrier
	s_setprio 1
	s_waitcnt lgkmcnt(0)
	v_mfma_f32_16x16x32_bf16 v[128:131], v[148:151], v[212:215], v[128:131]
	v_mfma_f32_16x16x32_bf16 v[124:127], v[174:177], v[212:215], v[124:127]
	v_mfma_f32_16x16x32_bf16 v[120:123], v[148:151], v[220:223], v[120:123]
	v_mfma_f32_16x16x32_bf16 v[116:119], v[174:177], v[220:223], v[116:119]
	v_mfma_f32_16x16x32_bf16 v[104:107], v[148:151], v[228:231], v[104:107]
	v_mfma_f32_16x16x32_bf16 v[100:103], v[174:177], v[228:231], v[100:103]
	v_mfma_f32_16x16x32_bf16 v[88:91], v[148:151], v[240:243], v[88:91]
	v_mfma_f32_16x16x32_bf16 v[84:87], v[174:177], v[240:243], v[84:87]
	v_mfma_f32_16x16x32_bf16 v[128:131], v[170:173], v[216:219], v[128:131]
	v_mfma_f32_16x16x32_bf16 v[124:127], v[178:181], v[216:219], v[124:127]
	v_mfma_f32_16x16x32_bf16 v[120:123], v[170:173], v[224:227], v[120:123]
	v_mfma_f32_16x16x32_bf16 v[116:119], v[178:181], v[224:227], v[116:119]
	v_mfma_f32_16x16x32_bf16 v[104:107], v[170:173], v[236:239], v[104:107]
	v_mfma_f32_16x16x32_bf16 v[100:103], v[178:181], v[236:239], v[100:103]
	v_mfma_f32_16x16x32_bf16 v[88:91], v[170:173], v[244:247], v[88:91]
	v_mfma_f32_16x16x32_bf16 v[84:87], v[178:181], v[244:247], v[84:87]
	s_setprio 0
	s_setprio 1
	v_mfma_f32_16x16x32_bf16 v[112:115], v[182:185], v[212:215], v[112:115]
	v_mfma_f32_16x16x32_bf16 v[108:111], v[190:193], v[212:215], v[108:111]
	v_mfma_f32_16x16x32_bf16 v[96:99], v[182:185], v[220:223], v[96:99]
	v_mfma_f32_16x16x32_bf16 v[92:95], v[190:193], v[220:223], v[92:95]
	v_mfma_f32_16x16x32_bf16 v[80:83], v[182:185], v[228:231], v[80:83]
	v_mfma_f32_16x16x32_bf16 v[76:79], v[190:193], v[228:231], v[76:79]
	v_mfma_f32_16x16x32_bf16 v[72:75], v[182:185], v[240:243], v[72:75]
	v_mfma_f32_16x16x32_bf16 v[68:71], v[190:193], v[240:243], v[68:71]
	v_mfma_f32_16x16x32_bf16 v[112:115], v[186:189], v[216:219], v[112:115]
	v_mfma_f32_16x16x32_bf16 v[108:111], v[194:197], v[216:219], v[108:111]
	v_mfma_f32_16x16x32_bf16 v[96:99], v[186:189], v[224:227], v[96:99]
	v_mfma_f32_16x16x32_bf16 v[92:95], v[194:197], v[224:227], v[92:95]
	v_mfma_f32_16x16x32_bf16 v[80:83], v[186:189], v[236:239], v[80:83]
	v_mfma_f32_16x16x32_bf16 v[76:79], v[194:197], v[236:239], v[76:79]
	v_mfma_f32_16x16x32_bf16 v[72:75], v[186:189], v[244:247], v[72:75]
	v_mfma_f32_16x16x32_bf16 v[68:71], v[194:197], v[244:247], v[68:71]
	s_setprio 0
	s_barrier
	s_add_i32 s50, s50, s4
	v_lshl_add_u64 v[152:153], s[42:43], 0, v[2:3]
	s_mov_b32 m0, s50
	ds_read_b128 v[212:215], v147 offset:16384
	ds_read_b128 v[216:219], v147 offset:17408
	ds_read_b128 v[220:223], v147 offset:18432
	ds_read_b128 v[224:227], v147 offset:19456
	ds_read_b128 v[228:231], v147 offset:20480
	ds_read_b128 v[236:239], v147 offset:21504
	ds_read_b128 v[240:243], v147 offset:22528
	ds_read_b128 v[244:247], v147 offset:23552
	global_load_lds_dwordx4 v[152:153], off
	s_add_i32 m0, s50, 0x2000
	s_add_u32 s50, s42, 0x40000
	v_lshl_add_u64 v[198:199], s[42:43], 0, v[0:1]
	s_addc_u32 s51, s43, 0
	s_add_i32 s12, s12, s4
	global_load_lds_dwordx4 v[198:199], off
	v_lshl_add_u64 v[248:249], s[50:51], 0, v[2:3]
	s_mov_b32 m0, s12
	v_lshl_add_u64 v[250:251], s[44:45], 0, v[132:133]
	global_load_lds_dwordx4 v[248:249], off
	v_lshl_add_u64 v[248:249], s[50:51], 0, v[0:1]
	s_add_i32 m0, s12, 0x2000
	s_nop 0
	global_load_lds_dwordx4 v[248:249], off
	v_lshl_add_u64 v[248:249], s[44:45], 0, v[134:135]
	s_mov_b32 m0, s5
	s_nop 0
	global_load_lds_dwordx4 v[248:249], off
	s_mov_b32 m0, s6
	s_nop 0
	global_load_lds_dwordx4 v[250:251], off
	s_waitcnt vmcnt(8)
	s_waitcnt lgkmcnt(0)
	s_barrier
; #define PG8_STAGE(bufoff, gbase, voff) do { _Pragma("unroll") for (int _i = 0; _i < 2; ++_i) \
;         __builtin_amdgcn_global_load_lds((const unsigned*)((const char*)(gbase) + (voff)[_i]), (PG8_LAS unsigned*)(lds + (bufoff) + ldsw + _i * 8192), 16, 0, 0); } while (0)
; #define PG8_LDA(dst, b, h) do { _Pragma("unroll") for (int m = 0; m < 4; ++m) _Pragma("unroll") for (int k = 0; k < 2; ++k) dst[m][k] = *(const PG8_LAS bf16x8*)(lds + PG8_SA(b, h) + aoff + m * 2048 + k * 1024); } while (0)
; #define PG8_LDB(dst, b, h) do { _Pragma("unroll") for (int n = 0; n < 2; ++n) _Pragma("unroll") for (int k = 0; k < 2; ++k) dst[n][k] = *(const PG8_LAS bf16x8*)(lds + PG8_SB(b, h) + boff + n * 2048 + k * 1024); } while (0)
; #define PG8_MMA(ai, bj, At, Bt) do { __builtin_amdgcn_s_setprio(1); _Pragma("unroll") for (int m = 0; m < 4; ++m) _Pragma("unroll") for (int n = 0; n < 2; ++n) _Pragma("unroll") for (int k = 0; k < 2; ++k) \
;         acc[ai][bj][m][n] = __builtin_amdgcn_mfma_f32_16x16x32_bf16(Bt[n][k], At[m][k], acc[ai][bj][m][n], 0, 0, 0); __builtin_amdgcn_s_setprio(0); } while (0)
; #define PG8_WAIT_V(n) asm volatile("s_waitcnt vmcnt(" #n ")" ::: "memory")
; #define PG8_WAIT_L(n) asm volatile("s_waitcnt lgkmcnt(" #n ")" ::: "memory")
; #define PG8_BAR __builtin_amdgcn_s_barrier()
; #define PG8_SCHED __builtin_amdgcn_sched_barrier(0)
; template <class Epi, class Sched, bool ALIGN_EPI = false, bool SP2 = false>
; __device__ __forceinline__ void gemm_phase(PG8_LAS unsigned char* lds, const Gemm g, const Sched& S, const Epi& E, const int tid) {
;     ...
;             PG8_WAIT_V(8); PG8_WAIT_L(0); PG8_BAR; PG8_MMA(1, 0, At, B0); PG8_MMA(1, 1, At, B1); PG8_BAR; PG8_SCHED;
;             PG8_LDB(B0, 1, 0); PG8_LDB(B1, 1, 1); PG8_SCHED; PG8_LDA(At, 1, 0); PG8_STAGE(PG8_SA(0, 1), a2 + hstep, voffA);
;             PG8_WAIT_V(8); PG8_WAIT_L(0); PG8_BAR; PG8_MMA(0, 0, At, B0); PG8_MMA(0, 1, At, B1); PG8_BAR; PG8_SCHED;
	s_setprio 1
	s_waitcnt lgkmcnt(0)
	v_mfma_f32_16x16x32_bf16 v[64:67], v[148:151], v[212:215], v[64:67]
	v_mfma_f32_16x16x32_bf16 v[60:63], v[174:177], v[212:215], v[60:63]
	v_mfma_f32_16x16x32_bf16 v[56:59], v[148:151], v[220:223], v[56:59]
	v_mfma_f32_16x16x32_bf16 v[52:55], v[174:177], v[220:223], v[52:55]
	v_mfma_f32_16x16x32_bf16 v[40:43], v[148:151], v[228:231], v[40:43]
	v_mfma_f32_16x16x32_bf16 v[36:39], v[174:177], v[228:231], v[36:39]
	v_mfma_f32_16x16x32_bf16 v[24:27], v[148:151], v[240:243], v[24:27]
	v_mfma_f32_16x16x32_bf16 v[20:23], v[174:177], v[240:243], v[20:23]
	v_mfma_f32_16x16x32_bf16 v[64:67], v[170:173], v[216:219], v[64:67]
	v_mfma_f32_16x16x32_bf16 v[60:63], v[178:181], v[216:219], v[60:63]
	v_mfma_f32_16x16x32_bf16 v[56:59], v[170:173], v[224:227], v[56:59]
	v_mfma_f32_16x16x32_bf16 v[52:55], v[178:181], v[224:227], v[52:55]
	v_mfma_f32_16x16x32_bf16 v[40:43], v[170:173], v[236:239], v[40:43]
	v_mfma_f32_16x16x32_bf16 v[36:39], v[178:181], v[236:239], v[36:39]
	v_mfma_f32_16x16x32_bf16 v[24:27], v[170:173], v[244:247], v[24:27]
	v_mfma_f32_16x16x32_bf16 v[20:23], v[178:181], v[244:247], v[20:23]
	s_setprio 0
	s_setprio 1
	v_mfma_f32_16x16x32_bf16 v[48:51], v[182:185], v[212:215], v[48:51]
	v_mfma_f32_16x16x32_bf16 v[44:47], v[190:193], v[212:215], v[44:47]
	v_mfma_f32_16x16x32_bf16 v[32:35], v[182:185], v[220:223], v[32:35]
	v_mfma_f32_16x16x32_bf16 v[28:31], v[190:193], v[220:223], v[28:31]
	v_mfma_f32_16x16x32_bf16 v[16:19], v[182:185], v[228:231], v[16:19]
	v_mfma_f32_16x16x32_bf16 v[12:15], v[190:193], v[228:231], v[12:15]
	v_mfma_f32_16x16x32_bf16 v[8:11], v[182:185], v[240:243], v[8:11]
	v_mfma_f32_16x16x32_bf16 v[4:7], v[190:193], v[240:243], v[4:7]
	v_mfma_f32_16x16x32_bf16 v[48:51], v[186:189], v[216:219], v[48:51]
	v_mfma_f32_16x16x32_bf16 v[44:47], v[194:197], v[216:219], v[44:47]
	v_mfma_f32_16x16x32_bf16 v[32:35], v[186:189], v[224:227], v[32:35]
	v_mfma_f32_16x16x32_bf16 v[28:31], v[194:197], v[224:227], v[28:31]
	v_mfma_f32_16x16x32_bf16 v[16:19], v[186:189], v[236:239], v[16:19]
	v_mfma_f32_16x16x32_bf16 v[12:15], v[194:197], v[236:239], v[12:15]
	v_mfma_f32_16x16x32_bf16 v[8:11], v[186:189], v[244:247], v[8:11]
	v_mfma_f32_16x16x32_bf16 v[4:7], v[194:197], v[244:247], v[4:7]
	s_setprio 0
	s_barrier
	s_add_i32 s12, 0, 0x18000
	v_add_u32_e32 v160, s12, v145
	s_add_i32 s50, 0, 0x1c000
	ds_read_b128 v[148:151], v160
	ds_read_b128 v[170:173], v160 offset:1024
	ds_read_b128 v[174:177], v160 offset:2048
	ds_read_b128 v[178:181], v160 offset:3072
	v_add_u32_e32 v160, s50, v145
	ds_read_b128 v[182:185], v160
	ds_read_b128 v[186:189], v160 offset:1024
	ds_read_b128 v[190:193], v160 offset:2048
	ds_read_b128 v[194:197], v160 offset:3072
	s_add_u32 s44, s44, 0x40000
	s_addc_u32 s45, s45, 0
	s_mov_b32 m0, s7
	v_lshl_add_u64 v[160:161], s[44:45], 0, v[134:135]
	ds_read_b128 v[212:215], v147 offset:32768
	ds_read_b128 v[216:219], v147 offset:33792
	ds_read_b128 v[220:223], v147 offset:34816
	ds_read_b128 v[224:227], v147 offset:35840
	ds_read_b128 v[228:231], v147 offset:36864
	ds_read_b128 v[236:239], v147 offset:37888
	ds_read_b128 v[240:243], v147 offset:38912
	ds_read_b128 v[244:247], v147 offset:39936
	global_load_lds_dwordx4 v[160:161], off
	v_lshl_add_u64 v[160:161], s[44:45], 0, v[132:133]
	s_mov_b32 m0, s8
	s_nop 0
	global_load_lds_dwordx4 v[160:161], off
	s_waitcnt vmcnt(8)
	s_waitcnt lgkmcnt(0)
	s_barrier
	s_setprio 1
	s_waitcnt lgkmcnt(0)
	v_mfma_f32_16x16x32_bf16 v[128:131], v[148:151], v[212:215], v[128:131]
	v_mfma_f32_16x16x32_bf16 v[124:127], v[174:177], v[212:215], v[124:127]
	v_mfma_f32_16x16x32_bf16 v[120:123], v[148:151], v[220:223], v[120:123]
	v_mfma_f32_16x16x32_bf16 v[116:119], v[174:177], v[220:223], v[116:119]
	v_mfma_f32_16x16x32_bf16 v[104:107], v[148:151], v[228:231], v[104:107]
	v_mfma_f32_16x16x32_bf16 v[100:103], v[174:177], v[228:231], v[100:103]
	v_mfma_f32_16x16x32_bf16 v[88:91], v[148:151], v[240:243], v[88:91]
	v_mfma_f32_16x16x32_bf16 v[84:87], v[174:177], v[240:243], v[84:87]
	v_mfma_f32_16x16x32_bf16 v[128:131], v[170:173], v[216:219], v[128:131]
	v_mfma_f32_16x16x32_bf16 v[124:127], v[178:181], v[216:219], v[124:127]
	v_mfma_f32_16x16x32_bf16 v[120:123], v[170:173], v[224:227], v[120:123]
	v_mfma_f32_16x16x32_bf16 v[116:119], v[178:181], v[224:227], v[116:119]
	v_mfma_f32_16x16x32_bf16 v[104:107], v[170:173], v[236:239], v[104:107]
	v_mfma_f32_16x16x32_bf16 v[100:103], v[178:181], v[236:239], v[100:103]
	v_mfma_f32_16x16x32_bf16 v[88:91], v[170:173], v[244:247], v[88:91]
	v_mfma_f32_16x16x32_bf16 v[84:87], v[178:181], v[244:247], v[84:87]
	s_setprio 0
	s_setprio 1
	v_mfma_f32_16x16x32_bf16 v[112:115], v[182:185], v[212:215], v[112:115]
	v_mfma_f32_16x16x32_bf16 v[108:111], v[190:193], v[212:215], v[108:111]
	v_mfma_f32_16x16x32_bf16 v[96:99], v[182:185], v[220:223], v[96:99]
	v_mfma_f32_16x16x32_bf16 v[92:95], v[190:193], v[220:223], v[92:95]
	v_mfma_f32_16x16x32_bf16 v[80:83], v[182:185], v[228:231], v[80:83]
	v_mfma_f32_16x16x32_bf16 v[76:79], v[190:193], v[228:231], v[76:79]
	v_mfma_f32_16x16x32_bf16 v[72:75], v[182:185], v[240:243], v[72:75]
	v_mfma_f32_16x16x32_bf16 v[68:71], v[190:193], v[240:243], v[68:71]
	v_mfma_f32_16x16x32_bf16 v[112:115], v[186:189], v[216:219], v[112:115]
	v_mfma_f32_16x16x32_bf16 v[108:111], v[194:197], v[216:219], v[108:111]
	v_mfma_f32_16x16x32_bf16 v[96:99], v[186:189], v[224:227], v[96:99]
	v_mfma_f32_16x16x32_bf16 v[92:95], v[194:197], v[224:227], v[92:95]
	v_mfma_f32_16x16x32_bf16 v[80:83], v[186:189], v[236:239], v[80:83]
	v_mfma_f32_16x16x32_bf16 v[76:79], v[194:197], v[236:239], v[76:79]
	v_mfma_f32_16x16x32_bf16 v[72:75], v[186:189], v[244:247], v[72:75]
	v_mfma_f32_16x16x32_bf16 v[68:71], v[194:197], v[244:247], v[68:71]
	s_setprio 0
	s_barrier
; #define PG8_STAGE(bufoff, gbase, voff) do { _Pragma("unroll") for (int _i = 0; _i < 2; ++_i) \
;         __builtin_amdgcn_global_load_lds((const unsigned*)((const char*)(gbase) + (voff)[_i]), (PG8_LAS unsigned*)(lds + (bufoff) + ldsw + _i * 8192), 16, 0, 0); } while (0)
; #define PG8_LDA(dst, b, h) do { _Pragma("unroll") for (int m = 0; m < 4; ++m) _Pragma("unroll") for (int k = 0; k < 2; ++k) dst[m][k] = *(const PG8_LAS bf16x8*)(lds + PG8_SA(b, h) + aoff + m * 2048 + k * 1024); } while (0)
; #define PG8_MMA(ai, bj, At, Bt) do { __builtin_amdgcn_s_setprio(1); _Pragma("unroll") for (int m = 0; m < 4; ++m) _Pragma("unroll") for (int n = 0; n < 2; ++n) _Pragma("unroll") for (int k = 0; k < 2; ++k) \
;         acc[ai][bj][m][n] = __builtin_amdgcn_mfma_f32_16x16x32_bf16(Bt[n][k], At[m][k], acc[ai][bj][m][n], 0, 0, 0); __builtin_amdgcn_s_setprio(0); } while (0)
; #define PG8_WAIT_V(n) asm volatile("s_waitcnt vmcnt(" #n ")" ::: "memory")
; #define PG8_WAIT_L(n) asm volatile("s_waitcnt lgkmcnt(" #n ")" ::: "memory")
; #define PG8_BAR __builtin_amdgcn_s_barrier()
; #define PG8_SCHED __builtin_amdgcn_sched_barrier(0)
; template <class Epi, class Sched, bool ALIGN_EPI = false, bool SP2 = false>
; __device__ __forceinline__ void gemm_phase(PG8_LAS unsigned char* lds, const Gemm g, const Sched& S, const Epi& E, const int tid) {
;     ...
;         for (int t = 0; t < nt; t += 2) {
;     ...
;             PG8_LDA(At, 1, 1); PG8_STAGE(PG8_SB(1, 0), b3, voffB); PG8_STAGE(PG8_SB(1, 1), b3 + hstep, voffB); PG8_STAGE(PG8_SA(1, 0), a3, voffA);
;             PG8_WAIT_V(8); PG8_WAIT_L(0); PG8_BAR; PG8_MMA(1, 0, At, B0); PG8_MMA(1, 1, At, B1); PG8_BAR; PG8_SCHED;
	s_add_i32 s12, s12, s4
	v_lshl_add_u64 v[152:153], v[152:153], 0, s[18:19]
	s_mov_b32 m0, s12
	ds_read_b128 v[212:215], v147 offset:49152
	ds_read_b128 v[216:219], v147 offset:50176
	ds_read_b128 v[220:223], v147 offset:51200
	ds_read_b128 v[224:227], v147 offset:52224
	ds_read_b128 v[228:231], v147 offset:53248
	ds_read_b128 v[236:239], v147 offset:54272
	ds_read_b128 v[240:243], v147 offset:55296
	ds_read_b128 v[244:247], v147 offset:56320
	global_load_lds_dwordx4 v[152:153], off
	s_add_i32 m0, s12, 0x2000
	s_add_u32 s42, s42, 0x40080
	v_lshl_add_u64 v[152:153], v[198:199], 0, s[18:19]
	s_addc_u32 s43, s43, 0
	s_add_i32 s12, s50, s4
	global_load_lds_dwordx4 v[152:153], off
	v_lshl_add_u64 v[152:153], s[42:43], 0, v[2:3]
	s_mov_b32 m0, s12
	s_nop 0
	global_load_lds_dwordx4 v[152:153], off
	v_lshl_add_u64 v[152:153], s[42:43], 0, v[0:1]
	s_add_i32 m0, s12, 0x2000
	s_nop 0
	global_load_lds_dwordx4 v[152:153], off
	v_lshl_add_u64 v[152:153], v[248:249], 0, s[18:19]
	s_mov_b32 m0, s9
	s_nop 0
	global_load_lds_dwordx4 v[152:153], off
	v_lshl_add_u64 v[152:153], v[250:251], 0, s[18:19]
	s_mov_b32 m0, s13
	s_nop 0
	global_load_lds_dwordx4 v[152:153], off
	s_waitcnt vmcnt(8)
	s_waitcnt lgkmcnt(0)
	s_barrier
	s_setprio 1
	s_waitcnt lgkmcnt(0)
	v_mfma_f32_16x16x32_bf16 v[64:67], v[148:151], v[212:215], v[64:67]
	v_mfma_f32_16x16x32_bf16 v[60:63], v[174:177], v[212:215], v[60:63]
	v_mfma_f32_16x16x32_bf16 v[56:59], v[148:151], v[220:223], v[56:59]
	v_mfma_f32_16x16x32_bf16 v[52:55], v[174:177], v[220:223], v[52:55]
	v_mfma_f32_16x16x32_bf16 v[40:43], v[148:151], v[228:231], v[40:43]
	v_mfma_f32_16x16x32_bf16 v[36:39], v[174:177], v[228:231], v[36:39]
	v_mfma_f32_16x16x32_bf16 v[24:27], v[148:151], v[240:243], v[24:27]
	v_mfma_f32_16x16x32_bf16 v[20:23], v[174:177], v[240:243], v[20:23]
	v_mfma_f32_16x16x32_bf16 v[64:67], v[170:173], v[216:219], v[64:67]
	v_mfma_f32_16x16x32_bf16 v[60:63], v[178:181], v[216:219], v[60:63]
	v_mfma_f32_16x16x32_bf16 v[56:59], v[170:173], v[224:227], v[56:59]
	v_mfma_f32_16x16x32_bf16 v[52:55], v[178:181], v[224:227], v[52:55]
	v_mfma_f32_16x16x32_bf16 v[40:43], v[170:173], v[236:239], v[40:43]
	v_mfma_f32_16x16x32_bf16 v[36:39], v[178:181], v[236:239], v[36:39]
	v_mfma_f32_16x16x32_bf16 v[24:27], v[170:173], v[244:247], v[24:27]
	v_mfma_f32_16x16x32_bf16 v[20:23], v[178:181], v[244:247], v[20:23]
	s_setprio 0
	s_setprio 1
	v_mfma_f32_16x16x32_bf16 v[48:51], v[182:185], v[212:215], v[48:51]
	v_mfma_f32_16x16x32_bf16 v[44:47], v[190:193], v[212:215], v[44:47]
	s_add_i32 s49, s49, 2
	v_mfma_f32_16x16x32_bf16 v[32:35], v[182:185], v[220:223], v[32:35]
	s_add_u32 s36, s36, 0x100
	v_mfma_f32_16x16x32_bf16 v[28:31], v[190:193], v[220:223], v[28:31]
	s_addc_u32 s37, s37, 0
	v_mfma_f32_16x16x32_bf16 v[16:19], v[182:185], v[228:231], v[16:19]
	s_add_u32 s47, s47, 0x100
	v_mfma_f32_16x16x32_bf16 v[12:15], v[190:193], v[228:231], v[12:15]
	s_addc_u32 s48, s48, 0
	v_mfma_f32_16x16x32_bf16 v[8:11], v[182:185], v[240:243], v[8:11]
	s_cmp_gt_u32 s49, 13
	v_mfma_f32_16x16x32_bf16 v[4:7], v[190:193], v[240:243], v[4:7]
	v_mfma_f32_16x16x32_bf16 v[48:51], v[186:189], v[216:219], v[48:51]
	v_mfma_f32_16x16x32_bf16 v[44:47], v[194:197], v[216:219], v[44:47]
	v_mfma_f32_16x16x32_bf16 v[32:35], v[186:189], v[224:227], v[32:35]
	v_mfma_f32_16x16x32_bf16 v[28:31], v[194:197], v[224:227], v[28:31]
	v_mfma_f32_16x16x32_bf16 v[16:19], v[186:189], v[236:239], v[16:19]
	v_mfma_f32_16x16x32_bf16 v[12:15], v[194:197], v[236:239], v[12:15]
	v_mfma_f32_16x16x32_bf16 v[8:11], v[186:189], v[244:247], v[8:11]
	v_mfma_f32_16x16x32_bf16 v[4:7], v[194:197], v[244:247], v[4:7]
	s_setprio 0
	s_barrier
	s_cbranch_scc0 .LBB0_1545
	s_and_b64 vcc, exec, s[20:21]
	s_cbranch_vccz .LBB0_1548
	s_barrier

; #define PG8_STAGE(bufoff, gbase, voff) do { _Pragma("unroll") for (int _i = 0; _i < 2; ++_i) \
;         __builtin_amdgcn_global_load_lds((const unsigned*)((const char*)(gbase) + (voff)[_i]), (PG8_LAS unsigned*)(lds + (bufoff) + ldsw + _i * 8192), 16, 0, 0); } while (0)
; #define PG8_LDA(dst, b, h) do { _Pragma("unroll") for (int m = 0; m < 4; ++m) _Pragma("unroll") for (int k = 0; k < 2; ++k) dst[m][k] = *(const PG8_LAS bf16x8*)(lds + PG8_SA(b, h) + aoff + m * 2048 + k * 1024); } while (0)
; #define PG8_LDB(dst, b, h) do { _Pragma("unroll") for (int n = 0; n < 2; ++n) _Pragma("unroll") for (int k = 0; k < 2; ++k) dst[n][k] = *(const PG8_LAS bf16x8*)(lds + PG8_SB(b, h) + boff + n * 2048 + k * 1024); } while (0)
; #define PG8_MMA(ai, bj, At, Bt) do { __builtin_amdgcn_s_setprio(1); _Pragma("unroll") for (int m = 0; m < 4; ++m) _Pragma("unroll") for (int n = 0; n < 2; ++n) _Pragma("unroll") for (int k = 0; k < 2; ++k) \
;         acc[ai][bj][m][n] = __builtin_amdgcn_mfma_f32_16x16x32_bf16(Bt[n][k], At[m][k], acc[ai][bj][m][n], 0, 0, 0); __builtin_amdgcn_s_setprio(0); } while (0)
; #define PG8_WAIT_V(n) asm volatile("s_waitcnt vmcnt(" #n ")" ::: "memory")
; #define PG8_WAIT_L(n) asm volatile("s_waitcnt lgkmcnt(" #n ")" ::: "memory")
; template <class Epi, class Sched, bool ALIGN_EPI = false, bool SP2 = false>
; __device__ __forceinline__ void gemm_phase(PG8_LAS unsigned char* lds, const Gemm g, const Sched& S, const Epi& E, const int tid) {
;     ...
;             const bool last = (t == nt - 2);
;             const char* a1 = cA + (size_t)(t + 1) * kstep;
;             const char* a2 = last ? nA : cA + (size_t)(t + 2) * kstep; const char* b2 = last ? nB : cB + (size_t)(t + 2) * kstep;
;             const char* a3 = a2 + kstep; const char* b3 = b2 + kstep;
;             if (last && has_next) S.a_ready(nxt);
;             if constexpr (SP2) {
;             PG8_LDB(B0, 0, 0); PG8_LDB(B1, 0, 1); PG8_SCHED; PG8_LDA(At, 0, 0); PG8_STAGE(PG8_SA(1, 1), a1 + hstep, voffA);
;             PG8_WAIT_V(8); PG8_WAIT_L(0); PG8_BAR; PG8_MMA(0, 0, At, B0); PG8_MMA(0, 1, At, B1); PG8_BAR; PG8_SCHED;
;             PG8_LDA(At, 0, 1); PG8_STAGE(PG8_SB(0, 0), b2, voffB); PG8_STAGE(PG8_SB(0, 1), b2 + hstep, voffB); PG8_STAGE(PG8_SA(0, 0), a2, voffA);
;             PG8_WAIT_V(8); PG8_WAIT_L(0); PG8_BAR; PG8_MMA(1, 0, At, B0); PG8_MMA(1, 1, At, B1); PG8_BAR; PG8_SCHED;
.LBB0_1567:
	s_add_i32 s50, 0, 0x10000
	v_add_u32_e32 v143, s50, v141
	ds_read_b128 v[146:149], v143
	ds_read_b128 v[150:153], v143 offset:1024
	ds_read_b128 v[170:173], v143 offset:2048
	ds_read_b128 v[174:177], v143 offset:3072
	s_add_u32 s12, s36, 0xfffc0080
	s_addc_u32 s42, s37, -1
	s_cmp_eq_u32 s49, 12
	s_cselect_b32 s45, s27, s42
	s_cselect_b32 s44, s30, s12
	s_cselect_b32 s43, s25, s48
	s_cselect_b32 s42, s46, s47
	s_add_i32 s12, 0, 0x14000
	v_add_u32_e32 v143, s12, v141
	ds_read_b128 v[178:181], v143
	ds_read_b128 v[182:185], v143 offset:1024
	ds_read_b128 v[186:189], v143 offset:2048
	ds_read_b128 v[190:193], v143 offset:3072
	v_lshl_add_u64 v[198:199], s[36:37], 0, v[136:137]
	s_add_i32 m0, s5, 0xc000
	ds_read_b128 v[194:197], v142
	ds_read_b128 v[212:215], v142 offset:1024
	ds_read_b128 v[216:219], v142 offset:2048
	ds_read_b128 v[220:223], v142 offset:3072
	ds_read_b128 v[224:227], v142 offset:4096
	ds_read_b128 v[228:231], v142 offset:5120
	ds_read_b128 v[236:239], v142 offset:6144
	ds_read_b128 v[240:243], v142 offset:7168
	global_load_lds_dwordx4 v[198:199], off
	v_lshl_add_u64 v[198:199], s[36:37], 0, v[138:139]
	s_add_i32 m0, s5, 0xe000
	s_nop 0
	global_load_lds_dwordx4 v[198:199], off
	s_waitcnt vmcnt(8)
	s_waitcnt lgkmcnt(0)
	s_barrier
	s_setprio 1
	s_waitcnt lgkmcnt(0)
	v_mfma_f32_16x16x32_bf16 v[128:131], v[146:149], v[194:197], v[128:131]
	v_mfma_f32_16x16x32_bf16 v[124:127], v[170:173], v[194:197], v[124:127]
	v_mfma_f32_16x16x32_bf16 v[120:123], v[146:149], v[216:219], v[120:123]
	v_mfma_f32_16x16x32_bf16 v[116:119], v[170:173], v[216:219], v[116:119]
	v_mfma_f32_16x16x32_bf16 v[104:107], v[146:149], v[224:227], v[104:107]
	v_mfma_f32_16x16x32_bf16 v[100:103], v[170:173], v[224:227], v[100:103]
	v_mfma_f32_16x16x32_bf16 v[88:91], v[146:149], v[236:239], v[88:91]
	v_mfma_f32_16x16x32_bf16 v[84:87], v[170:173], v[236:239], v[84:87]
	v_mfma_f32_16x16x32_bf16 v[128:131], v[150:153], v[212:215], v[128:131]
	v_mfma_f32_16x16x32_bf16 v[124:127], v[174:177], v[212:215], v[124:127]
	v_mfma_f32_16x16x32_bf16 v[120:123], v[150:153], v[220:223], v[120:123]
	v_mfma_f32_16x16x32_bf16 v[116:119], v[174:177], v[220:223], v[116:119]
	v_mfma_f32_16x16x32_bf16 v[104:107], v[150:153], v[228:231], v[104:107]
	v_mfma_f32_16x16x32_bf16 v[100:103], v[174:177], v[228:231], v[100:103]
	v_mfma_f32_16x16x32_bf16 v[88:91], v[150:153], v[240:243], v[88:91]
	v_mfma_f32_16x16x32_bf16 v[84:87], v[174:177], v[240:243], v[84:87]
	s_setprio 0
	s_setprio 1
	v_mfma_f32_16x16x32_bf16 v[112:115], v[178:181], v[194:197], v[112:115]
	v_mfma_f32_16x16x32_bf16 v[108:111], v[186:189], v[194:197], v[108:111]
	v_mfma_f32_16x16x32_bf16 v[96:99], v[178:181], v[216:219], v[96:99]
	v_mfma_f32_16x16x32_bf16 v[92:95], v[186:189], v[216:219], v[92:95]
	v_mfma_f32_16x16x32_bf16 v[80:83], v[178:181], v[224:227], v[80:83]
	v_mfma_f32_16x16x32_bf16 v[76:79], v[186:189], v[224:227], v[76:79]
	v_mfma_f32_16x16x32_bf16 v[72:75], v[178:181], v[236:239], v[72:75]
	v_mfma_f32_16x16x32_bf16 v[68:71], v[186:189], v[236:239], v[68:71]
	v_mfma_f32_16x16x32_bf16 v[112:115], v[182:185], v[212:215], v[112:115]
	v_mfma_f32_16x16x32_bf16 v[108:111], v[190:193], v[212:215], v[108:111]
	v_mfma_f32_16x16x32_bf16 v[96:99], v[182:185], v[220:223], v[96:99]
	v_mfma_f32_16x16x32_bf16 v[92:95], v[190:193], v[220:223], v[92:95]
	v_mfma_f32_16x16x32_bf16 v[80:83], v[182:185], v[228:231], v[80:83]
	v_mfma_f32_16x16x32_bf16 v[76:79], v[190:193], v[228:231], v[76:79]
	v_mfma_f32_16x16x32_bf16 v[72:75], v[182:185], v[240:243], v[72:75]
	v_mfma_f32_16x16x32_bf16 v[68:71], v[190:193], v[240:243], v[68:71]
	s_setprio 0
	s_barrier
	s_add_i32 s50, s50, s4
	v_lshl_add_u64 v[198:199], s[42:43], 0, v[2:3]
	s_mov_b32 m0, s50
	ds_read_b128 v[194:197], v142 offset:16384
	ds_read_b128 v[212:215], v142 offset:17408
	ds_read_b128 v[216:219], v142 offset:18432
	ds_read_b128 v[220:223], v142 offset:19456
	ds_read_b128 v[224:227], v142 offset:20480
	ds_read_b128 v[228:231], v142 offset:21504
	ds_read_b128 v[236:239], v142 offset:22528
	ds_read_b128 v[240:243], v142 offset:23552
	global_load_lds_dwordx4 v[198:199], off
	s_add_i32 m0, s50, 0x2000
	s_add_u32 s50, s42, 0x40000
	v_lshl_add_u64 v[244:245], s[42:43], 0, v[0:1]
	s_addc_u32 s51, s43, 0
	s_add_i32 s12, s12, s4
	global_load_lds_dwordx4 v[244:245], off
	v_lshl_add_u64 v[246:247], s[50:51], 0, v[2:3]
	s_mov_b32 m0, s12
	v_lshl_add_u64 v[248:249], s[44:45], 0, v[132:133]
	global_load_lds_dwordx4 v[246:247], off
	v_lshl_add_u64 v[246:247], s[50:51], 0, v[0:1]
	s_add_i32 m0, s12, 0x2000
	s_nop 0
	global_load_lds_dwordx4 v[246:247], off
	v_lshl_add_u64 v[246:247], s[44:45], 0, v[134:135]
	s_mov_b32 m0, s5
	s_nop 0
	global_load_lds_dwordx4 v[246:247], off
	s_mov_b32 m0, s6
	s_nop 0
	global_load_lds_dwordx4 v[248:249], off
	s_waitcnt vmcnt(8)
	s_waitcnt lgkmcnt(0)
	s_barrier
; #define PG8_STAGE(bufoff, gbase, voff) do { _Pragma("unroll") for (int _i = 0; _i < 2; ++_i) \
;         __builtin_amdgcn_global_load_lds((const unsigned*)((const char*)(gbase) + (voff)[_i]), (PG8_LAS unsigned*)(lds + (bufoff) + ldsw + _i * 8192), 16, 0, 0); } while (0)
; #define PG8_LDA(dst, b, h) do { _Pragma("unroll") for (int m = 0; m < 4; ++m) _Pragma("unroll") for (int k = 0; k < 2; ++k) dst[m][k] = *(const PG8_LAS bf16x8*)(lds + PG8_SA(b, h) + aoff + m * 2048 + k * 1024); } while (0)
; #define PG8_LDB(dst, b, h) do { _Pragma("unroll") for (int n = 0; n < 2; ++n) _Pragma("unroll") for (int k = 0; k < 2; ++k) dst[n][k] = *(const PG8_LAS bf16x8*)(lds + PG8_SB(b, h) + boff + n * 2048 + k * 1024); } while (0)
; #define PG8_MMA(ai, bj, At, Bt) do { __builtin_amdgcn_s_setprio(1); _Pragma("unroll") for (int m = 0; m < 4; ++m) _Pragma("unroll") for (int n = 0; n < 2; ++n) _Pragma("unroll") for (int k = 0; k < 2; ++k) \
;         acc[ai][bj][m][n] = __builtin_amdgcn_mfma_f32_16x16x32_bf16(Bt[n][k], At[m][k], acc[ai][bj][m][n], 0, 0, 0); __builtin_amdgcn_s_setprio(0); } while (0)
; #define PG8_WAIT_V(n) asm volatile("s_waitcnt vmcnt(" #n ")" ::: "memory")
; #define PG8_WAIT_L(n) asm volatile("s_waitcnt lgkmcnt(" #n ")" ::: "memory")
; #define PG8_BAR __builtin_amdgcn_s_barrier()
; #define PG8_SCHED __builtin_amdgcn_sched_barrier(0)
; template <class Epi, class Sched, bool ALIGN_EPI = false, bool SP2 = false>
; __device__ __forceinline__ void gemm_phase(PG8_LAS unsigned char* lds, const Gemm g, const Sched& S, const Epi& E, const int tid) {
;     ...
;             PG8_WAIT_V(8); PG8_WAIT_L(0); PG8_BAR; PG8_MMA(1, 0, At, B0); PG8_MMA(1, 1, At, B1); PG8_BAR; PG8_SCHED;
;             PG8_LDB(B0, 1, 0); PG8_LDB(B1, 1, 1); PG8_SCHED; PG8_LDA(At, 1, 0); PG8_STAGE(PG8_SA(0, 1), a2 + hstep, voffA);
;             PG8_WAIT_V(8); PG8_WAIT_L(0); PG8_BAR; PG8_MMA(0, 0, At, B0); PG8_MMA(0, 1, At, B1); PG8_BAR; PG8_SCHED;
	s_setprio 1
	s_waitcnt lgkmcnt(0)
	v_mfma_f32_16x16x32_bf16 v[64:67], v[146:149], v[194:197], v[64:67]
	v_mfma_f32_16x16x32_bf16 v[60:63], v[170:173], v[194:197], v[60:63]
	v_mfma_f32_16x16x32_bf16 v[56:59], v[146:149], v[216:219], v[56:59]
	v_mfma_f32_16x16x32_bf16 v[52:55], v[170:173], v[216:219], v[52:55]
	v_mfma_f32_16x16x32_bf16 v[40:43], v[146:149], v[224:227], v[40:43]
	v_mfma_f32_16x16x32_bf16 v[36:39], v[170:173], v[224:227], v[36:39]
	v_mfma_f32_16x16x32_bf16 v[24:27], v[146:149], v[236:239], v[24:27]
	v_mfma_f32_16x16x32_bf16 v[20:23], v[170:173], v[236:239], v[20:23]
	v_mfma_f32_16x16x32_bf16 v[64:67], v[150:153], v[212:215], v[64:67]
	v_mfma_f32_16x16x32_bf16 v[60:63], v[174:177], v[212:215], v[60:63]
	v_mfma_f32_16x16x32_bf16 v[56:59], v[150:153], v[220:223], v[56:59]
	v_mfma_f32_16x16x32_bf16 v[52:55], v[174:177], v[220:223], v[52:55]
	v_mfma_f32_16x16x32_bf16 v[40:43], v[150:153], v[228:231], v[40:43]
	v_mfma_f32_16x16x32_bf16 v[36:39], v[174:177], v[228:231], v[36:39]
	v_mfma_f32_16x16x32_bf16 v[24:27], v[150:153], v[240:243], v[24:27]
	v_mfma_f32_16x16x32_bf16 v[20:23], v[174:177], v[240:243], v[20:23]
	s_setprio 0
	s_setprio 1
	v_mfma_f32_16x16x32_bf16 v[48:51], v[178:181], v[194:197], v[48:51]
	v_mfma_f32_16x16x32_bf16 v[44:47], v[186:189], v[194:197], v[44:47]
	v_mfma_f32_16x16x32_bf16 v[32:35], v[178:181], v[216:219], v[32:35]
	v_mfma_f32_16x16x32_bf16 v[28:31], v[186:189], v[216:219], v[28:31]
	v_mfma_f32_16x16x32_bf16 v[16:19], v[178:181], v[224:227], v[16:19]
	v_mfma_f32_16x16x32_bf16 v[12:15], v[186:189], v[224:227], v[12:15]
	v_mfma_f32_16x16x32_bf16 v[8:11], v[178:181], v[236:239], v[8:11]
	v_mfma_f32_16x16x32_bf16 v[4:7], v[186:189], v[236:239], v[4:7]
	v_mfma_f32_16x16x32_bf16 v[48:51], v[182:185], v[212:215], v[48:51]
	v_mfma_f32_16x16x32_bf16 v[44:47], v[190:193], v[212:215], v[44:47]
	v_mfma_f32_16x16x32_bf16 v[32:35], v[182:185], v[220:223], v[32:35]
	v_mfma_f32_16x16x32_bf16 v[28:31], v[190:193], v[220:223], v[28:31]
	v_mfma_f32_16x16x32_bf16 v[16:19], v[182:185], v[228:231], v[16:19]
	v_mfma_f32_16x16x32_bf16 v[12:15], v[190:193], v[228:231], v[12:15]
	v_mfma_f32_16x16x32_bf16 v[8:11], v[182:185], v[240:243], v[8:11]
	v_mfma_f32_16x16x32_bf16 v[4:7], v[190:193], v[240:243], v[4:7]
	s_setprio 0
	s_barrier
	s_add_i32 s12, 0, 0x18000
	v_add_u32_e32 v143, s12, v141
	s_add_i32 s50, 0, 0x1c000
	ds_read_b128 v[146:149], v143
	ds_read_b128 v[150:153], v143 offset:1024
	ds_read_b128 v[170:173], v143 offset:2048
	ds_read_b128 v[174:177], v143 offset:3072
	v_add_u32_e32 v143, s50, v141
	ds_read_b128 v[178:181], v143
	ds_read_b128 v[182:185], v143 offset:1024
	ds_read_b128 v[186:189], v143 offset:2048
	ds_read_b128 v[190:193], v143 offset:3072
	s_add_u32 s44, s44, 0x40000
	s_addc_u32 s45, s45, 0
	s_mov_b32 m0, s7
	v_lshl_add_u64 v[250:251], s[44:45], 0, v[134:135]
	ds_read_b128 v[194:197], v142 offset:32768
	ds_read_b128 v[212:215], v142 offset:33792
	ds_read_b128 v[216:219], v142 offset:34816
	ds_read_b128 v[220:223], v142 offset:35840
	ds_read_b128 v[224:227], v142 offset:36864
	ds_read_b128 v[228:231], v142 offset:37888
	ds_read_b128 v[236:239], v142 offset:38912
	ds_read_b128 v[240:243], v142 offset:39936
	global_load_lds_dwordx4 v[250:251], off
	v_lshl_add_u64 v[250:251], s[44:45], 0, v[132:133]
	s_mov_b32 m0, s8
	s_nop 0
	global_load_lds_dwordx4 v[250:251], off
	s_waitcnt vmcnt(8)
	s_waitcnt lgkmcnt(0)
	s_barrier
	s_setprio 1
	s_waitcnt lgkmcnt(0)
	v_mfma_f32_16x16x32_bf16 v[128:131], v[146:149], v[194:197], v[128:131]
	v_mfma_f32_16x16x32_bf16 v[124:127], v[170:173], v[194:197], v[124:127]
	v_mfma_f32_16x16x32_bf16 v[120:123], v[146:149], v[216:219], v[120:123]
	v_mfma_f32_16x16x32_bf16 v[116:119], v[170:173], v[216:219], v[116:119]
	v_mfma_f32_16x16x32_bf16 v[104:107], v[146:149], v[224:227], v[104:107]
	v_mfma_f32_16x16x32_bf16 v[100:103], v[170:173], v[224:227], v[100:103]
	v_mfma_f32_16x16x32_bf16 v[88:91], v[146:149], v[236:239], v[88:91]
	v_mfma_f32_16x16x32_bf16 v[84:87], v[170:173], v[236:239], v[84:87]
	v_mfma_f32_16x16x32_bf16 v[128:131], v[150:153], v[212:215], v[128:131]
	v_mfma_f32_16x16x32_bf16 v[124:127], v[174:177], v[212:215], v[124:127]
	v_mfma_f32_16x16x32_bf16 v[120:123], v[150:153], v[220:223], v[120:123]
	v_mfma_f32_16x16x32_bf16 v[116:119], v[174:177], v[220:223], v[116:119]
	v_mfma_f32_16x16x32_bf16 v[104:107], v[150:153], v[228:231], v[104:107]
	v_mfma_f32_16x16x32_bf16 v[100:103], v[174:177], v[228:231], v[100:103]
	v_mfma_f32_16x16x32_bf16 v[88:91], v[150:153], v[240:243], v[88:91]
	v_mfma_f32_16x16x32_bf16 v[84:87], v[174:177], v[240:243], v[84:87]
	s_setprio 0
	s_setprio 1
	v_mfma_f32_16x16x32_bf16 v[112:115], v[178:181], v[194:197], v[112:115]
	v_mfma_f32_16x16x32_bf16 v[108:111], v[186:189], v[194:197], v[108:111]
	v_mfma_f32_16x16x32_bf16 v[96:99], v[178:181], v[216:219], v[96:99]
	v_mfma_f32_16x16x32_bf16 v[92:95], v[186:189], v[216:219], v[92:95]
	v_mfma_f32_16x16x32_bf16 v[80:83], v[178:181], v[224:227], v[80:83]
	v_mfma_f32_16x16x32_bf16 v[76:79], v[186:189], v[224:227], v[76:79]
	v_mfma_f32_16x16x32_bf16 v[72:75], v[178:181], v[236:239], v[72:75]
	v_mfma_f32_16x16x32_bf16 v[68:71], v[186:189], v[236:239], v[68:71]
	v_mfma_f32_16x16x32_bf16 v[112:115], v[182:185], v[212:215], v[112:115]
	v_mfma_f32_16x16x32_bf16 v[108:111], v[190:193], v[212:215], v[108:111]
	v_mfma_f32_16x16x32_bf16 v[96:99], v[182:185], v[220:223], v[96:99]
	v_mfma_f32_16x16x32_bf16 v[92:95], v[190:193], v[220:223], v[92:95]
	v_mfma_f32_16x16x32_bf16 v[80:83], v[182:185], v[228:231], v[80:83]
	v_mfma_f32_16x16x32_bf16 v[76:79], v[190:193], v[228:231], v[76:79]
	v_mfma_f32_16x16x32_bf16 v[72:75], v[182:185], v[240:243], v[72:75]
	v_mfma_f32_16x16x32_bf16 v[68:71], v[190:193], v[240:243], v[68:71]
	s_setprio 0
	s_barrier
; #define PG8_STAGE(bufoff, gbase, voff) do { _Pragma("unroll") for (int _i = 0; _i < 2; ++_i) \
;         __builtin_amdgcn_global_load_lds((const unsigned*)((const char*)(gbase) + (voff)[_i]), (PG8_LAS unsigned*)(lds + (bufoff) + ldsw + _i * 8192), 16, 0, 0); } while (0)
; #define PG8_LDA(dst, b, h) do { _Pragma("unroll") for (int m = 0; m < 4; ++m) _Pragma("unroll") for (int k = 0; k < 2; ++k) dst[m][k] = *(const PG8_LAS bf16x8*)(lds + PG8_SA(b, h) + aoff + m * 2048 + k * 1024); } while (0)
; #define PG8_MMA(ai, bj, At, Bt) do { __builtin_amdgcn_s_setprio(1); _Pragma("unroll") for (int m = 0; m < 4; ++m) _Pragma("unroll") for (int n = 0; n < 2; ++n) _Pragma("unroll") for (int k = 0; k < 2; ++k) \
;         acc[ai][bj][m][n] = __builtin_amdgcn_mfma_f32_16x16x32_bf16(Bt[n][k], At[m][k], acc[ai][bj][m][n], 0, 0, 0); __builtin_amdgcn_s_setprio(0); } while (0)
; #define PG8_WAIT_V(n) asm volatile("s_waitcnt vmcnt(" #n ")" ::: "memory")
; #define PG8_WAIT_L(n) asm volatile("s_waitcnt lgkmcnt(" #n ")" ::: "memory")
; #define PG8_BAR __builtin_amdgcn_s_barrier()
; #define PG8_SCHED __builtin_amdgcn_sched_barrier(0)
; template <class Epi, class Sched, bool ALIGN_EPI = false, bool SP2 = false>
; __device__ __forceinline__ void gemm_phase(PG8_LAS unsigned char* lds, const Gemm g, const Sched& S, const Epi& E, const int tid) {
;     ...
;         for (int t = 0; t < nt; t += 2) {
;     ...
;             PG8_LDA(At, 1, 1); PG8_STAGE(PG8_SB(1, 0), b3, voffB); PG8_STAGE(PG8_SB(1, 1), b3 + hstep, voffB); PG8_STAGE(PG8_SA(1, 0), a3, voffA);
;             PG8_WAIT_V(8); PG8_WAIT_L(0); PG8_BAR; PG8_MMA(1, 0, At, B0); PG8_MMA(1, 1, At, B1); PG8_BAR; PG8_SCHED;
	s_add_i32 s12, s12, s4
	v_lshl_add_u64 v[198:199], v[198:199], 0, s[18:19]
	s_mov_b32 m0, s12
	ds_read_b128 v[194:197], v142 offset:49152
	ds_read_b128 v[212:215], v142 offset:50176
	ds_read_b128 v[216:219], v142 offset:51200
	ds_read_b128 v[220:223], v142 offset:52224
	ds_read_b128 v[224:227], v142 offset:53248
	ds_read_b128 v[228:231], v142 offset:54272
	ds_read_b128 v[236:239], v142 offset:55296
	ds_read_b128 v[240:243], v142 offset:56320
	global_load_lds_dwordx4 v[198:199], off
	s_add_i32 m0, s12, 0x2000
	s_add_u32 s42, s42, 0x40080
	v_lshl_add_u64 v[198:199], v[244:245], 0, s[18:19]
	s_addc_u32 s43, s43, 0
	s_add_i32 s12, s50, s4
	global_load_lds_dwordx4 v[198:199], off
	v_lshl_add_u64 v[198:199], s[42:43], 0, v[2:3]
	s_mov_b32 m0, s12
	s_nop 0
	global_load_lds_dwordx4 v[198:199], off
	v_lshl_add_u64 v[198:199], s[42:43], 0, v[0:1]
	s_add_i32 m0, s12, 0x2000
	s_nop 0
	global_load_lds_dwordx4 v[198:199], off
	v_lshl_add_u64 v[198:199], v[246:247], 0, s[18:19]
	s_mov_b32 m0, s9
	s_nop 0
	global_load_lds_dwordx4 v[198:199], off
	v_lshl_add_u64 v[198:199], v[248:249], 0, s[18:19]
	s_mov_b32 m0, s13
	s_nop 0
	global_load_lds_dwordx4 v[198:199], off
	s_waitcnt vmcnt(8)
	s_waitcnt lgkmcnt(0)
	s_barrier
	s_setprio 1
	s_waitcnt lgkmcnt(0)
	v_mfma_f32_16x16x32_bf16 v[64:67], v[146:149], v[194:197], v[64:67]
	v_mfma_f32_16x16x32_bf16 v[60:63], v[170:173], v[194:197], v[60:63]
	v_mfma_f32_16x16x32_bf16 v[56:59], v[146:149], v[216:219], v[56:59]
	v_mfma_f32_16x16x32_bf16 v[52:55], v[170:173], v[216:219], v[52:55]
	v_mfma_f32_16x16x32_bf16 v[40:43], v[146:149], v[224:227], v[40:43]
	v_mfma_f32_16x16x32_bf16 v[36:39], v[170:173], v[224:227], v[36:39]
	v_mfma_f32_16x16x32_bf16 v[24:27], v[146:149], v[236:239], v[24:27]
	v_mfma_f32_16x16x32_bf16 v[20:23], v[170:173], v[236:239], v[20:23]
	v_mfma_f32_16x16x32_bf16 v[64:67], v[150:153], v[212:215], v[64:67]
	v_mfma_f32_16x16x32_bf16 v[60:63], v[174:177], v[212:215], v[60:63]
	v_mfma_f32_16x16x32_bf16 v[56:59], v[150:153], v[220:223], v[56:59]
	v_mfma_f32_16x16x32_bf16 v[52:55], v[174:177], v[220:223], v[52:55]
	v_mfma_f32_16x16x32_bf16 v[40:43], v[150:153], v[228:231], v[40:43]
	v_mfma_f32_16x16x32_bf16 v[36:39], v[174:177], v[228:231], v[36:39]
	v_mfma_f32_16x16x32_bf16 v[24:27], v[150:153], v[240:243], v[24:27]
	v_mfma_f32_16x16x32_bf16 v[20:23], v[174:177], v[240:243], v[20:23]
	s_setprio 0
	s_setprio 1
	v_mfma_f32_16x16x32_bf16 v[48:51], v[178:181], v[194:197], v[48:51]
	v_mfma_f32_16x16x32_bf16 v[44:47], v[186:189], v[194:197], v[44:47]
	s_add_i32 s49, s49, 2
	v_mfma_f32_16x16x32_bf16 v[32:35], v[178:181], v[216:219], v[32:35]
	s_add_u32 s36, s36, 0x100
	v_mfma_f32_16x16x32_bf16 v[28:31], v[186:189], v[216:219], v[28:31]
	s_addc_u32 s37, s37, 0
	v_mfma_f32_16x16x32_bf16 v[16:19], v[178:181], v[224:227], v[16:19]
	s_add_u32 s47, s47, 0x100
	v_mfma_f32_16x16x32_bf16 v[12:15], v[186:189], v[224:227], v[12:15]
	s_addc_u32 s48, s48, 0
	v_mfma_f32_16x16x32_bf16 v[8:11], v[178:181], v[236:239], v[8:11]
	s_cmp_gt_u32 s49, 13
	v_mfma_f32_16x16x32_bf16 v[4:7], v[186:189], v[236:239], v[4:7]
	v_mfma_f32_16x16x32_bf16 v[48:51], v[182:185], v[212:215], v[48:51]
	v_mfma_f32_16x16x32_bf16 v[44:47], v[190:193], v[212:215], v[44:47]
	v_mfma_f32_16x16x32_bf16 v[32:35], v[182:185], v[220:223], v[32:35]
	v_mfma_f32_16x16x32_bf16 v[28:31], v[190:193], v[220:223], v[28:31]
	v_mfma_f32_16x16x32_bf16 v[16:19], v[182:185], v[228:231], v[16:19]
	v_mfma_f32_16x16x32_bf16 v[12:15], v[190:193], v[228:231], v[12:15]
	v_mfma_f32_16x16x32_bf16 v[8:11], v[182:185], v[240:243], v[8:11]
	v_mfma_f32_16x16x32_bf16 v[4:7], v[190:193], v[240:243], v[4:7]
	s_setprio 0
	s_barrier
	s_cbranch_scc0 .LBB0_1567
	s_and_b64 vcc, exec, s[20:21]
	s_cbranch_vccz .LBB0_1570
	s_barrier
